# S2_V
# baseline (speedup 1.0000x reference)
;     __device__ bool next(int i, Unit& u) const { if (!base.next(i >> 1, u)) return false; u.sub = i & 1; return true; }
; #define PG8_STAGE(bufoff, gbase, voff) do { _Pragma("unroll") for (int _i = 0; _i < 2; ++_i) \
;         __builtin_amdgcn_global_load_lds((const unsigned*)((const char*)(gbase) + (voff)[_i]), (PG8_LAS unsigned*)(lds + (bufoff) + ldsw + _i * 8192), 16, 0, 0); } while (0)
; #define PG8_LDA(dst, b, h) do { _Pragma("unroll") for (int m = 0; m < 4; ++m) _Pragma("unroll") for (int k = 0; k < 2; ++k) dst[m][k] = *(const PG8_LAS bf16x8*)(lds + PG8_SA(b, h) + aoff + m * 2048 + k * 1024); } while (0)
; #define PG8_LDB(dst, b, h) do { _Pragma("unroll") for (int n = 0; n < 2; ++n) _Pragma("unroll") for (int k = 0; k < 2; ++k) dst[n][k] = *(const PG8_LAS bf16x8*)(lds + PG8_SB(b, h) + boff + n * 2048 + k * 1024); } while (0)
; #define PG8_WAIT_V(n) asm volatile("s_waitcnt vmcnt(" #n ")" ::: "memory")
; template <class Epi, class Sched, bool ALIGN_EPI = false, bool SP2 = false, bool DUAL = false>
; __device__ __forceinline__ void gemm_phase(PG8_LAS unsigned char* lds, const Gemm g, const Sched& S, const Epi& E) {
;     ...
;         const bool has_next = S.next(ui + 1, nxt);
;         const char* nA = has_next ? (const char*)((DUAL && nxt.sub) ? g.A2 : g.A) + (size_t)nxt.pm * tstep : cA; const char* nB = has_next ? (const char*)((DUAL && nxt.sub) ? g.Bt2 : g.Bt) + (size_t)nxt.pn * tstep : cB;
;         for (int t = 0; t < nt; t += 2) {
;             const bool last = (t == nt - 2);
;             const char* a1 = cA + (size_t)(t + 1) * kstep;
;             const char* a2 = last ? nA : cA + (size_t)(t + 2) * kstep; const char* b2 = last ? nB : cB + (size_t)(t + 2) * kstep;
;             const char* a3 = a2 + kstep; const char* b3 = b2 + kstep;
;             if (last && has_next) S.a_ready(nxt);
;             if constexpr (SP2) {
;             PG8_LDB(B0, 0, 0); PG8_LDB(B1, 0, 1); PG8_SCHED; PG8_LDA(At, 0, 0); PG8_STAGE(PG8_SA(1, 1), a1 + hstep, voffA);
;             PG8_WAIT_V(8); PG8_WAIT_L(0); PG8_BAR; PG8_MMA(0, 0, At, B0); PG8_MMA(0, 1, At, B1); PG8_BAR; PG8_SCHED;
;             PG8_LDA(At, 0, 1); PG8_STAGE(PG8_SB(0, 0), b2, voffB); PG8_STAGE(PG8_SB(0, 1), b2 + hstep, voffB); PG8_STAGE(PG8_SA(0, 0), a2, voffA);
;             PG8_WAIT_V(8); PG8_WAIT_L(0); PG8_BAR; PG8_MMA(1, 0, At, B0); PG8_MMA(1, 1, At, B1); PG8_BAR; PG8_SCHED;
.LBB0_251:
	s_ashr_i32 s87, s86, 31
	s_lshl_b64 s[16:17], s[86:87], 20
	s_add_u32 s92, s58, s16
	s_addc_u32 s93, s59, s17
	s_and_b64 s[16:17], s[4:5], exec
	s_cselect_b32 s7, s93, s11
	s_cselect_b32 s9, s92, s10
	s_ashr_i32 s1, s0, 31
	s_lshl_b64 s[16:17], s[0:1], 20
	s_add_u32 s88, s90, s16
	s_addc_u32 s89, s91, s17
	s_and_b64 s[16:17], s[4:5], exec
	s_cselect_b32 s1, s89, s15
	s_cselect_b32 s45, s88, s14
	s_add_u32 s10, s10, 0x80080
	s_addc_u32 s11, s11, 0
	s_add_u32 s46, s14, 0x100
	s_addc_u32 s47, s15, 0
	s_mov_b32 s48, -2
	s_add_u32 s14, s10, 0xfff80080
	s_addc_u32 s15, s11, -1
	s_cmp_eq_u32 s48, 28
	s_cselect_b32 s17, s7, s15
	s_cselect_b32 s16, s9, s14
	s_cselect_b32 s15, s1, s47
	s_cselect_b32 s14, s45, s46
	s_waitcnt vmcnt(8)
	s_waitcnt lgkmcnt(0)
	s_setprio 1
	s_barrier
	v_mfma_f32_16x16x32_bf16 v[140:143], v[80:83], v[208:211], 0
	v_mfma_f32_16x16x32_bf16 v[140:143], v[84:87], v[212:215], v[140:143]
	v_mfma_f32_16x16x32_bf16 v[124:127], v[80:83], v[216:219], 0
	v_mfma_f32_16x16x32_bf16 v[124:127], v[84:87], v[220:223], v[124:127]
	v_mfma_f32_16x16x32_bf16 v[108:111], v[80:83], v[232:235], 0
	v_mfma_f32_16x16x32_bf16 v[108:111], v[84:87], v[236:239], v[108:111]
	v_mfma_f32_16x16x32_bf16 v[76:79], v[80:83], v[240:243], 0
	v_mfma_f32_16x16x32_bf16 v[76:79], v[84:87], v[244:247], v[76:79]
	v_mfma_f32_16x16x32_bf16 v[132:135], v[88:91], v[208:211], 0
	v_mfma_f32_16x16x32_bf16 v[132:135], v[92:95], v[212:215], v[132:135]
	v_mfma_f32_16x16x32_bf16 v[120:123], v[88:91], v[216:219], 0
	v_mfma_f32_16x16x32_bf16 v[120:123], v[92:95], v[220:223], v[120:123]
	v_mfma_f32_16x16x32_bf16 v[104:107], v[88:91], v[232:235], 0
	v_mfma_f32_16x16x32_bf16 v[104:107], v[92:95], v[236:239], v[104:107]
	v_mfma_f32_16x16x32_bf16 v[72:75], v[88:91], v[240:243], 0
	v_mfma_f32_16x16x32_bf16 v[72:75], v[92:95], v[244:247], v[72:75]
	s_setprio 0
	s_setprio 1
	v_mfma_f32_16x16x32_bf16 v[136:139], v[144:147], v[208:211], 0
	v_mfma_f32_16x16x32_bf16 v[136:139], v[148:151], v[212:215], v[136:139]
	v_mfma_f32_16x16x32_bf16 v[116:119], v[144:147], v[216:219], 0
	v_mfma_f32_16x16x32_bf16 v[116:119], v[148:151], v[220:223], v[116:119]
	v_mfma_f32_16x16x32_bf16 v[100:103], v[144:147], v[232:235], 0
	v_mfma_f32_16x16x32_bf16 v[100:103], v[148:151], v[236:239], v[100:103]
	v_mfma_f32_16x16x32_bf16 v[68:71], v[144:147], v[240:243], 0
	v_mfma_f32_16x16x32_bf16 v[68:71], v[148:151], v[244:247], v[68:71]
	v_mfma_f32_16x16x32_bf16 v[128:131], v[152:155], v[208:211], 0
	v_mfma_f32_16x16x32_bf16 v[128:131], v[156:159], v[212:215], v[128:131]
	v_mfma_f32_16x16x32_bf16 v[112:115], v[152:155], v[216:219], 0
	v_mfma_f32_16x16x32_bf16 v[112:115], v[156:159], v[220:223], v[112:115]
	v_mfma_f32_16x16x32_bf16 v[96:99], v[152:155], v[232:235], 0
	v_mfma_f32_16x16x32_bf16 v[96:99], v[156:159], v[236:239], v[96:99]
	v_mfma_f32_16x16x32_bf16 v[64:67], v[152:155], v[240:243], 0
	v_mfma_f32_16x16x32_bf16 v[64:67], v[156:159], v[244:247], v[64:67]
	s_barrier
	s_setprio 0
	s_add_u32 s98, s14, 0x80
	s_addc_u32 s99, s15, 0
	s_add_u32 s100, s16, 0x80
	s_addc_u32 s101, s17, 0
	s_add_i32 m0, s19, 0xc000
	s_nop 0
	global_load_lds_dwordx4 v186, s[10:11]
	s_add_i32 m0, s19, 0xe000
	s_nop 0
	global_load_lds_dwordx4 v188, s[10:11]
	s_add_i32 s49, s31, s18
	s_mov_b32 m0, s49
	ds_read_b128 v[208:211], v203 offset:16384
	ds_read_b128 v[212:215], v203 offset:17408
	ds_read_b128 v[216:219], v203 offset:18432
	ds_read_b128 v[220:223], v203 offset:19456
	ds_read_b128 v[232:235], v203 offset:20480
	ds_read_b128 v[236:239], v203 offset:21504
	ds_read_b128 v[240:243], v203 offset:22528
	ds_read_b128 v[244:247], v203 offset:23552
	global_load_lds_dwordx4 v166, s[14:15]
	s_add_i32 m0, s49, 0x2000
	s_add_u32 s50, s14, 0x80000
	s_addc_u32 s51, s15, 0
	s_add_i32 s49, s34, s18
	global_load_lds_dwordx4 v170, s[14:15]
	s_mov_b32 m0, s49
	s_nop 0
	global_load_lds_dwordx4 v166, s[50:51]
	s_add_i32 m0, s49, 0x2000
	s_nop 0
	global_load_lds_dwordx4 v170, s[50:51]
	s_mov_b32 m0, s19
	s_nop 0
	global_load_lds_dwordx4 v164, s[16:17]
	s_mov_b32 m0, s20
	s_nop 0
	global_load_lds_dwordx4 v168, s[16:17]
	s_waitcnt vmcnt(8)
	s_waitcnt lgkmcnt(0)
	s_setprio 1
	s_barrier
	v_mfma_f32_16x16x32_bf16 v[60:63], v[80:83], v[208:211], 0
	v_mfma_f32_16x16x32_bf16 v[60:63], v[84:87], v[212:215], v[60:63]
	v_mfma_f32_16x16x32_bf16 v[44:47], v[80:83], v[216:219], 0
	v_mfma_f32_16x16x32_bf16 v[44:47], v[84:87], v[220:223], v[44:47]
	v_mfma_f32_16x16x32_bf16 v[28:31], v[80:83], v[232:235], 0
	v_mfma_f32_16x16x32_bf16 v[28:31], v[84:87], v[236:239], v[28:31]
	v_mfma_f32_16x16x32_bf16 v[12:15], v[80:83], v[240:243], 0
	v_mfma_f32_16x16x32_bf16 v[12:15], v[84:87], v[244:247], v[12:15]
	v_mfma_f32_16x16x32_bf16 v[56:59], v[88:91], v[208:211], 0
	v_mfma_f32_16x16x32_bf16 v[56:59], v[92:95], v[212:215], v[56:59]
	v_mfma_f32_16x16x32_bf16 v[40:43], v[88:91], v[216:219], 0
	v_mfma_f32_16x16x32_bf16 v[40:43], v[92:95], v[220:223], v[40:43]
	v_mfma_f32_16x16x32_bf16 v[24:27], v[88:91], v[232:235], 0
	v_mfma_f32_16x16x32_bf16 v[24:27], v[92:95], v[236:239], v[24:27]
	v_mfma_f32_16x16x32_bf16 v[8:11], v[88:91], v[240:243], 0
	v_mfma_f32_16x16x32_bf16 v[8:11], v[92:95], v[244:247], v[8:11]
	s_setprio 0
	s_setprio 1
	v_mfma_f32_16x16x32_bf16 v[52:55], v[144:147], v[208:211], 0
	v_mfma_f32_16x16x32_bf16 v[52:55], v[148:151], v[212:215], v[52:55]
	v_mfma_f32_16x16x32_bf16 v[36:39], v[144:147], v[216:219], 0
	v_mfma_f32_16x16x32_bf16 v[36:39], v[148:151], v[220:223], v[36:39]
	v_mfma_f32_16x16x32_bf16 v[20:23], v[144:147], v[232:235], 0
	v_mfma_f32_16x16x32_bf16 v[20:23], v[148:151], v[236:239], v[20:23]
	v_mfma_f32_16x16x32_bf16 v[4:7], v[144:147], v[240:243], 0
	v_mfma_f32_16x16x32_bf16 v[4:7], v[148:151], v[244:247], v[4:7]
	v_mfma_f32_16x16x32_bf16 v[48:51], v[152:155], v[208:211], 0
	v_mfma_f32_16x16x32_bf16 v[48:51], v[156:159], v[212:215], v[48:51]
	v_mfma_f32_16x16x32_bf16 v[32:35], v[152:155], v[216:219], 0
	v_mfma_f32_16x16x32_bf16 v[32:35], v[156:159], v[220:223], v[32:35]
	v_mfma_f32_16x16x32_bf16 v[16:19], v[152:155], v[232:235], 0
	v_mfma_f32_16x16x32_bf16 v[16:19], v[156:159], v[236:239], v[16:19]
	v_mfma_f32_16x16x32_bf16 v[0:3], v[152:155], v[240:243], 0
	v_mfma_f32_16x16x32_bf16 v[0:3], v[156:159], v[244:247], v[0:3]
	s_barrier
; #define PG8_STAGE(bufoff, gbase, voff) do { _Pragma("unroll") for (int _i = 0; _i < 2; ++_i) \
;         __builtin_amdgcn_global_load_lds((const unsigned*)((const char*)(gbase) + (voff)[_i]), (PG8_LAS unsigned*)(lds + (bufoff) + ldsw + _i * 8192), 16, 0, 0); } while (0)
; #define PG8_LDA(dst, b, h) do { _Pragma("unroll") for (int m = 0; m < 4; ++m) _Pragma("unroll") for (int k = 0; k < 2; ++k) dst[m][k] = *(const PG8_LAS bf16x8*)(lds + PG8_SA(b, h) + aoff + m * 2048 + k * 1024); } while (0)
; #define PG8_LDB(dst, b, h) do { _Pragma("unroll") for (int n = 0; n < 2; ++n) _Pragma("unroll") for (int k = 0; k < 2; ++k) dst[n][k] = *(const PG8_LAS bf16x8*)(lds + PG8_SB(b, h) + boff + n * 2048 + k * 1024); } while (0)
; #define PG8_MMA(ai, bj, At, Bt) do { __builtin_amdgcn_s_setprio(1); _Pragma("unroll") for (int m = 0; m < 4; ++m) _Pragma("unroll") for (int n = 0; n < 2; ++n) _Pragma("unroll") for (int k = 0; k < 2; ++k) \
;         acc[ai][bj][m][n] = __builtin_amdgcn_mfma_f32_16x16x32_bf16(Bt[n][k], At[m][k], acc[ai][bj][m][n], 0, 0, 0); __builtin_amdgcn_s_setprio(0); } while (0)
; #define PG8_WAIT_V(n) asm volatile("s_waitcnt vmcnt(" #n ")" ::: "memory")
; #define PG8_WAIT_L(n) asm volatile("s_waitcnt lgkmcnt(" #n ")" ::: "memory")
; #define PG8_BAR __builtin_amdgcn_s_barrier()
; #define PG8_SCHED __builtin_amdgcn_sched_barrier(0)
; template <class Epi, class Sched, bool ALIGN_EPI = false, bool SP2 = false, bool DUAL = false>
; __device__ __forceinline__ void gemm_phase(PG8_LAS unsigned char* lds, const Gemm g, const Sched& S, const Epi& E) {
;     ...
;             PG8_LDB(B0, 1, 0); PG8_LDB(B1, 1, 1); PG8_SCHED; PG8_LDA(At, 1, 0); PG8_STAGE(PG8_SA(0, 1), a2 + hstep, voffA);
;             PG8_WAIT_V(8); PG8_WAIT_L(0); PG8_BAR; PG8_MMA(0, 0, At, B0); PG8_MMA(0, 1, At, B1); PG8_BAR; PG8_SCHED;
;             PG8_LDA(At, 1, 1); PG8_STAGE(PG8_SB(1, 0), b3, voffB); PG8_STAGE(PG8_SB(1, 1), b3 + hstep, voffB); PG8_STAGE(PG8_SA(1, 0), a3, voffA);
;             PG8_WAIT_V(8); PG8_WAIT_L(0); PG8_BAR; PG8_MMA(1, 0, At, B0); PG8_MMA(1, 1, At, B1); PG8_BAR; PG8_SCHED;
	s_setprio 0
	s_add_i32 s49, 0, 0x18000
	s_add_i32 s50, 0, 0x1c000
	ds_read_b128 v[80:83], v199 offset:32768
	ds_read_b128 v[84:87], v199 offset:33792
	ds_read_b128 v[88:91], v199 offset:34816
	ds_read_b128 v[92:95], v199 offset:35840
	ds_read_b128 v[144:147], v202 offset:32768
	ds_read_b128 v[148:151], v202 offset:33792
	ds_read_b128 v[152:155], v202 offset:34816
	ds_read_b128 v[156:159], v202 offset:35840
	s_add_u32 s16, s16, 0x80000
	s_addc_u32 s17, s17, 0
	s_mov_b32 m0, s21
	ds_read_b128 v[208:211], v203 offset:32768
	ds_read_b128 v[212:215], v203 offset:33792
	ds_read_b128 v[216:219], v203 offset:34816
	ds_read_b128 v[220:223], v203 offset:35840
	ds_read_b128 v[232:235], v203 offset:36864
	ds_read_b128 v[236:239], v203 offset:37888
	ds_read_b128 v[240:243], v203 offset:38912
	ds_read_b128 v[244:247], v203 offset:39936
	global_load_lds_dwordx4 v164, s[16:17]
	s_mov_b32 m0, s22
	s_nop 0
	global_load_lds_dwordx4 v168, s[16:17]
	s_waitcnt vmcnt(8)
	s_waitcnt lgkmcnt(0)
	s_setprio 1
	s_barrier
	v_mfma_f32_16x16x32_bf16 v[140:143], v[80:83], v[208:211], v[140:143]
	v_mfma_f32_16x16x32_bf16 v[140:143], v[84:87], v[212:215], v[140:143]
	v_mfma_f32_16x16x32_bf16 v[124:127], v[80:83], v[216:219], v[124:127]
	v_mfma_f32_16x16x32_bf16 v[124:127], v[84:87], v[220:223], v[124:127]
	v_mfma_f32_16x16x32_bf16 v[108:111], v[80:83], v[232:235], v[108:111]
	v_mfma_f32_16x16x32_bf16 v[108:111], v[84:87], v[236:239], v[108:111]
	v_mfma_f32_16x16x32_bf16 v[76:79], v[80:83], v[240:243], v[76:79]
	v_mfma_f32_16x16x32_bf16 v[76:79], v[84:87], v[244:247], v[76:79]
	v_mfma_f32_16x16x32_bf16 v[132:135], v[88:91], v[208:211], v[132:135]
	v_mfma_f32_16x16x32_bf16 v[132:135], v[92:95], v[212:215], v[132:135]
	v_mfma_f32_16x16x32_bf16 v[120:123], v[88:91], v[216:219], v[120:123]
	v_mfma_f32_16x16x32_bf16 v[120:123], v[92:95], v[220:223], v[120:123]
	v_mfma_f32_16x16x32_bf16 v[104:107], v[88:91], v[232:235], v[104:107]
	v_mfma_f32_16x16x32_bf16 v[104:107], v[92:95], v[236:239], v[104:107]
	v_mfma_f32_16x16x32_bf16 v[72:75], v[88:91], v[240:243], v[72:75]
	v_mfma_f32_16x16x32_bf16 v[72:75], v[92:95], v[244:247], v[72:75]
	s_setprio 0
	s_setprio 1
	v_mfma_f32_16x16x32_bf16 v[136:139], v[144:147], v[208:211], v[136:139]
	v_mfma_f32_16x16x32_bf16 v[136:139], v[148:151], v[212:215], v[136:139]
	v_mfma_f32_16x16x32_bf16 v[116:119], v[144:147], v[216:219], v[116:119]
	v_mfma_f32_16x16x32_bf16 v[116:119], v[148:151], v[220:223], v[116:119]
	v_mfma_f32_16x16x32_bf16 v[100:103], v[144:147], v[232:235], v[100:103]
	v_mfma_f32_16x16x32_bf16 v[100:103], v[148:151], v[236:239], v[100:103]
	v_mfma_f32_16x16x32_bf16 v[68:71], v[144:147], v[240:243], v[68:71]
	v_mfma_f32_16x16x32_bf16 v[68:71], v[148:151], v[244:247], v[68:71]
	v_mfma_f32_16x16x32_bf16 v[128:131], v[152:155], v[208:211], v[128:131]
	v_mfma_f32_16x16x32_bf16 v[128:131], v[156:159], v[212:215], v[128:131]
	v_mfma_f32_16x16x32_bf16 v[112:115], v[152:155], v[216:219], v[112:115]
	v_mfma_f32_16x16x32_bf16 v[112:115], v[156:159], v[220:223], v[112:115]
	v_mfma_f32_16x16x32_bf16 v[96:99], v[152:155], v[232:235], v[96:99]
	v_mfma_f32_16x16x32_bf16 v[96:99], v[156:159], v[236:239], v[96:99]
	v_mfma_f32_16x16x32_bf16 v[64:67], v[152:155], v[240:243], v[64:67]
	v_mfma_f32_16x16x32_bf16 v[64:67], v[156:159], v[244:247], v[64:67]
	s_barrier
	s_setprio 0
	s_add_i32 s16, s49, s18
	s_mov_b32 m0, s16
	ds_read_b128 v[208:211], v203 offset:49152
	ds_read_b128 v[212:215], v203 offset:50176
	ds_read_b128 v[216:219], v203 offset:51200
	ds_read_b128 v[220:223], v203 offset:52224
	ds_read_b128 v[232:235], v203 offset:53248
	ds_read_b128 v[236:239], v203 offset:54272
	ds_read_b128 v[240:243], v203 offset:55296
	ds_read_b128 v[244:247], v203 offset:56320
	global_load_lds_dwordx4 v166, s[98:99]
	s_add_i32 m0, s16, 0x2000
	s_add_u32 s14, s14, 0x80080
	s_addc_u32 s15, s15, 0
	s_add_i32 s16, s50, s18
	global_load_lds_dwordx4 v170, s[98:99]
	s_mov_b32 m0, s16
	s_nop 0
	global_load_lds_dwordx4 v166, s[14:15]
	s_add_i32 m0, s16, 0x2000
	s_nop 0
	global_load_lds_dwordx4 v170, s[14:15]
	s_mov_b32 m0, s27
	s_nop 0
	global_load_lds_dwordx4 v164, s[100:101]
	s_mov_b32 m0, s28
	s_nop 0
	global_load_lds_dwordx4 v168, s[100:101]
	s_waitcnt vmcnt(8)
	s_waitcnt lgkmcnt(0)
	s_setprio 1
	s_barrier
	v_mfma_f32_16x16x32_bf16 v[60:63], v[80:83], v[208:211], v[60:63]
	v_mfma_f32_16x16x32_bf16 v[60:63], v[84:87], v[212:215], v[60:63]
	v_mfma_f32_16x16x32_bf16 v[44:47], v[80:83], v[216:219], v[44:47]
	v_mfma_f32_16x16x32_bf16 v[44:47], v[84:87], v[220:223], v[44:47]
	v_mfma_f32_16x16x32_bf16 v[28:31], v[80:83], v[232:235], v[28:31]
	v_mfma_f32_16x16x32_bf16 v[28:31], v[84:87], v[236:239], v[28:31]
	v_mfma_f32_16x16x32_bf16 v[12:15], v[80:83], v[240:243], v[12:15]
	v_mfma_f32_16x16x32_bf16 v[12:15], v[84:87], v[244:247], v[12:15]
	v_mfma_f32_16x16x32_bf16 v[56:59], v[88:91], v[208:211], v[56:59]
	v_mfma_f32_16x16x32_bf16 v[56:59], v[92:95], v[212:215], v[56:59]
	v_mfma_f32_16x16x32_bf16 v[40:43], v[88:91], v[216:219], v[40:43]
	v_mfma_f32_16x16x32_bf16 v[40:43], v[92:95], v[220:223], v[40:43]
	v_mfma_f32_16x16x32_bf16 v[24:27], v[88:91], v[232:235], v[24:27]
	v_mfma_f32_16x16x32_bf16 v[24:27], v[92:95], v[236:239], v[24:27]
	v_mfma_f32_16x16x32_bf16 v[8:11], v[88:91], v[240:243], v[8:11]
	v_mfma_f32_16x16x32_bf16 v[8:11], v[92:95], v[244:247], v[8:11]
	s_setprio 0
	s_setprio 1
	v_mfma_f32_16x16x32_bf16 v[52:55], v[144:147], v[208:211], v[52:55]
	v_mfma_f32_16x16x32_bf16 v[52:55], v[148:151], v[212:215], v[52:55]
	v_mfma_f32_16x16x32_bf16 v[36:39], v[144:147], v[216:219], v[36:39]
	v_mfma_f32_16x16x32_bf16 v[36:39], v[148:151], v[220:223], v[36:39]
	v_mfma_f32_16x16x32_bf16 v[20:23], v[144:147], v[232:235], v[20:23]
	v_mfma_f32_16x16x32_bf16 v[20:23], v[148:151], v[236:239], v[20:23]
	v_mfma_f32_16x16x32_bf16 v[4:7], v[144:147], v[240:243], v[4:7]
	v_mfma_f32_16x16x32_bf16 v[4:7], v[148:151], v[244:247], v[4:7]
	v_mfma_f32_16x16x32_bf16 v[48:51], v[152:155], v[208:211], v[48:51]
	v_mfma_f32_16x16x32_bf16 v[48:51], v[156:159], v[212:215], v[48:51]
	v_mfma_f32_16x16x32_bf16 v[32:35], v[152:155], v[216:219], v[32:35]
	v_mfma_f32_16x16x32_bf16 v[32:35], v[156:159], v[220:223], v[32:35]
	v_mfma_f32_16x16x32_bf16 v[16:19], v[152:155], v[232:235], v[16:19]
	v_mfma_f32_16x16x32_bf16 v[16:19], v[156:159], v[236:239], v[16:19]
	v_mfma_f32_16x16x32_bf16 v[0:3], v[152:155], v[240:243], v[0:3]
	v_mfma_f32_16x16x32_bf16 v[0:3], v[156:159], v[244:247], v[0:3]
	s_barrier
	s_setprio 0
	s_add_i32 s48, s48, 2
	s_add_u32 s10, s10, 0x100
	s_addc_u32 s11, s11, 0
	s_add_u32 s46, s46, 0x100
	s_addc_u32 s47, s47, 0
; #define PG8_STAGE(bufoff, gbase, voff) do { _Pragma("unroll") for (int _i = 0; _i < 2; ++_i) \
;         __builtin_amdgcn_global_load_lds((const unsigned*)((const char*)(gbase) + (voff)[_i]), (PG8_LAS unsigned*)(lds + (bufoff) + ldsw + _i * 8192), 16, 0, 0); } while (0)
; #define PG8_LDA(dst, b, h) do { _Pragma("unroll") for (int m = 0; m < 4; ++m) _Pragma("unroll") for (int k = 0; k < 2; ++k) dst[m][k] = *(const PG8_LAS bf16x8*)(lds + PG8_SA(b, h) + aoff + m * 2048 + k * 1024); } while (0)
; #define PG8_LDB(dst, b, h) do { _Pragma("unroll") for (int n = 0; n < 2; ++n) _Pragma("unroll") for (int k = 0; k < 2; ++k) dst[n][k] = *(const PG8_LAS bf16x8*)(lds + PG8_SB(b, h) + boff + n * 2048 + k * 1024); } while (0)
; #define PG8_MMA(ai, bj, At, Bt) do { __builtin_amdgcn_s_setprio(1); _Pragma("unroll") for (int m = 0; m < 4; ++m) _Pragma("unroll") for (int n = 0; n < 2; ++n) _Pragma("unroll") for (int k = 0; k < 2; ++k) \
;         acc[ai][bj][m][n] = __builtin_amdgcn_mfma_f32_16x16x32_bf16(Bt[n][k], At[m][k], acc[ai][bj][m][n], 0, 0, 0); __builtin_amdgcn_s_setprio(0); } while (0)
; #define PG8_WAIT_V(n) asm volatile("s_waitcnt vmcnt(" #n ")" ::: "memory")
; #define PG8_BAR __builtin_amdgcn_s_barrier()
; template <class Epi, class Sched, bool ALIGN_EPI = false, bool SP2 = false, bool DUAL = false>
; __device__ __forceinline__ void gemm_phase(PG8_LAS unsigned char* lds, const Gemm g, const Sched& S, const Epi& E) {
;     ...
;         for (int t = 0; t < nt; t += 2) {
;             const bool last = (t == nt - 2);
;             const char* a1 = cA + (size_t)(t + 1) * kstep;
;             const char* a2 = last ? nA : cA + (size_t)(t + 2) * kstep; const char* b2 = last ? nB : cB + (size_t)(t + 2) * kstep;
;             const char* a3 = a2 + kstep; const char* b3 = b2 + kstep;
;             if (last && has_next) S.a_ready(nxt);
;             if constexpr (SP2) {
;             PG8_LDB(B0, 0, 0); PG8_LDB(B1, 0, 1); PG8_SCHED; PG8_LDA(At, 0, 0); PG8_STAGE(PG8_SA(1, 1), a1 + hstep, voffA);
;             PG8_WAIT_V(8); PG8_WAIT_L(0); PG8_BAR; PG8_MMA(0, 0, At, B0); PG8_MMA(0, 1, At, B1); PG8_BAR; PG8_SCHED;
;             PG8_LDA(At, 0, 1); PG8_STAGE(PG8_SB(0, 0), b2, voffB); PG8_STAGE(PG8_SB(0, 1), b2 + hstep, voffB); PG8_STAGE(PG8_SA(0, 0), a2, voffA);
;             PG8_WAIT_V(8); PG8_WAIT_L(0); PG8_BAR; PG8_MMA(1, 0, At, B0); PG8_MMA(1, 1, At, B1); PG8_BAR; PG8_SCHED;
.LBB0_252:
	ds_read_b128 v[80:83], v199
	ds_read_b128 v[84:87], v199 offset:1024
	ds_read_b128 v[88:91], v199 offset:2048
	ds_read_b128 v[92:95], v199 offset:3072
	ds_read_b128 v[144:147], v202
	ds_read_b128 v[148:151], v202 offset:1024
	ds_read_b128 v[152:155], v202 offset:2048
	ds_read_b128 v[156:159], v202 offset:3072
	s_add_u32 s14, s10, 0xfff80080
	s_addc_u32 s15, s11, -1
	s_cmp_eq_u32 s48, 28
	s_cselect_b32 s17, s7, s15
	s_cselect_b32 s16, s9, s14
	s_cselect_b32 s15, s1, s47
	s_cselect_b32 s14, s45, s46
	s_add_i32 m0, s19, 0xc000
	ds_read_b128 v[208:211], v203
	ds_read_b128 v[212:215], v203 offset:1024
	ds_read_b128 v[216:219], v203 offset:2048
	ds_read_b128 v[220:223], v203 offset:3072
	ds_read_b128 v[232:235], v203 offset:4096
	ds_read_b128 v[236:239], v203 offset:5120
	ds_read_b128 v[240:243], v203 offset:6144
	ds_read_b128 v[244:247], v203 offset:7168
	global_load_lds_dwordx4 v186, s[10:11]
	s_add_i32 m0, s19, 0xe000
	s_nop 0
	global_load_lds_dwordx4 v188, s[10:11]
	s_waitcnt vmcnt(8)
	s_waitcnt lgkmcnt(0)
	s_setprio 1
	s_barrier
	v_mfma_f32_16x16x32_bf16 v[140:143], v[80:83], v[208:211], v[140:143]
	v_mfma_f32_16x16x32_bf16 v[140:143], v[84:87], v[212:215], v[140:143]
	v_mfma_f32_16x16x32_bf16 v[124:127], v[80:83], v[216:219], v[124:127]
	v_mfma_f32_16x16x32_bf16 v[124:127], v[84:87], v[220:223], v[124:127]
	v_mfma_f32_16x16x32_bf16 v[108:111], v[80:83], v[232:235], v[108:111]
	v_mfma_f32_16x16x32_bf16 v[108:111], v[84:87], v[236:239], v[108:111]
	v_mfma_f32_16x16x32_bf16 v[76:79], v[80:83], v[240:243], v[76:79]
	v_mfma_f32_16x16x32_bf16 v[76:79], v[84:87], v[244:247], v[76:79]
	v_mfma_f32_16x16x32_bf16 v[132:135], v[88:91], v[208:211], v[132:135]
	v_mfma_f32_16x16x32_bf16 v[132:135], v[92:95], v[212:215], v[132:135]
	v_mfma_f32_16x16x32_bf16 v[120:123], v[88:91], v[216:219], v[120:123]
	v_mfma_f32_16x16x32_bf16 v[120:123], v[92:95], v[220:223], v[120:123]
	v_mfma_f32_16x16x32_bf16 v[104:107], v[88:91], v[232:235], v[104:107]
	v_mfma_f32_16x16x32_bf16 v[104:107], v[92:95], v[236:239], v[104:107]
	v_mfma_f32_16x16x32_bf16 v[72:75], v[88:91], v[240:243], v[72:75]
	v_mfma_f32_16x16x32_bf16 v[72:75], v[92:95], v[244:247], v[72:75]
	s_setprio 0
	s_setprio 1
	v_mfma_f32_16x16x32_bf16 v[136:139], v[144:147], v[208:211], v[136:139]
	v_mfma_f32_16x16x32_bf16 v[136:139], v[148:151], v[212:215], v[136:139]
	v_mfma_f32_16x16x32_bf16 v[116:119], v[144:147], v[216:219], v[116:119]
	v_mfma_f32_16x16x32_bf16 v[116:119], v[148:151], v[220:223], v[116:119]
	v_mfma_f32_16x16x32_bf16 v[100:103], v[144:147], v[232:235], v[100:103]
	v_mfma_f32_16x16x32_bf16 v[100:103], v[148:151], v[236:239], v[100:103]
	v_mfma_f32_16x16x32_bf16 v[68:71], v[144:147], v[240:243], v[68:71]
	v_mfma_f32_16x16x32_bf16 v[68:71], v[148:151], v[244:247], v[68:71]
	v_mfma_f32_16x16x32_bf16 v[128:131], v[152:155], v[208:211], v[128:131]
	v_mfma_f32_16x16x32_bf16 v[128:131], v[156:159], v[212:215], v[128:131]
	v_mfma_f32_16x16x32_bf16 v[112:115], v[152:155], v[216:219], v[112:115]
	v_mfma_f32_16x16x32_bf16 v[112:115], v[156:159], v[220:223], v[112:115]
	v_mfma_f32_16x16x32_bf16 v[96:99], v[152:155], v[232:235], v[96:99]
	v_mfma_f32_16x16x32_bf16 v[96:99], v[156:159], v[236:239], v[96:99]
	v_mfma_f32_16x16x32_bf16 v[64:67], v[152:155], v[240:243], v[64:67]
	v_mfma_f32_16x16x32_bf16 v[64:67], v[156:159], v[244:247], v[64:67]
	s_barrier
	s_setprio 0
	s_add_u32 s98, s14, 0x80
	s_addc_u32 s99, s15, 0
	s_add_u32 s100, s16, 0x80
	s_addc_u32 s101, s17, 0
	s_add_i32 s49, s31, s18
	s_mov_b32 m0, s49
	ds_read_b128 v[208:211], v203 offset:16384
	ds_read_b128 v[212:215], v203 offset:17408
	ds_read_b128 v[216:219], v203 offset:18432
	ds_read_b128 v[220:223], v203 offset:19456
	ds_read_b128 v[232:235], v203 offset:20480
	ds_read_b128 v[236:239], v203 offset:21504
	ds_read_b128 v[240:243], v203 offset:22528
	ds_read_b128 v[244:247], v203 offset:23552
	global_load_lds_dwordx4 v166, s[14:15]
	s_add_i32 m0, s49, 0x2000
	s_add_u32 s50, s14, 0x80000
	s_addc_u32 s51, s15, 0
	s_add_i32 s49, s34, s18
	global_load_lds_dwordx4 v170, s[14:15]
	s_mov_b32 m0, s49
	s_nop 0
	global_load_lds_dwordx4 v166, s[50:51]
	s_add_i32 m0, s49, 0x2000
	s_nop 0
	global_load_lds_dwordx4 v170, s[50:51]
	s_mov_b32 m0, s19
	s_nop 0
	global_load_lds_dwordx4 v164, s[16:17]
	s_mov_b32 m0, s20
	s_nop 0
	global_load_lds_dwordx4 v168, s[16:17]
	s_waitcnt vmcnt(8)
	s_waitcnt lgkmcnt(0)
	s_setprio 1
	s_barrier
	v_mfma_f32_16x16x32_bf16 v[60:63], v[80:83], v[208:211], v[60:63]
	v_mfma_f32_16x16x32_bf16 v[60:63], v[84:87], v[212:215], v[60:63]
	v_mfma_f32_16x16x32_bf16 v[44:47], v[80:83], v[216:219], v[44:47]
	v_mfma_f32_16x16x32_bf16 v[44:47], v[84:87], v[220:223], v[44:47]
	v_mfma_f32_16x16x32_bf16 v[28:31], v[80:83], v[232:235], v[28:31]
	v_mfma_f32_16x16x32_bf16 v[28:31], v[84:87], v[236:239], v[28:31]
	v_mfma_f32_16x16x32_bf16 v[12:15], v[80:83], v[240:243], v[12:15]
	v_mfma_f32_16x16x32_bf16 v[12:15], v[84:87], v[244:247], v[12:15]
	v_mfma_f32_16x16x32_bf16 v[56:59], v[88:91], v[208:211], v[56:59]
	v_mfma_f32_16x16x32_bf16 v[56:59], v[92:95], v[212:215], v[56:59]
	v_mfma_f32_16x16x32_bf16 v[40:43], v[88:91], v[216:219], v[40:43]
	v_mfma_f32_16x16x32_bf16 v[40:43], v[92:95], v[220:223], v[40:43]
	v_mfma_f32_16x16x32_bf16 v[24:27], v[88:91], v[232:235], v[24:27]
	v_mfma_f32_16x16x32_bf16 v[24:27], v[92:95], v[236:239], v[24:27]
	v_mfma_f32_16x16x32_bf16 v[8:11], v[88:91], v[240:243], v[8:11]
	v_mfma_f32_16x16x32_bf16 v[8:11], v[92:95], v[244:247], v[8:11]
	s_setprio 0
	s_setprio 1
	v_mfma_f32_16x16x32_bf16 v[52:55], v[144:147], v[208:211], v[52:55]
	v_mfma_f32_16x16x32_bf16 v[52:55], v[148:151], v[212:215], v[52:55]
	v_mfma_f32_16x16x32_bf16 v[36:39], v[144:147], v[216:219], v[36:39]
	v_mfma_f32_16x16x32_bf16 v[36:39], v[148:151], v[220:223], v[36:39]
	v_mfma_f32_16x16x32_bf16 v[20:23], v[144:147], v[232:235], v[20:23]
	v_mfma_f32_16x16x32_bf16 v[20:23], v[148:151], v[236:239], v[20:23]
	v_mfma_f32_16x16x32_bf16 v[4:7], v[144:147], v[240:243], v[4:7]
	v_mfma_f32_16x16x32_bf16 v[4:7], v[148:151], v[244:247], v[4:7]
	v_mfma_f32_16x16x32_bf16 v[48:51], v[152:155], v[208:211], v[48:51]
	v_mfma_f32_16x16x32_bf16 v[48:51], v[156:159], v[212:215], v[48:51]
	v_mfma_f32_16x16x32_bf16 v[32:35], v[152:155], v[216:219], v[32:35]
	v_mfma_f32_16x16x32_bf16 v[32:35], v[156:159], v[220:223], v[32:35]
	v_mfma_f32_16x16x32_bf16 v[16:19], v[152:155], v[232:235], v[16:19]
	v_mfma_f32_16x16x32_bf16 v[16:19], v[156:159], v[236:239], v[16:19]
	v_mfma_f32_16x16x32_bf16 v[0:3], v[152:155], v[240:243], v[0:3]
	v_mfma_f32_16x16x32_bf16 v[0:3], v[156:159], v[244:247], v[0:3]
	s_barrier
; #define PG8_STAGE(bufoff, gbase, voff) do { _Pragma("unroll") for (int _i = 0; _i < 2; ++_i) \
;         __builtin_amdgcn_global_load_lds((const unsigned*)((const char*)(gbase) + (voff)[_i]), (PG8_LAS unsigned*)(lds + (bufoff) + ldsw + _i * 8192), 16, 0, 0); } while (0)
; #define PG8_LDA(dst, b, h) do { _Pragma("unroll") for (int m = 0; m < 4; ++m) _Pragma("unroll") for (int k = 0; k < 2; ++k) dst[m][k] = *(const PG8_LAS bf16x8*)(lds + PG8_SA(b, h) + aoff + m * 2048 + k * 1024); } while (0)
; #define PG8_LDB(dst, b, h) do { _Pragma("unroll") for (int n = 0; n < 2; ++n) _Pragma("unroll") for (int k = 0; k < 2; ++k) dst[n][k] = *(const PG8_LAS bf16x8*)(lds + PG8_SB(b, h) + boff + n * 2048 + k * 1024); } while (0)
; #define PG8_MMA(ai, bj, At, Bt) do { __builtin_amdgcn_s_setprio(1); _Pragma("unroll") for (int m = 0; m < 4; ++m) _Pragma("unroll") for (int n = 0; n < 2; ++n) _Pragma("unroll") for (int k = 0; k < 2; ++k) \
;         acc[ai][bj][m][n] = __builtin_amdgcn_mfma_f32_16x16x32_bf16(Bt[n][k], At[m][k], acc[ai][bj][m][n], 0, 0, 0); __builtin_amdgcn_s_setprio(0); } while (0)
; #define PG8_WAIT_V(n) asm volatile("s_waitcnt vmcnt(" #n ")" ::: "memory")
; #define PG8_WAIT_L(n) asm volatile("s_waitcnt lgkmcnt(" #n ")" ::: "memory")
; #define PG8_BAR __builtin_amdgcn_s_barrier()
; #define PG8_SCHED __builtin_amdgcn_sched_barrier(0)
; template <class Epi, class Sched, bool ALIGN_EPI = false, bool SP2 = false, bool DUAL = false>
; __device__ __forceinline__ void gemm_phase(PG8_LAS unsigned char* lds, const Gemm g, const Sched& S, const Epi& E) {
;     ...
;             PG8_LDB(B0, 1, 0); PG8_LDB(B1, 1, 1); PG8_SCHED; PG8_LDA(At, 1, 0); PG8_STAGE(PG8_SA(0, 1), a2 + hstep, voffA);
;             PG8_WAIT_V(8); PG8_WAIT_L(0); PG8_BAR; PG8_MMA(0, 0, At, B0); PG8_MMA(0, 1, At, B1); PG8_BAR; PG8_SCHED;
;             PG8_LDA(At, 1, 1); PG8_STAGE(PG8_SB(1, 0), b3, voffB); PG8_STAGE(PG8_SB(1, 1), b3 + hstep, voffB); PG8_STAGE(PG8_SA(1, 0), a3, voffA);
;             PG8_WAIT_V(8); PG8_WAIT_L(0); PG8_BAR; PG8_MMA(1, 0, At, B0); PG8_MMA(1, 1, At, B1); PG8_BAR; PG8_SCHED;
	s_setprio 0
	s_add_i32 s49, 0, 0x18000
	s_add_i32 s50, 0, 0x1c000
	ds_read_b128 v[80:83], v199 offset:32768
	ds_read_b128 v[84:87], v199 offset:33792
	ds_read_b128 v[88:91], v199 offset:34816
	ds_read_b128 v[92:95], v199 offset:35840
	ds_read_b128 v[144:147], v202 offset:32768
	ds_read_b128 v[148:151], v202 offset:33792
	ds_read_b128 v[152:155], v202 offset:34816
	ds_read_b128 v[156:159], v202 offset:35840
	s_add_u32 s16, s16, 0x80000
	s_addc_u32 s17, s17, 0
	s_mov_b32 m0, s21
	ds_read_b128 v[208:211], v203 offset:32768
	ds_read_b128 v[212:215], v203 offset:33792
	ds_read_b128 v[216:219], v203 offset:34816
	ds_read_b128 v[220:223], v203 offset:35840
	ds_read_b128 v[232:235], v203 offset:36864
	ds_read_b128 v[236:239], v203 offset:37888
	ds_read_b128 v[240:243], v203 offset:38912
	ds_read_b128 v[244:247], v203 offset:39936
	global_load_lds_dwordx4 v164, s[16:17]
	s_mov_b32 m0, s22
	s_nop 0
	global_load_lds_dwordx4 v168, s[16:17]
	s_waitcnt vmcnt(8)
	s_waitcnt lgkmcnt(0)
	s_setprio 1
	s_barrier
	v_mfma_f32_16x16x32_bf16 v[140:143], v[80:83], v[208:211], v[140:143]
	v_mfma_f32_16x16x32_bf16 v[140:143], v[84:87], v[212:215], v[140:143]
	v_mfma_f32_16x16x32_bf16 v[124:127], v[80:83], v[216:219], v[124:127]
	v_mfma_f32_16x16x32_bf16 v[124:127], v[84:87], v[220:223], v[124:127]
	v_mfma_f32_16x16x32_bf16 v[108:111], v[80:83], v[232:235], v[108:111]
	v_mfma_f32_16x16x32_bf16 v[108:111], v[84:87], v[236:239], v[108:111]
	v_mfma_f32_16x16x32_bf16 v[76:79], v[80:83], v[240:243], v[76:79]
	v_mfma_f32_16x16x32_bf16 v[76:79], v[84:87], v[244:247], v[76:79]
	v_mfma_f32_16x16x32_bf16 v[132:135], v[88:91], v[208:211], v[132:135]
	v_mfma_f32_16x16x32_bf16 v[132:135], v[92:95], v[212:215], v[132:135]
	v_mfma_f32_16x16x32_bf16 v[120:123], v[88:91], v[216:219], v[120:123]
	v_mfma_f32_16x16x32_bf16 v[120:123], v[92:95], v[220:223], v[120:123]
	v_mfma_f32_16x16x32_bf16 v[104:107], v[88:91], v[232:235], v[104:107]
	v_mfma_f32_16x16x32_bf16 v[104:107], v[92:95], v[236:239], v[104:107]
	v_mfma_f32_16x16x32_bf16 v[72:75], v[88:91], v[240:243], v[72:75]
	v_mfma_f32_16x16x32_bf16 v[72:75], v[92:95], v[244:247], v[72:75]
	s_setprio 0
	s_setprio 1
	v_mfma_f32_16x16x32_bf16 v[136:139], v[144:147], v[208:211], v[136:139]
	v_mfma_f32_16x16x32_bf16 v[136:139], v[148:151], v[212:215], v[136:139]
	v_mfma_f32_16x16x32_bf16 v[116:119], v[144:147], v[216:219], v[116:119]
	v_mfma_f32_16x16x32_bf16 v[116:119], v[148:151], v[220:223], v[116:119]
	v_mfma_f32_16x16x32_bf16 v[100:103], v[144:147], v[232:235], v[100:103]
	v_mfma_f32_16x16x32_bf16 v[100:103], v[148:151], v[236:239], v[100:103]
	v_mfma_f32_16x16x32_bf16 v[68:71], v[144:147], v[240:243], v[68:71]
	v_mfma_f32_16x16x32_bf16 v[68:71], v[148:151], v[244:247], v[68:71]
	v_mfma_f32_16x16x32_bf16 v[128:131], v[152:155], v[208:211], v[128:131]
	v_mfma_f32_16x16x32_bf16 v[128:131], v[156:159], v[212:215], v[128:131]
	v_mfma_f32_16x16x32_bf16 v[112:115], v[152:155], v[216:219], v[112:115]
	v_mfma_f32_16x16x32_bf16 v[112:115], v[156:159], v[220:223], v[112:115]
	v_mfma_f32_16x16x32_bf16 v[96:99], v[152:155], v[232:235], v[96:99]
	v_mfma_f32_16x16x32_bf16 v[96:99], v[156:159], v[236:239], v[96:99]
	v_mfma_f32_16x16x32_bf16 v[64:67], v[152:155], v[240:243], v[64:67]
	v_mfma_f32_16x16x32_bf16 v[64:67], v[156:159], v[244:247], v[64:67]
	s_barrier
	s_setprio 0
	s_add_i32 s16, s49, s18
	s_mov_b32 m0, s16
	ds_read_b128 v[208:211], v203 offset:49152
	ds_read_b128 v[212:215], v203 offset:50176
	ds_read_b128 v[216:219], v203 offset:51200
	ds_read_b128 v[220:223], v203 offset:52224
	ds_read_b128 v[232:235], v203 offset:53248
	ds_read_b128 v[236:239], v203 offset:54272
	ds_read_b128 v[240:243], v203 offset:55296
	ds_read_b128 v[244:247], v203 offset:56320
	global_load_lds_dwordx4 v166, s[98:99]
	s_add_i32 m0, s16, 0x2000
	s_add_u32 s14, s14, 0x80080
	s_addc_u32 s15, s15, 0
	s_add_i32 s16, s50, s18
	global_load_lds_dwordx4 v170, s[98:99]
	s_mov_b32 m0, s16
	s_nop 0
	global_load_lds_dwordx4 v166, s[14:15]
	s_add_i32 m0, s16, 0x2000
	s_nop 0
	global_load_lds_dwordx4 v170, s[14:15]
	s_mov_b32 m0, s27
	s_nop 0
	global_load_lds_dwordx4 v164, s[100:101]
	s_mov_b32 m0, s28
	s_nop 0
	global_load_lds_dwordx4 v168, s[100:101]
	s_waitcnt vmcnt(8)
	s_waitcnt lgkmcnt(0)
	s_setprio 1
	s_barrier
	v_mfma_f32_16x16x32_bf16 v[60:63], v[80:83], v[208:211], v[60:63]
	v_mfma_f32_16x16x32_bf16 v[60:63], v[84:87], v[212:215], v[60:63]
	v_mfma_f32_16x16x32_bf16 v[44:47], v[80:83], v[216:219], v[44:47]
	v_mfma_f32_16x16x32_bf16 v[44:47], v[84:87], v[220:223], v[44:47]
	v_mfma_f32_16x16x32_bf16 v[28:31], v[80:83], v[232:235], v[28:31]
	v_mfma_f32_16x16x32_bf16 v[28:31], v[84:87], v[236:239], v[28:31]
	v_mfma_f32_16x16x32_bf16 v[12:15], v[80:83], v[240:243], v[12:15]
	v_mfma_f32_16x16x32_bf16 v[12:15], v[84:87], v[244:247], v[12:15]
	v_mfma_f32_16x16x32_bf16 v[56:59], v[88:91], v[208:211], v[56:59]
	v_mfma_f32_16x16x32_bf16 v[56:59], v[92:95], v[212:215], v[56:59]
	v_mfma_f32_16x16x32_bf16 v[40:43], v[88:91], v[216:219], v[40:43]
	v_mfma_f32_16x16x32_bf16 v[40:43], v[92:95], v[220:223], v[40:43]
	v_mfma_f32_16x16x32_bf16 v[24:27], v[88:91], v[232:235], v[24:27]
	v_mfma_f32_16x16x32_bf16 v[24:27], v[92:95], v[236:239], v[24:27]
	v_mfma_f32_16x16x32_bf16 v[8:11], v[88:91], v[240:243], v[8:11]
	v_mfma_f32_16x16x32_bf16 v[8:11], v[92:95], v[244:247], v[8:11]
	s_setprio 0
	s_setprio 1
	v_mfma_f32_16x16x32_bf16 v[52:55], v[144:147], v[208:211], v[52:55]
	v_mfma_f32_16x16x32_bf16 v[52:55], v[148:151], v[212:215], v[52:55]
	v_mfma_f32_16x16x32_bf16 v[36:39], v[144:147], v[216:219], v[36:39]
	v_mfma_f32_16x16x32_bf16 v[36:39], v[148:151], v[220:223], v[36:39]
	v_mfma_f32_16x16x32_bf16 v[20:23], v[144:147], v[232:235], v[20:23]
	v_mfma_f32_16x16x32_bf16 v[20:23], v[148:151], v[236:239], v[20:23]
	v_mfma_f32_16x16x32_bf16 v[4:7], v[144:147], v[240:243], v[4:7]
	v_mfma_f32_16x16x32_bf16 v[4:7], v[148:151], v[244:247], v[4:7]
	v_mfma_f32_16x16x32_bf16 v[48:51], v[152:155], v[208:211], v[48:51]
	v_mfma_f32_16x16x32_bf16 v[48:51], v[156:159], v[212:215], v[48:51]
	v_mfma_f32_16x16x32_bf16 v[32:35], v[152:155], v[216:219], v[32:35]
	v_mfma_f32_16x16x32_bf16 v[32:35], v[156:159], v[220:223], v[32:35]
	v_mfma_f32_16x16x32_bf16 v[16:19], v[152:155], v[232:235], v[16:19]
	v_mfma_f32_16x16x32_bf16 v[16:19], v[156:159], v[236:239], v[16:19]
	v_mfma_f32_16x16x32_bf16 v[0:3], v[152:155], v[240:243], v[0:3]
	v_mfma_f32_16x16x32_bf16 v[0:3], v[156:159], v[244:247], v[0:3]
	s_barrier
	s_setprio 0
	s_add_i32 s48, s48, 2
	s_add_u32 s10, s10, 0x100
	s_addc_u32 s11, s11, 0
	s_add_u32 s46, s46, 0x100
	s_addc_u32 s47, s47, 0
	s_cmp_gt_u32 s48, 29
	s_cbranch_scc0 .LBB0_252
	s_and_b64 vcc, exec, s[38:39]
	s_cbranch_vccz .LBB0_255
	s_barrier

;     __device__ bool next(int i, Unit& u) const { if (!base.next(i >> 1, u)) return false; u.sub = i & 1; return true; }
; #define PG8_STAGE(bufoff, gbase, voff) do { _Pragma("unroll") for (int _i = 0; _i < 2; ++_i) \
;         __builtin_amdgcn_global_load_lds((const unsigned*)((const char*)(gbase) + (voff)[_i]), (PG8_LAS unsigned*)(lds + (bufoff) + ldsw + _i * 8192), 16, 0, 0); } while (0)
; #define PG8_LDA(dst, b, h) do { _Pragma("unroll") for (int m = 0; m < 4; ++m) _Pragma("unroll") for (int k = 0; k < 2; ++k) dst[m][k] = *(const PG8_LAS bf16x8*)(lds + PG8_SA(b, h) + aoff + m * 2048 + k * 1024); } while (0)
; #define PG8_LDB(dst, b, h) do { _Pragma("unroll") for (int n = 0; n < 2; ++n) _Pragma("unroll") for (int k = 0; k < 2; ++k) dst[n][k] = *(const PG8_LAS bf16x8*)(lds + PG8_SB(b, h) + boff + n * 2048 + k * 1024); } while (0)
; #define PG8_WAIT_V(n) asm volatile("s_waitcnt vmcnt(" #n ")" ::: "memory")
; template <class Epi, class Sched, bool ALIGN_EPI = false, bool SP2 = false, bool DUAL = false>
; __device__ __forceinline__ void gemm_phase(PG8_LAS unsigned char* lds, const Gemm g, const Sched& S, const Epi& E) {
;     ...
;         const bool has_next = S.next(ui + 1, nxt);
;         const char* nA = has_next ? (const char*)((DUAL && nxt.sub) ? g.A2 : g.A) + (size_t)nxt.pm * tstep : cA; const char* nB = has_next ? (const char*)((DUAL && nxt.sub) ? g.Bt2 : g.Bt) + (size_t)nxt.pn * tstep : cB;
;         for (int t = 0; t < nt; t += 2) {
;             const bool last = (t == nt - 2);
;             const char* a1 = cA + (size_t)(t + 1) * kstep;
;             const char* a2 = last ? nA : cA + (size_t)(t + 2) * kstep; const char* b2 = last ? nB : cB + (size_t)(t + 2) * kstep;
;             const char* a3 = a2 + kstep; const char* b3 = b2 + kstep;
;             if (last && has_next) S.a_ready(nxt);
;             if constexpr (SP2) {
;             PG8_LDB(B0, 0, 0); PG8_LDB(B1, 0, 1); PG8_SCHED; PG8_LDA(At, 0, 0); PG8_STAGE(PG8_SA(1, 1), a1 + hstep, voffA);
;             PG8_WAIT_V(8); PG8_WAIT_L(0); PG8_BAR; PG8_MMA(0, 0, At, B0); PG8_MMA(0, 1, At, B1); PG8_BAR; PG8_SCHED;
;             PG8_LDA(At, 0, 1); PG8_STAGE(PG8_SB(0, 0), b2, voffB); PG8_STAGE(PG8_SB(0, 1), b2 + hstep, voffB); PG8_STAGE(PG8_SA(0, 0), a2, voffA);
;             PG8_WAIT_V(8); PG8_WAIT_L(0); PG8_BAR; PG8_MMA(1, 0, At, B0); PG8_MMA(1, 1, At, B1); PG8_BAR; PG8_SCHED;
.LBB0_895:
	s_ashr_i32 s61, s60, 31
	s_lshl_b64 s[18:19], s[60:61], 20
	s_add_u32 s62, s10, s18
	s_addc_u32 s63, s11, s19
	s_and_b64 s[18:19], s[6:7], exec
	s_cselect_b32 s18, s63, s17
	s_cselect_b32 s19, s62, s16
	s_ashr_i32 s41, s40, 31
	s_lshl_b64 s[64:65], s[40:41], 20
	s_add_u32 s64, s12, s64
	s_addc_u32 s65, s13, s65
	s_and_b64 s[68:69], s[6:7], exec
	s_cselect_b32 s41, s65, s15
	s_cselect_b32 s61, s64, s14
	s_add_u32 s68, s16, 0x80080
	s_addc_u32 s69, s17, 0
	s_add_u32 s67, s14, 0x100
	s_addc_u32 s70, s15, 0
	s_mov_b32 s71, -2
	s_waitcnt lgkmcnt(0)
	s_add_u32 s14, s68, 0xfff80080
	s_addc_u32 s15, s69, -1
	s_cmp_eq_u32 s71, 28
	s_cselect_b32 s17, s18, s15
	s_cselect_b32 s16, s19, s14
	s_cselect_b32 s15, s41, s70
	s_cselect_b32 s14, s61, s67
	s_waitcnt vmcnt(8)
	s_waitcnt lgkmcnt(0)
	s_setprio 1
	s_barrier
	v_mfma_f32_16x16x32_bf16 v[124:127], v[128:131], v[160:163], 0
	v_mfma_f32_16x16x32_bf16 v[124:127], v[132:135], v[164:167], v[124:127]
	v_mfma_f32_16x16x32_bf16 v[108:111], v[128:131], v[168:171], 0
	v_mfma_f32_16x16x32_bf16 v[108:111], v[132:135], v[172:175], v[108:111]
	v_mfma_f32_16x16x32_bf16 v[92:95], v[128:131], v[196:199], 0
	v_mfma_f32_16x16x32_bf16 v[92:95], v[132:135], v[202:205], v[92:95]
	v_mfma_f32_16x16x32_bf16 v[76:79], v[128:131], v[206:209], 0
	v_mfma_f32_16x16x32_bf16 v[76:79], v[132:135], v[232:235], v[76:79]
	v_mfma_f32_16x16x32_bf16 v[120:123], v[136:139], v[160:163], 0
	v_mfma_f32_16x16x32_bf16 v[120:123], v[140:143], v[164:167], v[120:123]
	v_mfma_f32_16x16x32_bf16 v[104:107], v[136:139], v[168:171], 0
	v_mfma_f32_16x16x32_bf16 v[104:107], v[140:143], v[172:175], v[104:107]
	v_mfma_f32_16x16x32_bf16 v[88:91], v[136:139], v[196:199], 0
	v_mfma_f32_16x16x32_bf16 v[88:91], v[140:143], v[202:205], v[88:91]
	v_mfma_f32_16x16x32_bf16 v[72:75], v[136:139], v[206:209], 0
	v_mfma_f32_16x16x32_bf16 v[72:75], v[140:143], v[232:235], v[72:75]
	s_setprio 0
	s_setprio 1
	v_mfma_f32_16x16x32_bf16 v[116:119], v[144:147], v[160:163], 0
	v_mfma_f32_16x16x32_bf16 v[116:119], v[148:151], v[164:167], v[116:119]
	v_mfma_f32_16x16x32_bf16 v[100:103], v[144:147], v[168:171], 0
	v_mfma_f32_16x16x32_bf16 v[100:103], v[148:151], v[172:175], v[100:103]
	v_mfma_f32_16x16x32_bf16 v[84:87], v[144:147], v[196:199], 0
	v_mfma_f32_16x16x32_bf16 v[84:87], v[148:151], v[202:205], v[84:87]
	v_mfma_f32_16x16x32_bf16 v[68:71], v[144:147], v[206:209], 0
	v_mfma_f32_16x16x32_bf16 v[68:71], v[148:151], v[232:235], v[68:71]
	v_mfma_f32_16x16x32_bf16 v[112:115], v[152:155], v[160:163], 0
	v_mfma_f32_16x16x32_bf16 v[112:115], v[156:159], v[164:167], v[112:115]
	v_mfma_f32_16x16x32_bf16 v[96:99], v[152:155], v[168:171], 0
	v_mfma_f32_16x16x32_bf16 v[96:99], v[156:159], v[172:175], v[96:99]
	v_mfma_f32_16x16x32_bf16 v[80:83], v[152:155], v[196:199], 0
	v_mfma_f32_16x16x32_bf16 v[80:83], v[156:159], v[202:205], v[80:83]
	v_mfma_f32_16x16x32_bf16 v[64:67], v[152:155], v[206:209], 0
	v_mfma_f32_16x16x32_bf16 v[64:67], v[156:159], v[232:235], v[64:67]
	s_barrier
	s_setprio 0
	s_add_u32 s98, s14, 0x80
	s_addc_u32 s99, s15, 0
	s_add_u32 s100, s16, 0x80
	s_addc_u32 s101, s17, 0
	s_add_i32 m0, s27, 0xc000
	s_nop 0
	global_load_lds_dwordx4 v188, s[68:69]
	s_add_i32 m0, s27, 0xe000
	s_nop 0
	global_load_lds_dwordx4 v190, s[68:69]
	s_add_i32 s72, s48, s26
	s_mov_b32 m0, s72
	ds_read_b128 v[160:163], v220 offset:16384
	ds_read_b128 v[164:167], v220 offset:17408
	ds_read_b128 v[168:171], v220 offset:18432
	ds_read_b128 v[172:175], v220 offset:19456
	ds_read_b128 v[196:199], v220 offset:20480
	ds_read_b128 v[202:205], v220 offset:21504
	ds_read_b128 v[206:209], v220 offset:22528
	ds_read_b128 v[232:235], v220 offset:23552
	global_load_lds_dwordx4 v182, s[14:15]
	s_add_i32 m0, s72, 0x2000
	s_add_u32 s72, s14, 0x80000
	s_addc_u32 s73, s15, 0
	s_add_i32 s74, s49, s26
	global_load_lds_dwordx4 v186, s[14:15]
	s_mov_b32 m0, s74
	s_nop 0
	global_load_lds_dwordx4 v182, s[72:73]
	s_add_i32 m0, s74, 0x2000
	s_nop 0
	global_load_lds_dwordx4 v186, s[72:73]
	s_mov_b32 m0, s27
	s_nop 0
	global_load_lds_dwordx4 v180, s[16:17]
	s_mov_b32 m0, s28
	s_nop 0
	global_load_lds_dwordx4 v184, s[16:17]
	s_waitcnt vmcnt(8)
	s_waitcnt lgkmcnt(0)
	s_setprio 1
	s_barrier
	v_mfma_f32_16x16x32_bf16 v[60:63], v[128:131], v[160:163], 0
	v_mfma_f32_16x16x32_bf16 v[60:63], v[132:135], v[164:167], v[60:63]
	v_mfma_f32_16x16x32_bf16 v[44:47], v[128:131], v[168:171], 0
	v_mfma_f32_16x16x32_bf16 v[44:47], v[132:135], v[172:175], v[44:47]
	v_mfma_f32_16x16x32_bf16 v[28:31], v[128:131], v[196:199], 0
	v_mfma_f32_16x16x32_bf16 v[28:31], v[132:135], v[202:205], v[28:31]
	v_mfma_f32_16x16x32_bf16 v[12:15], v[128:131], v[206:209], 0
	v_mfma_f32_16x16x32_bf16 v[12:15], v[132:135], v[232:235], v[12:15]
	v_mfma_f32_16x16x32_bf16 v[56:59], v[136:139], v[160:163], 0
	v_mfma_f32_16x16x32_bf16 v[56:59], v[140:143], v[164:167], v[56:59]
	v_mfma_f32_16x16x32_bf16 v[40:43], v[136:139], v[168:171], 0
	v_mfma_f32_16x16x32_bf16 v[40:43], v[140:143], v[172:175], v[40:43]
	v_mfma_f32_16x16x32_bf16 v[24:27], v[136:139], v[196:199], 0
	v_mfma_f32_16x16x32_bf16 v[24:27], v[140:143], v[202:205], v[24:27]
	v_mfma_f32_16x16x32_bf16 v[8:11], v[136:139], v[206:209], 0
	v_mfma_f32_16x16x32_bf16 v[8:11], v[140:143], v[232:235], v[8:11]
	s_setprio 0
	s_setprio 1
	v_mfma_f32_16x16x32_bf16 v[52:55], v[144:147], v[160:163], 0
	v_mfma_f32_16x16x32_bf16 v[52:55], v[148:151], v[164:167], v[52:55]
	v_mfma_f32_16x16x32_bf16 v[36:39], v[144:147], v[168:171], 0
	v_mfma_f32_16x16x32_bf16 v[36:39], v[148:151], v[172:175], v[36:39]
	v_mfma_f32_16x16x32_bf16 v[20:23], v[144:147], v[196:199], 0
	v_mfma_f32_16x16x32_bf16 v[20:23], v[148:151], v[202:205], v[20:23]
	v_mfma_f32_16x16x32_bf16 v[4:7], v[144:147], v[206:209], 0
	v_mfma_f32_16x16x32_bf16 v[4:7], v[148:151], v[232:235], v[4:7]
	v_mfma_f32_16x16x32_bf16 v[48:51], v[152:155], v[160:163], 0
	v_mfma_f32_16x16x32_bf16 v[48:51], v[156:159], v[164:167], v[48:51]
	v_mfma_f32_16x16x32_bf16 v[32:35], v[152:155], v[168:171], 0
	v_mfma_f32_16x16x32_bf16 v[32:35], v[156:159], v[172:175], v[32:35]
	v_mfma_f32_16x16x32_bf16 v[16:19], v[152:155], v[196:199], 0
	v_mfma_f32_16x16x32_bf16 v[16:19], v[156:159], v[202:205], v[16:19]
	v_mfma_f32_16x16x32_bf16 v[0:3], v[152:155], v[206:209], 0
	v_mfma_f32_16x16x32_bf16 v[0:3], v[156:159], v[232:235], v[0:3]
	s_barrier
; #define PG8_STAGE(bufoff, gbase, voff) do { _Pragma("unroll") for (int _i = 0; _i < 2; ++_i) \
;         __builtin_amdgcn_global_load_lds((const unsigned*)((const char*)(gbase) + (voff)[_i]), (PG8_LAS unsigned*)(lds + (bufoff) + ldsw + _i * 8192), 16, 0, 0); } while (0)
; #define PG8_LDA(dst, b, h) do { _Pragma("unroll") for (int m = 0; m < 4; ++m) _Pragma("unroll") for (int k = 0; k < 2; ++k) dst[m][k] = *(const PG8_LAS bf16x8*)(lds + PG8_SA(b, h) + aoff + m * 2048 + k * 1024); } while (0)
; #define PG8_LDB(dst, b, h) do { _Pragma("unroll") for (int n = 0; n < 2; ++n) _Pragma("unroll") for (int k = 0; k < 2; ++k) dst[n][k] = *(const PG8_LAS bf16x8*)(lds + PG8_SB(b, h) + boff + n * 2048 + k * 1024); } while (0)
; #define PG8_MMA(ai, bj, At, Bt) do { __builtin_amdgcn_s_setprio(1); _Pragma("unroll") for (int m = 0; m < 4; ++m) _Pragma("unroll") for (int n = 0; n < 2; ++n) _Pragma("unroll") for (int k = 0; k < 2; ++k) \
;         acc[ai][bj][m][n] = __builtin_amdgcn_mfma_f32_16x16x32_bf16(Bt[n][k], At[m][k], acc[ai][bj][m][n], 0, 0, 0); __builtin_amdgcn_s_setprio(0); } while (0)
; #define PG8_WAIT_V(n) asm volatile("s_waitcnt vmcnt(" #n ")" ::: "memory")
; #define PG8_WAIT_L(n) asm volatile("s_waitcnt lgkmcnt(" #n ")" ::: "memory")
; #define PG8_BAR __builtin_amdgcn_s_barrier()
; #define PG8_SCHED __builtin_amdgcn_sched_barrier(0)
; template <class Epi, class Sched, bool ALIGN_EPI = false, bool SP2 = false, bool DUAL = false>
; __device__ __forceinline__ void gemm_phase(PG8_LAS unsigned char* lds, const Gemm g, const Sched& S, const Epi& E) {
;     ...
;             PG8_LDB(B0, 1, 0); PG8_LDB(B1, 1, 1); PG8_SCHED; PG8_LDA(At, 1, 0); PG8_STAGE(PG8_SA(0, 1), a2 + hstep, voffA);
;             PG8_WAIT_V(8); PG8_WAIT_L(0); PG8_BAR; PG8_MMA(0, 0, At, B0); PG8_MMA(0, 1, At, B1); PG8_BAR; PG8_SCHED;
;             PG8_LDA(At, 1, 1); PG8_STAGE(PG8_SB(1, 0), b3, voffB); PG8_STAGE(PG8_SB(1, 1), b3 + hstep, voffB); PG8_STAGE(PG8_SA(1, 0), a3, voffA);
;             PG8_WAIT_V(8); PG8_WAIT_L(0); PG8_BAR; PG8_MMA(1, 0, At, B0); PG8_MMA(1, 1, At, B1); PG8_BAR; PG8_SCHED;
	s_setprio 0
	s_add_i32 s72, 0, 0x18000
	s_add_i32 s73, 0, 0x1c000
	ds_read_b128 v[128:131], v218 offset:32768
	ds_read_b128 v[132:135], v218 offset:33792
	ds_read_b128 v[136:139], v218 offset:34816
	ds_read_b128 v[140:143], v218 offset:35840
	ds_read_b128 v[144:147], v219 offset:32768
	ds_read_b128 v[148:151], v219 offset:33792
	ds_read_b128 v[152:155], v219 offset:34816
	ds_read_b128 v[156:159], v219 offset:35840
	s_add_u32 s16, s16, 0x80000
	s_addc_u32 s17, s17, 0
	s_mov_b32 m0, s29
	ds_read_b128 v[160:163], v220 offset:32768
	ds_read_b128 v[164:167], v220 offset:33792
	ds_read_b128 v[168:171], v220 offset:34816
	ds_read_b128 v[172:175], v220 offset:35840
	ds_read_b128 v[196:199], v220 offset:36864
	ds_read_b128 v[202:205], v220 offset:37888
	ds_read_b128 v[206:209], v220 offset:38912
	ds_read_b128 v[232:235], v220 offset:39936
	global_load_lds_dwordx4 v180, s[16:17]
	s_mov_b32 m0, s34
	s_nop 0
	global_load_lds_dwordx4 v184, s[16:17]
	s_waitcnt vmcnt(8)
	s_waitcnt lgkmcnt(0)
	s_setprio 1
	s_barrier
	v_mfma_f32_16x16x32_bf16 v[124:127], v[128:131], v[160:163], v[124:127]
	v_mfma_f32_16x16x32_bf16 v[124:127], v[132:135], v[164:167], v[124:127]
	v_mfma_f32_16x16x32_bf16 v[108:111], v[128:131], v[168:171], v[108:111]
	v_mfma_f32_16x16x32_bf16 v[108:111], v[132:135], v[172:175], v[108:111]
	v_mfma_f32_16x16x32_bf16 v[92:95], v[128:131], v[196:199], v[92:95]
	v_mfma_f32_16x16x32_bf16 v[92:95], v[132:135], v[202:205], v[92:95]
	v_mfma_f32_16x16x32_bf16 v[76:79], v[128:131], v[206:209], v[76:79]
	v_mfma_f32_16x16x32_bf16 v[76:79], v[132:135], v[232:235], v[76:79]
	v_mfma_f32_16x16x32_bf16 v[120:123], v[136:139], v[160:163], v[120:123]
	v_mfma_f32_16x16x32_bf16 v[120:123], v[140:143], v[164:167], v[120:123]
	v_mfma_f32_16x16x32_bf16 v[104:107], v[136:139], v[168:171], v[104:107]
	v_mfma_f32_16x16x32_bf16 v[104:107], v[140:143], v[172:175], v[104:107]
	v_mfma_f32_16x16x32_bf16 v[88:91], v[136:139], v[196:199], v[88:91]
	v_mfma_f32_16x16x32_bf16 v[88:91], v[140:143], v[202:205], v[88:91]
	v_mfma_f32_16x16x32_bf16 v[72:75], v[136:139], v[206:209], v[72:75]
	v_mfma_f32_16x16x32_bf16 v[72:75], v[140:143], v[232:235], v[72:75]
	s_setprio 0
	s_setprio 1
	v_mfma_f32_16x16x32_bf16 v[116:119], v[144:147], v[160:163], v[116:119]
	v_mfma_f32_16x16x32_bf16 v[116:119], v[148:151], v[164:167], v[116:119]
	v_mfma_f32_16x16x32_bf16 v[100:103], v[144:147], v[168:171], v[100:103]
	v_mfma_f32_16x16x32_bf16 v[100:103], v[148:151], v[172:175], v[100:103]
	v_mfma_f32_16x16x32_bf16 v[84:87], v[144:147], v[196:199], v[84:87]
	v_mfma_f32_16x16x32_bf16 v[84:87], v[148:151], v[202:205], v[84:87]
	v_mfma_f32_16x16x32_bf16 v[68:71], v[144:147], v[206:209], v[68:71]
	v_mfma_f32_16x16x32_bf16 v[68:71], v[148:151], v[232:235], v[68:71]
	v_mfma_f32_16x16x32_bf16 v[112:115], v[152:155], v[160:163], v[112:115]
	v_mfma_f32_16x16x32_bf16 v[112:115], v[156:159], v[164:167], v[112:115]
	v_mfma_f32_16x16x32_bf16 v[96:99], v[152:155], v[168:171], v[96:99]
	v_mfma_f32_16x16x32_bf16 v[96:99], v[156:159], v[172:175], v[96:99]
	v_mfma_f32_16x16x32_bf16 v[80:83], v[152:155], v[196:199], v[80:83]
	v_mfma_f32_16x16x32_bf16 v[80:83], v[156:159], v[202:205], v[80:83]
	v_mfma_f32_16x16x32_bf16 v[64:67], v[152:155], v[206:209], v[64:67]
	v_mfma_f32_16x16x32_bf16 v[64:67], v[156:159], v[232:235], v[64:67]
	s_barrier
	s_setprio 0
	s_add_i32 s16, s72, s26
	s_mov_b32 m0, s16
	ds_read_b128 v[160:163], v220 offset:49152
	ds_read_b128 v[164:167], v220 offset:50176
	ds_read_b128 v[168:171], v220 offset:51200
	ds_read_b128 v[172:175], v220 offset:52224
	ds_read_b128 v[196:199], v220 offset:53248
	ds_read_b128 v[202:205], v220 offset:54272
	ds_read_b128 v[206:209], v220 offset:55296
	ds_read_b128 v[232:235], v220 offset:56320
	global_load_lds_dwordx4 v182, s[98:99]
	s_add_i32 m0, s16, 0x2000
	s_add_u32 s14, s14, 0x80080
	s_addc_u32 s15, s15, 0
	s_add_i32 s16, s73, s26
	global_load_lds_dwordx4 v186, s[98:99]
	s_mov_b32 m0, s16
	s_nop 0
	global_load_lds_dwordx4 v182, s[14:15]
	s_add_i32 m0, s16, 0x2000
	s_nop 0
	global_load_lds_dwordx4 v186, s[14:15]
	s_mov_b32 m0, s44
	s_nop 0
	global_load_lds_dwordx4 v180, s[100:101]
	s_mov_b32 m0, s45
	s_nop 0
	global_load_lds_dwordx4 v184, s[100:101]
	s_waitcnt vmcnt(8)
	s_waitcnt lgkmcnt(0)
	s_setprio 1
	s_barrier
	v_mfma_f32_16x16x32_bf16 v[60:63], v[128:131], v[160:163], v[60:63]
	v_mfma_f32_16x16x32_bf16 v[60:63], v[132:135], v[164:167], v[60:63]
	v_mfma_f32_16x16x32_bf16 v[44:47], v[128:131], v[168:171], v[44:47]
	v_mfma_f32_16x16x32_bf16 v[44:47], v[132:135], v[172:175], v[44:47]
	v_mfma_f32_16x16x32_bf16 v[28:31], v[128:131], v[196:199], v[28:31]
	v_mfma_f32_16x16x32_bf16 v[28:31], v[132:135], v[202:205], v[28:31]
	v_mfma_f32_16x16x32_bf16 v[12:15], v[128:131], v[206:209], v[12:15]
	v_mfma_f32_16x16x32_bf16 v[12:15], v[132:135], v[232:235], v[12:15]
	v_mfma_f32_16x16x32_bf16 v[56:59], v[136:139], v[160:163], v[56:59]
	v_mfma_f32_16x16x32_bf16 v[56:59], v[140:143], v[164:167], v[56:59]
	v_mfma_f32_16x16x32_bf16 v[40:43], v[136:139], v[168:171], v[40:43]
	v_mfma_f32_16x16x32_bf16 v[40:43], v[140:143], v[172:175], v[40:43]
	v_mfma_f32_16x16x32_bf16 v[24:27], v[136:139], v[196:199], v[24:27]
	v_mfma_f32_16x16x32_bf16 v[24:27], v[140:143], v[202:205], v[24:27]
	v_mfma_f32_16x16x32_bf16 v[8:11], v[136:139], v[206:209], v[8:11]
	v_mfma_f32_16x16x32_bf16 v[8:11], v[140:143], v[232:235], v[8:11]
	s_setprio 0
	s_setprio 1
	v_mfma_f32_16x16x32_bf16 v[52:55], v[144:147], v[160:163], v[52:55]
	v_mfma_f32_16x16x32_bf16 v[52:55], v[148:151], v[164:167], v[52:55]
	v_mfma_f32_16x16x32_bf16 v[36:39], v[144:147], v[168:171], v[36:39]
	v_mfma_f32_16x16x32_bf16 v[36:39], v[148:151], v[172:175], v[36:39]
	v_mfma_f32_16x16x32_bf16 v[20:23], v[144:147], v[196:199], v[20:23]
	v_mfma_f32_16x16x32_bf16 v[20:23], v[148:151], v[202:205], v[20:23]
	v_mfma_f32_16x16x32_bf16 v[4:7], v[144:147], v[206:209], v[4:7]
	v_mfma_f32_16x16x32_bf16 v[4:7], v[148:151], v[232:235], v[4:7]
	v_mfma_f32_16x16x32_bf16 v[48:51], v[152:155], v[160:163], v[48:51]
	v_mfma_f32_16x16x32_bf16 v[48:51], v[156:159], v[164:167], v[48:51]
	v_mfma_f32_16x16x32_bf16 v[32:35], v[152:155], v[168:171], v[32:35]
	v_mfma_f32_16x16x32_bf16 v[32:35], v[156:159], v[172:175], v[32:35]
	v_mfma_f32_16x16x32_bf16 v[16:19], v[152:155], v[196:199], v[16:19]
	v_mfma_f32_16x16x32_bf16 v[16:19], v[156:159], v[202:205], v[16:19]
	v_mfma_f32_16x16x32_bf16 v[0:3], v[152:155], v[206:209], v[0:3]
	v_mfma_f32_16x16x32_bf16 v[0:3], v[156:159], v[232:235], v[0:3]
	s_barrier
	s_setprio 0
	s_add_i32 s71, s71, 2
	s_add_u32 s68, s68, 0x100
	s_addc_u32 s69, s69, 0
	s_add_u32 s67, s67, 0x100
	s_addc_u32 s70, s70, 0
; #define PG8_STAGE(bufoff, gbase, voff) do { _Pragma("unroll") for (int _i = 0; _i < 2; ++_i) \
;         __builtin_amdgcn_global_load_lds((const unsigned*)((const char*)(gbase) + (voff)[_i]), (PG8_LAS unsigned*)(lds + (bufoff) + ldsw + _i * 8192), 16, 0, 0); } while (0)
; #define PG8_LDA(dst, b, h) do { _Pragma("unroll") for (int m = 0; m < 4; ++m) _Pragma("unroll") for (int k = 0; k < 2; ++k) dst[m][k] = *(const PG8_LAS bf16x8*)(lds + PG8_SA(b, h) + aoff + m * 2048 + k * 1024); } while (0)
; #define PG8_LDB(dst, b, h) do { _Pragma("unroll") for (int n = 0; n < 2; ++n) _Pragma("unroll") for (int k = 0; k < 2; ++k) dst[n][k] = *(const PG8_LAS bf16x8*)(lds + PG8_SB(b, h) + boff + n * 2048 + k * 1024); } while (0)
; #define PG8_MMA(ai, bj, At, Bt) do { __builtin_amdgcn_s_setprio(1); _Pragma("unroll") for (int m = 0; m < 4; ++m) _Pragma("unroll") for (int n = 0; n < 2; ++n) _Pragma("unroll") for (int k = 0; k < 2; ++k) \
;         acc[ai][bj][m][n] = __builtin_amdgcn_mfma_f32_16x16x32_bf16(Bt[n][k], At[m][k], acc[ai][bj][m][n], 0, 0, 0); __builtin_amdgcn_s_setprio(0); } while (0)
; #define PG8_WAIT_V(n) asm volatile("s_waitcnt vmcnt(" #n ")" ::: "memory")
; #define PG8_BAR __builtin_amdgcn_s_barrier()
; template <class Epi, class Sched, bool ALIGN_EPI = false, bool SP2 = false, bool DUAL = false>
; __device__ __forceinline__ void gemm_phase(PG8_LAS unsigned char* lds, const Gemm g, const Sched& S, const Epi& E) {
;     ...
;         for (int t = 0; t < nt; t += 2) {
;             const bool last = (t == nt - 2);
;             const char* a1 = cA + (size_t)(t + 1) * kstep;
;             const char* a2 = last ? nA : cA + (size_t)(t + 2) * kstep; const char* b2 = last ? nB : cB + (size_t)(t + 2) * kstep;
;             const char* a3 = a2 + kstep; const char* b3 = b2 + kstep;
;             if (last && has_next) S.a_ready(nxt);
;             if constexpr (SP2) {
;             PG8_LDB(B0, 0, 0); PG8_LDB(B1, 0, 1); PG8_SCHED; PG8_LDA(At, 0, 0); PG8_STAGE(PG8_SA(1, 1), a1 + hstep, voffA);
;             PG8_WAIT_V(8); PG8_WAIT_L(0); PG8_BAR; PG8_MMA(0, 0, At, B0); PG8_MMA(0, 1, At, B1); PG8_BAR; PG8_SCHED;
;             PG8_LDA(At, 0, 1); PG8_STAGE(PG8_SB(0, 0), b2, voffB); PG8_STAGE(PG8_SB(0, 1), b2 + hstep, voffB); PG8_STAGE(PG8_SA(0, 0), a2, voffA);
;             PG8_WAIT_V(8); PG8_WAIT_L(0); PG8_BAR; PG8_MMA(1, 0, At, B0); PG8_MMA(1, 1, At, B1); PG8_BAR; PG8_SCHED;
.LBB0_896:
	ds_read_b128 v[128:131], v218
	ds_read_b128 v[132:135], v218 offset:1024
	ds_read_b128 v[136:139], v218 offset:2048
	ds_read_b128 v[140:143], v218 offset:3072
	ds_read_b128 v[144:147], v219
	ds_read_b128 v[148:151], v219 offset:1024
	ds_read_b128 v[152:155], v219 offset:2048
	ds_read_b128 v[156:159], v219 offset:3072
	s_add_u32 s14, s68, 0xfff80080
	s_addc_u32 s15, s69, -1
	s_cmp_eq_u32 s71, 28
	s_cselect_b32 s17, s18, s15
	s_cselect_b32 s16, s19, s14
	s_cselect_b32 s15, s41, s70
	s_cselect_b32 s14, s61, s67
	s_add_i32 m0, s27, 0xc000
	ds_read_b128 v[160:163], v220
	ds_read_b128 v[164:167], v220 offset:1024
	ds_read_b128 v[168:171], v220 offset:2048
	ds_read_b128 v[172:175], v220 offset:3072
	ds_read_b128 v[196:199], v220 offset:4096
	ds_read_b128 v[202:205], v220 offset:5120
	ds_read_b128 v[206:209], v220 offset:6144
	ds_read_b128 v[232:235], v220 offset:7168
	global_load_lds_dwordx4 v188, s[68:69]
	s_add_i32 m0, s27, 0xe000
	s_nop 0
	global_load_lds_dwordx4 v190, s[68:69]
	s_waitcnt vmcnt(8)
	s_waitcnt lgkmcnt(0)
	s_setprio 1
	s_barrier
	v_mfma_f32_16x16x32_bf16 v[124:127], v[128:131], v[160:163], v[124:127]
	v_mfma_f32_16x16x32_bf16 v[124:127], v[132:135], v[164:167], v[124:127]
	v_mfma_f32_16x16x32_bf16 v[108:111], v[128:131], v[168:171], v[108:111]
	v_mfma_f32_16x16x32_bf16 v[108:111], v[132:135], v[172:175], v[108:111]
	v_mfma_f32_16x16x32_bf16 v[92:95], v[128:131], v[196:199], v[92:95]
	v_mfma_f32_16x16x32_bf16 v[92:95], v[132:135], v[202:205], v[92:95]
	v_mfma_f32_16x16x32_bf16 v[76:79], v[128:131], v[206:209], v[76:79]
	v_mfma_f32_16x16x32_bf16 v[76:79], v[132:135], v[232:235], v[76:79]
	v_mfma_f32_16x16x32_bf16 v[120:123], v[136:139], v[160:163], v[120:123]
	v_mfma_f32_16x16x32_bf16 v[120:123], v[140:143], v[164:167], v[120:123]
	v_mfma_f32_16x16x32_bf16 v[104:107], v[136:139], v[168:171], v[104:107]
	v_mfma_f32_16x16x32_bf16 v[104:107], v[140:143], v[172:175], v[104:107]
	v_mfma_f32_16x16x32_bf16 v[88:91], v[136:139], v[196:199], v[88:91]
	v_mfma_f32_16x16x32_bf16 v[88:91], v[140:143], v[202:205], v[88:91]
	v_mfma_f32_16x16x32_bf16 v[72:75], v[136:139], v[206:209], v[72:75]
	v_mfma_f32_16x16x32_bf16 v[72:75], v[140:143], v[232:235], v[72:75]
	s_setprio 0
	s_setprio 1
	v_mfma_f32_16x16x32_bf16 v[116:119], v[144:147], v[160:163], v[116:119]
	v_mfma_f32_16x16x32_bf16 v[116:119], v[148:151], v[164:167], v[116:119]
	v_mfma_f32_16x16x32_bf16 v[100:103], v[144:147], v[168:171], v[100:103]
	v_mfma_f32_16x16x32_bf16 v[100:103], v[148:151], v[172:175], v[100:103]
	v_mfma_f32_16x16x32_bf16 v[84:87], v[144:147], v[196:199], v[84:87]
	v_mfma_f32_16x16x32_bf16 v[84:87], v[148:151], v[202:205], v[84:87]
	v_mfma_f32_16x16x32_bf16 v[68:71], v[144:147], v[206:209], v[68:71]
	v_mfma_f32_16x16x32_bf16 v[68:71], v[148:151], v[232:235], v[68:71]
	v_mfma_f32_16x16x32_bf16 v[112:115], v[152:155], v[160:163], v[112:115]
	v_mfma_f32_16x16x32_bf16 v[112:115], v[156:159], v[164:167], v[112:115]
	v_mfma_f32_16x16x32_bf16 v[96:99], v[152:155], v[168:171], v[96:99]
	v_mfma_f32_16x16x32_bf16 v[96:99], v[156:159], v[172:175], v[96:99]
	v_mfma_f32_16x16x32_bf16 v[80:83], v[152:155], v[196:199], v[80:83]
	v_mfma_f32_16x16x32_bf16 v[80:83], v[156:159], v[202:205], v[80:83]
	v_mfma_f32_16x16x32_bf16 v[64:67], v[152:155], v[206:209], v[64:67]
	v_mfma_f32_16x16x32_bf16 v[64:67], v[156:159], v[232:235], v[64:67]
	s_barrier
	s_setprio 0
	s_add_u32 s98, s14, 0x80
	s_addc_u32 s99, s15, 0
	s_add_u32 s100, s16, 0x80
	s_addc_u32 s101, s17, 0
	s_add_i32 s72, s48, s26
	s_mov_b32 m0, s72
	ds_read_b128 v[160:163], v220 offset:16384
	ds_read_b128 v[164:167], v220 offset:17408
	ds_read_b128 v[168:171], v220 offset:18432
	ds_read_b128 v[172:175], v220 offset:19456
	ds_read_b128 v[196:199], v220 offset:20480
	ds_read_b128 v[202:205], v220 offset:21504
	ds_read_b128 v[206:209], v220 offset:22528
	ds_read_b128 v[232:235], v220 offset:23552
	global_load_lds_dwordx4 v182, s[14:15]
	s_add_i32 m0, s72, 0x2000
	s_add_u32 s72, s14, 0x80000
	s_addc_u32 s73, s15, 0
	s_add_i32 s74, s49, s26
	global_load_lds_dwordx4 v186, s[14:15]
	s_mov_b32 m0, s74
	s_nop 0
	global_load_lds_dwordx4 v182, s[72:73]
	s_add_i32 m0, s74, 0x2000
	s_nop 0
	global_load_lds_dwordx4 v186, s[72:73]
	s_mov_b32 m0, s27
	s_nop 0
	global_load_lds_dwordx4 v180, s[16:17]
	s_mov_b32 m0, s28
	s_nop 0
	global_load_lds_dwordx4 v184, s[16:17]
	s_waitcnt vmcnt(8)
	s_waitcnt lgkmcnt(0)
	s_setprio 1
	s_barrier
	v_mfma_f32_16x16x32_bf16 v[60:63], v[128:131], v[160:163], v[60:63]
	v_mfma_f32_16x16x32_bf16 v[60:63], v[132:135], v[164:167], v[60:63]
	v_mfma_f32_16x16x32_bf16 v[44:47], v[128:131], v[168:171], v[44:47]
	v_mfma_f32_16x16x32_bf16 v[44:47], v[132:135], v[172:175], v[44:47]
	v_mfma_f32_16x16x32_bf16 v[28:31], v[128:131], v[196:199], v[28:31]
	v_mfma_f32_16x16x32_bf16 v[28:31], v[132:135], v[202:205], v[28:31]
	v_mfma_f32_16x16x32_bf16 v[12:15], v[128:131], v[206:209], v[12:15]
	v_mfma_f32_16x16x32_bf16 v[12:15], v[132:135], v[232:235], v[12:15]
	v_mfma_f32_16x16x32_bf16 v[56:59], v[136:139], v[160:163], v[56:59]
	v_mfma_f32_16x16x32_bf16 v[56:59], v[140:143], v[164:167], v[56:59]
	v_mfma_f32_16x16x32_bf16 v[40:43], v[136:139], v[168:171], v[40:43]
	v_mfma_f32_16x16x32_bf16 v[40:43], v[140:143], v[172:175], v[40:43]
	v_mfma_f32_16x16x32_bf16 v[24:27], v[136:139], v[196:199], v[24:27]
	v_mfma_f32_16x16x32_bf16 v[24:27], v[140:143], v[202:205], v[24:27]
	v_mfma_f32_16x16x32_bf16 v[8:11], v[136:139], v[206:209], v[8:11]
	v_mfma_f32_16x16x32_bf16 v[8:11], v[140:143], v[232:235], v[8:11]
	s_setprio 0
	s_setprio 1
	v_mfma_f32_16x16x32_bf16 v[52:55], v[144:147], v[160:163], v[52:55]
	v_mfma_f32_16x16x32_bf16 v[52:55], v[148:151], v[164:167], v[52:55]
	v_mfma_f32_16x16x32_bf16 v[36:39], v[144:147], v[168:171], v[36:39]
	v_mfma_f32_16x16x32_bf16 v[36:39], v[148:151], v[172:175], v[36:39]
	v_mfma_f32_16x16x32_bf16 v[20:23], v[144:147], v[196:199], v[20:23]
	v_mfma_f32_16x16x32_bf16 v[20:23], v[148:151], v[202:205], v[20:23]
	v_mfma_f32_16x16x32_bf16 v[4:7], v[144:147], v[206:209], v[4:7]
	v_mfma_f32_16x16x32_bf16 v[4:7], v[148:151], v[232:235], v[4:7]
	v_mfma_f32_16x16x32_bf16 v[48:51], v[152:155], v[160:163], v[48:51]
	v_mfma_f32_16x16x32_bf16 v[48:51], v[156:159], v[164:167], v[48:51]
	v_mfma_f32_16x16x32_bf16 v[32:35], v[152:155], v[168:171], v[32:35]
	v_mfma_f32_16x16x32_bf16 v[32:35], v[156:159], v[172:175], v[32:35]
	v_mfma_f32_16x16x32_bf16 v[16:19], v[152:155], v[196:199], v[16:19]
	v_mfma_f32_16x16x32_bf16 v[16:19], v[156:159], v[202:205], v[16:19]
	v_mfma_f32_16x16x32_bf16 v[0:3], v[152:155], v[206:209], v[0:3]
	v_mfma_f32_16x16x32_bf16 v[0:3], v[156:159], v[232:235], v[0:3]
	s_barrier
; #define PG8_STAGE(bufoff, gbase, voff) do { _Pragma("unroll") for (int _i = 0; _i < 2; ++_i) \
;         __builtin_amdgcn_global_load_lds((const unsigned*)((const char*)(gbase) + (voff)[_i]), (PG8_LAS unsigned*)(lds + (bufoff) + ldsw + _i * 8192), 16, 0, 0); } while (0)
; #define PG8_LDA(dst, b, h) do { _Pragma("unroll") for (int m = 0; m < 4; ++m) _Pragma("unroll") for (int k = 0; k < 2; ++k) dst[m][k] = *(const PG8_LAS bf16x8*)(lds + PG8_SA(b, h) + aoff + m * 2048 + k * 1024); } while (0)
; #define PG8_LDB(dst, b, h) do { _Pragma("unroll") for (int n = 0; n < 2; ++n) _Pragma("unroll") for (int k = 0; k < 2; ++k) dst[n][k] = *(const PG8_LAS bf16x8*)(lds + PG8_SB(b, h) + boff + n * 2048 + k * 1024); } while (0)
; #define PG8_MMA(ai, bj, At, Bt) do { __builtin_amdgcn_s_setprio(1); _Pragma("unroll") for (int m = 0; m < 4; ++m) _Pragma("unroll") for (int n = 0; n < 2; ++n) _Pragma("unroll") for (int k = 0; k < 2; ++k) \
;         acc[ai][bj][m][n] = __builtin_amdgcn_mfma_f32_16x16x32_bf16(Bt[n][k], At[m][k], acc[ai][bj][m][n], 0, 0, 0); __builtin_amdgcn_s_setprio(0); } while (0)
; #define PG8_WAIT_V(n) asm volatile("s_waitcnt vmcnt(" #n ")" ::: "memory")
; #define PG8_WAIT_L(n) asm volatile("s_waitcnt lgkmcnt(" #n ")" ::: "memory")
; #define PG8_BAR __builtin_amdgcn_s_barrier()
; #define PG8_SCHED __builtin_amdgcn_sched_barrier(0)
; template <class Epi, class Sched, bool ALIGN_EPI = false, bool SP2 = false, bool DUAL = false>
; __device__ __forceinline__ void gemm_phase(PG8_LAS unsigned char* lds, const Gemm g, const Sched& S, const Epi& E) {
;     ...
;             PG8_LDB(B0, 1, 0); PG8_LDB(B1, 1, 1); PG8_SCHED; PG8_LDA(At, 1, 0); PG8_STAGE(PG8_SA(0, 1), a2 + hstep, voffA);
;             PG8_WAIT_V(8); PG8_WAIT_L(0); PG8_BAR; PG8_MMA(0, 0, At, B0); PG8_MMA(0, 1, At, B1); PG8_BAR; PG8_SCHED;
;             PG8_LDA(At, 1, 1); PG8_STAGE(PG8_SB(1, 0), b3, voffB); PG8_STAGE(PG8_SB(1, 1), b3 + hstep, voffB); PG8_STAGE(PG8_SA(1, 0), a3, voffA);
;             PG8_WAIT_V(8); PG8_WAIT_L(0); PG8_BAR; PG8_MMA(1, 0, At, B0); PG8_MMA(1, 1, At, B1); PG8_BAR; PG8_SCHED;
	s_setprio 0
	s_add_i32 s72, 0, 0x18000
	s_add_i32 s73, 0, 0x1c000
	ds_read_b128 v[128:131], v218 offset:32768
	ds_read_b128 v[132:135], v218 offset:33792
	ds_read_b128 v[136:139], v218 offset:34816
	ds_read_b128 v[140:143], v218 offset:35840
	ds_read_b128 v[144:147], v219 offset:32768
	ds_read_b128 v[148:151], v219 offset:33792
	ds_read_b128 v[152:155], v219 offset:34816
	ds_read_b128 v[156:159], v219 offset:35840
	s_add_u32 s16, s16, 0x80000
	s_addc_u32 s17, s17, 0
	s_mov_b32 m0, s29
	ds_read_b128 v[160:163], v220 offset:32768
	ds_read_b128 v[164:167], v220 offset:33792
	ds_read_b128 v[168:171], v220 offset:34816
	ds_read_b128 v[172:175], v220 offset:35840
	ds_read_b128 v[196:199], v220 offset:36864
	ds_read_b128 v[202:205], v220 offset:37888
	ds_read_b128 v[206:209], v220 offset:38912
	ds_read_b128 v[232:235], v220 offset:39936
	global_load_lds_dwordx4 v180, s[16:17]
	s_mov_b32 m0, s34
	s_nop 0
	global_load_lds_dwordx4 v184, s[16:17]
	s_waitcnt vmcnt(8)
	s_waitcnt lgkmcnt(0)
	s_setprio 1
	s_barrier
	v_mfma_f32_16x16x32_bf16 v[124:127], v[128:131], v[160:163], v[124:127]
	v_mfma_f32_16x16x32_bf16 v[124:127], v[132:135], v[164:167], v[124:127]
	v_mfma_f32_16x16x32_bf16 v[108:111], v[128:131], v[168:171], v[108:111]
	v_mfma_f32_16x16x32_bf16 v[108:111], v[132:135], v[172:175], v[108:111]
	v_mfma_f32_16x16x32_bf16 v[92:95], v[128:131], v[196:199], v[92:95]
	v_mfma_f32_16x16x32_bf16 v[92:95], v[132:135], v[202:205], v[92:95]
	v_mfma_f32_16x16x32_bf16 v[76:79], v[128:131], v[206:209], v[76:79]
	v_mfma_f32_16x16x32_bf16 v[76:79], v[132:135], v[232:235], v[76:79]
	v_mfma_f32_16x16x32_bf16 v[120:123], v[136:139], v[160:163], v[120:123]
	v_mfma_f32_16x16x32_bf16 v[120:123], v[140:143], v[164:167], v[120:123]
	v_mfma_f32_16x16x32_bf16 v[104:107], v[136:139], v[168:171], v[104:107]
	v_mfma_f32_16x16x32_bf16 v[104:107], v[140:143], v[172:175], v[104:107]
	v_mfma_f32_16x16x32_bf16 v[88:91], v[136:139], v[196:199], v[88:91]
	v_mfma_f32_16x16x32_bf16 v[88:91], v[140:143], v[202:205], v[88:91]
	v_mfma_f32_16x16x32_bf16 v[72:75], v[136:139], v[206:209], v[72:75]
	v_mfma_f32_16x16x32_bf16 v[72:75], v[140:143], v[232:235], v[72:75]
	s_setprio 0
	s_setprio 1
	v_mfma_f32_16x16x32_bf16 v[116:119], v[144:147], v[160:163], v[116:119]
	v_mfma_f32_16x16x32_bf16 v[116:119], v[148:151], v[164:167], v[116:119]
	v_mfma_f32_16x16x32_bf16 v[100:103], v[144:147], v[168:171], v[100:103]
	v_mfma_f32_16x16x32_bf16 v[100:103], v[148:151], v[172:175], v[100:103]
	v_mfma_f32_16x16x32_bf16 v[84:87], v[144:147], v[196:199], v[84:87]
	v_mfma_f32_16x16x32_bf16 v[84:87], v[148:151], v[202:205], v[84:87]
	v_mfma_f32_16x16x32_bf16 v[68:71], v[144:147], v[206:209], v[68:71]
	v_mfma_f32_16x16x32_bf16 v[68:71], v[148:151], v[232:235], v[68:71]
	v_mfma_f32_16x16x32_bf16 v[112:115], v[152:155], v[160:163], v[112:115]
	v_mfma_f32_16x16x32_bf16 v[112:115], v[156:159], v[164:167], v[112:115]
	v_mfma_f32_16x16x32_bf16 v[96:99], v[152:155], v[168:171], v[96:99]
	v_mfma_f32_16x16x32_bf16 v[96:99], v[156:159], v[172:175], v[96:99]
	v_mfma_f32_16x16x32_bf16 v[80:83], v[152:155], v[196:199], v[80:83]
	v_mfma_f32_16x16x32_bf16 v[80:83], v[156:159], v[202:205], v[80:83]
	v_mfma_f32_16x16x32_bf16 v[64:67], v[152:155], v[206:209], v[64:67]
	v_mfma_f32_16x16x32_bf16 v[64:67], v[156:159], v[232:235], v[64:67]
	s_barrier
	s_setprio 0
	s_add_i32 s16, s72, s26
	s_mov_b32 m0, s16
	ds_read_b128 v[160:163], v220 offset:49152
	ds_read_b128 v[164:167], v220 offset:50176
	ds_read_b128 v[168:171], v220 offset:51200
	ds_read_b128 v[172:175], v220 offset:52224
	ds_read_b128 v[196:199], v220 offset:53248
	ds_read_b128 v[202:205], v220 offset:54272
	ds_read_b128 v[206:209], v220 offset:55296
	ds_read_b128 v[232:235], v220 offset:56320
	global_load_lds_dwordx4 v182, s[98:99]
	s_add_i32 m0, s16, 0x2000
	s_add_u32 s14, s14, 0x80080
	s_addc_u32 s15, s15, 0
	s_add_i32 s16, s73, s26
	global_load_lds_dwordx4 v186, s[98:99]
	s_mov_b32 m0, s16
	s_nop 0
	global_load_lds_dwordx4 v182, s[14:15]
	s_add_i32 m0, s16, 0x2000
	s_nop 0
	global_load_lds_dwordx4 v186, s[14:15]
	s_mov_b32 m0, s44
	s_nop 0
	global_load_lds_dwordx4 v180, s[100:101]
	s_mov_b32 m0, s45
	s_nop 0
	global_load_lds_dwordx4 v184, s[100:101]
	s_waitcnt vmcnt(8)
	s_waitcnt lgkmcnt(0)
	s_setprio 1
	s_barrier
	v_mfma_f32_16x16x32_bf16 v[60:63], v[128:131], v[160:163], v[60:63]
	v_mfma_f32_16x16x32_bf16 v[60:63], v[132:135], v[164:167], v[60:63]
	v_mfma_f32_16x16x32_bf16 v[44:47], v[128:131], v[168:171], v[44:47]
	v_mfma_f32_16x16x32_bf16 v[44:47], v[132:135], v[172:175], v[44:47]
	v_mfma_f32_16x16x32_bf16 v[28:31], v[128:131], v[196:199], v[28:31]
	v_mfma_f32_16x16x32_bf16 v[28:31], v[132:135], v[202:205], v[28:31]
	v_mfma_f32_16x16x32_bf16 v[12:15], v[128:131], v[206:209], v[12:15]
	v_mfma_f32_16x16x32_bf16 v[12:15], v[132:135], v[232:235], v[12:15]
	v_mfma_f32_16x16x32_bf16 v[56:59], v[136:139], v[160:163], v[56:59]
	v_mfma_f32_16x16x32_bf16 v[56:59], v[140:143], v[164:167], v[56:59]
	v_mfma_f32_16x16x32_bf16 v[40:43], v[136:139], v[168:171], v[40:43]
	v_mfma_f32_16x16x32_bf16 v[40:43], v[140:143], v[172:175], v[40:43]
	v_mfma_f32_16x16x32_bf16 v[24:27], v[136:139], v[196:199], v[24:27]
	v_mfma_f32_16x16x32_bf16 v[24:27], v[140:143], v[202:205], v[24:27]
	v_mfma_f32_16x16x32_bf16 v[8:11], v[136:139], v[206:209], v[8:11]
	v_mfma_f32_16x16x32_bf16 v[8:11], v[140:143], v[232:235], v[8:11]
	s_setprio 0
	s_setprio 1
	v_mfma_f32_16x16x32_bf16 v[52:55], v[144:147], v[160:163], v[52:55]
	v_mfma_f32_16x16x32_bf16 v[52:55], v[148:151], v[164:167], v[52:55]
	v_mfma_f32_16x16x32_bf16 v[36:39], v[144:147], v[168:171], v[36:39]
	v_mfma_f32_16x16x32_bf16 v[36:39], v[148:151], v[172:175], v[36:39]
	v_mfma_f32_16x16x32_bf16 v[20:23], v[144:147], v[196:199], v[20:23]
	v_mfma_f32_16x16x32_bf16 v[20:23], v[148:151], v[202:205], v[20:23]
	v_mfma_f32_16x16x32_bf16 v[4:7], v[144:147], v[206:209], v[4:7]
	v_mfma_f32_16x16x32_bf16 v[4:7], v[148:151], v[232:235], v[4:7]
	v_mfma_f32_16x16x32_bf16 v[48:51], v[152:155], v[160:163], v[48:51]
	v_mfma_f32_16x16x32_bf16 v[48:51], v[156:159], v[164:167], v[48:51]
	v_mfma_f32_16x16x32_bf16 v[32:35], v[152:155], v[168:171], v[32:35]
	v_mfma_f32_16x16x32_bf16 v[32:35], v[156:159], v[172:175], v[32:35]
	v_mfma_f32_16x16x32_bf16 v[16:19], v[152:155], v[196:199], v[16:19]
	v_mfma_f32_16x16x32_bf16 v[16:19], v[156:159], v[202:205], v[16:19]
	v_mfma_f32_16x16x32_bf16 v[0:3], v[152:155], v[206:209], v[0:3]
	v_mfma_f32_16x16x32_bf16 v[0:3], v[156:159], v[232:235], v[0:3]
	s_barrier
	s_setprio 0
	s_add_i32 s71, s71, 2
	s_add_u32 s68, s68, 0x100
	s_addc_u32 s69, s69, 0
	s_add_u32 s67, s67, 0x100
	s_addc_u32 s70, s70, 0
	s_cmp_gt_u32 s71, 29
	s_cbranch_scc0 .LBB0_896
	s_and_b64 vcc, exec, s[38:39]
	s_cbranch_vccz .LBB0_899
	s_barrier

;     __device__ bool next(int i, Unit& u) const { if (!base.next(i >> 1, u)) return false; u.sub = i & 1; return true; }
; #define PG8_STAGE(bufoff, gbase, voff) do { _Pragma("unroll") for (int _i = 0; _i < 2; ++_i) \
;         __builtin_amdgcn_global_load_lds((const unsigned*)((const char*)(gbase) + (voff)[_i]), (PG8_LAS unsigned*)(lds + (bufoff) + ldsw + _i * 8192), 16, 0, 0); } while (0)
; #define PG8_LDA(dst, b, h) do { _Pragma("unroll") for (int m = 0; m < 4; ++m) _Pragma("unroll") for (int k = 0; k < 2; ++k) dst[m][k] = *(const PG8_LAS bf16x8*)(lds + PG8_SA(b, h) + aoff + m * 2048 + k * 1024); } while (0)
; #define PG8_LDB(dst, b, h) do { _Pragma("unroll") for (int n = 0; n < 2; ++n) _Pragma("unroll") for (int k = 0; k < 2; ++k) dst[n][k] = *(const PG8_LAS bf16x8*)(lds + PG8_SB(b, h) + boff + n * 2048 + k * 1024); } while (0)
; #define PG8_WAIT_V(n) asm volatile("s_waitcnt vmcnt(" #n ")" ::: "memory")
; template <class Epi, class Sched, bool ALIGN_EPI = false, bool SP2 = false, bool DUAL = false>
; __device__ __forceinline__ void gemm_phase(PG8_LAS unsigned char* lds, const Gemm g, const Sched& S, const Epi& E) {
;     ...
;         const bool has_next = S.next(ui + 1, nxt);
;         const char* nA = has_next ? (const char*)((DUAL && nxt.sub) ? g.A2 : g.A) + (size_t)nxt.pm * tstep : cA; const char* nB = has_next ? (const char*)((DUAL && nxt.sub) ? g.Bt2 : g.Bt) + (size_t)nxt.pn * tstep : cB;
;         for (int t = 0; t < nt; t += 2) {
;             const bool last = (t == nt - 2);
;             const char* a1 = cA + (size_t)(t + 1) * kstep;
;             const char* a2 = last ? nA : cA + (size_t)(t + 2) * kstep; const char* b2 = last ? nB : cB + (size_t)(t + 2) * kstep;
;             const char* a3 = a2 + kstep; const char* b3 = b2 + kstep;
;             if (last && has_next) S.a_ready(nxt);
;             if constexpr (SP2) {
;             PG8_LDB(B0, 0, 0); PG8_LDB(B1, 0, 1); PG8_SCHED; PG8_LDA(At, 0, 0); PG8_STAGE(PG8_SA(1, 1), a1 + hstep, voffA);
;             PG8_WAIT_V(8); PG8_WAIT_L(0); PG8_BAR; PG8_MMA(0, 0, At, B0); PG8_MMA(0, 1, At, B1); PG8_BAR; PG8_SCHED;
;             PG8_LDA(At, 0, 1); PG8_STAGE(PG8_SB(0, 0), b2, voffB); PG8_STAGE(PG8_SB(0, 1), b2 + hstep, voffB); PG8_STAGE(PG8_SA(0, 0), a2, voffA);
;             PG8_WAIT_V(8); PG8_WAIT_L(0); PG8_BAR; PG8_MMA(1, 0, At, B0); PG8_MMA(1, 1, At, B1); PG8_BAR; PG8_SCHED;
.LBB0_991:
	s_ashr_i32 s25, s24, 31
	s_lshl_b64 s[28:29], s[24:25], 20
	s_add_u32 s30, s19, s28
	s_addc_u32 s31, s21, s29
	s_and_b64 s[28:29], s[4:5], exec
	s_cselect_b32 s25, s31, s27
	s_cselect_b32 s28, s30, s26
	s_ashr_i32 s23, s22, 31
	s_lshl_b64 s[36:37], s[22:23], 20
	s_add_u32 s36, s8, s36
	s_addc_u32 s37, s9, s37
	s_and_b64 s[40:41], s[4:5], exec
	s_cselect_b32 s23, s37, s15
	s_cselect_b32 s29, s36, s14
	s_add_u32 s40, s26, 0x80080
	s_addc_u32 s41, s27, 0
	s_add_u32 s63, s14, 0x100
	s_addc_u32 s64, s15, 0
	s_mov_b32 s65, -2
	s_add_u32 s14, s40, 0xfff80080
	s_addc_u32 s15, s41, -1
	s_cmp_eq_u32 s65, 28
	s_cselect_b32 s27, s25, s15
	s_cselect_b32 s26, s28, s14
	s_cselect_b32 s15, s23, s64
	s_cselect_b32 s14, s29, s63
	s_waitcnt vmcnt(8)
	s_waitcnt lgkmcnt(0)
	s_setprio 1
	s_barrier
	v_mfma_f32_16x16x32_bf16 v[124:127], v[128:131], v[160:163], 0
	v_mfma_f32_16x16x32_bf16 v[124:127], v[132:135], v[164:167], v[124:127]
	v_mfma_f32_16x16x32_bf16 v[108:111], v[128:131], v[188:191], 0
	v_mfma_f32_16x16x32_bf16 v[108:111], v[132:135], v[192:195], v[108:111]
	v_mfma_f32_16x16x32_bf16 v[92:95], v[128:131], v[196:199], 0
	v_mfma_f32_16x16x32_bf16 v[92:95], v[132:135], v[202:205], v[92:95]
	v_mfma_f32_16x16x32_bf16 v[76:79], v[128:131], v[206:209], 0
	v_mfma_f32_16x16x32_bf16 v[76:79], v[132:135], v[220:223], v[76:79]
	v_mfma_f32_16x16x32_bf16 v[120:123], v[136:139], v[160:163], 0
	v_mfma_f32_16x16x32_bf16 v[120:123], v[140:143], v[164:167], v[120:123]
	v_mfma_f32_16x16x32_bf16 v[104:107], v[136:139], v[188:191], 0
	v_mfma_f32_16x16x32_bf16 v[104:107], v[140:143], v[192:195], v[104:107]
	v_mfma_f32_16x16x32_bf16 v[88:91], v[136:139], v[196:199], 0
	v_mfma_f32_16x16x32_bf16 v[88:91], v[140:143], v[202:205], v[88:91]
	v_mfma_f32_16x16x32_bf16 v[72:75], v[136:139], v[206:209], 0
	v_mfma_f32_16x16x32_bf16 v[72:75], v[140:143], v[220:223], v[72:75]
	s_setprio 0
	s_setprio 1
	v_mfma_f32_16x16x32_bf16 v[116:119], v[144:147], v[160:163], 0
	v_mfma_f32_16x16x32_bf16 v[116:119], v[148:151], v[164:167], v[116:119]
	v_mfma_f32_16x16x32_bf16 v[100:103], v[144:147], v[188:191], 0
	v_mfma_f32_16x16x32_bf16 v[100:103], v[148:151], v[192:195], v[100:103]
	v_mfma_f32_16x16x32_bf16 v[84:87], v[144:147], v[196:199], 0
	v_mfma_f32_16x16x32_bf16 v[84:87], v[148:151], v[202:205], v[84:87]
	v_mfma_f32_16x16x32_bf16 v[68:71], v[144:147], v[206:209], 0
	v_mfma_f32_16x16x32_bf16 v[68:71], v[148:151], v[220:223], v[68:71]
	v_mfma_f32_16x16x32_bf16 v[112:115], v[152:155], v[160:163], 0
	v_mfma_f32_16x16x32_bf16 v[112:115], v[156:159], v[164:167], v[112:115]
	v_mfma_f32_16x16x32_bf16 v[96:99], v[152:155], v[188:191], 0
	v_mfma_f32_16x16x32_bf16 v[96:99], v[156:159], v[192:195], v[96:99]
	v_mfma_f32_16x16x32_bf16 v[80:83], v[152:155], v[196:199], 0
	v_mfma_f32_16x16x32_bf16 v[80:83], v[156:159], v[202:205], v[80:83]
	v_mfma_f32_16x16x32_bf16 v[64:67], v[152:155], v[206:209], 0
	v_mfma_f32_16x16x32_bf16 v[64:67], v[156:159], v[220:223], v[64:67]
	s_barrier
	s_setprio 0
	s_add_u32 s98, s14, 0x80
	s_addc_u32 s99, s15, 0
	s_add_u32 s100, s26, 0x80
	s_addc_u32 s101, s27, 0
	s_add_i32 m0, s39, 0xc000
	s_nop 0
	global_load_lds_dwordx4 v180, s[40:41]
	s_add_i32 m0, s39, 0xe000
	s_nop 0
	global_load_lds_dwordx4 v182, s[40:41]
	s_add_i32 s66, s50, s34
	s_mov_b32 m0, s66
	ds_read_b128 v[160:163], v217 offset:16384
	ds_read_b128 v[164:167], v217 offset:17408
	ds_read_b128 v[188:191], v217 offset:18432
	ds_read_b128 v[192:195], v217 offset:19456
	ds_read_b128 v[196:199], v217 offset:20480
	ds_read_b128 v[202:205], v217 offset:21504
	ds_read_b128 v[206:209], v217 offset:22528
	ds_read_b128 v[220:223], v217 offset:23552
	global_load_lds_dwordx4 v170, s[14:15]
	s_add_i32 m0, s66, 0x2000
	s_add_u32 s66, s14, 0x80000
	s_addc_u32 s67, s15, 0
	s_add_i32 s68, s51, s34
	global_load_lds_dwordx4 v174, s[14:15]
	s_mov_b32 m0, s68
	s_nop 0
	global_load_lds_dwordx4 v170, s[66:67]
	s_add_i32 m0, s68, 0x2000
	s_nop 0
	global_load_lds_dwordx4 v174, s[66:67]
	s_mov_b32 m0, s39
	s_nop 0
	global_load_lds_dwordx4 v168, s[26:27]
	s_mov_b32 m0, s42
	s_nop 0
	global_load_lds_dwordx4 v172, s[26:27]
	s_waitcnt vmcnt(8)
	s_waitcnt lgkmcnt(0)
	s_setprio 1
	s_barrier
	v_mfma_f32_16x16x32_bf16 v[60:63], v[128:131], v[160:163], 0
	v_mfma_f32_16x16x32_bf16 v[60:63], v[132:135], v[164:167], v[60:63]
	v_mfma_f32_16x16x32_bf16 v[44:47], v[128:131], v[188:191], 0
	v_mfma_f32_16x16x32_bf16 v[44:47], v[132:135], v[192:195], v[44:47]
	v_mfma_f32_16x16x32_bf16 v[28:31], v[128:131], v[196:199], 0
	v_mfma_f32_16x16x32_bf16 v[28:31], v[132:135], v[202:205], v[28:31]
	v_mfma_f32_16x16x32_bf16 v[12:15], v[128:131], v[206:209], 0
	v_mfma_f32_16x16x32_bf16 v[12:15], v[132:135], v[220:223], v[12:15]
	v_mfma_f32_16x16x32_bf16 v[56:59], v[136:139], v[160:163], 0
	v_mfma_f32_16x16x32_bf16 v[56:59], v[140:143], v[164:167], v[56:59]
	v_mfma_f32_16x16x32_bf16 v[40:43], v[136:139], v[188:191], 0
	v_mfma_f32_16x16x32_bf16 v[40:43], v[140:143], v[192:195], v[40:43]
	v_mfma_f32_16x16x32_bf16 v[24:27], v[136:139], v[196:199], 0
	v_mfma_f32_16x16x32_bf16 v[24:27], v[140:143], v[202:205], v[24:27]
	v_mfma_f32_16x16x32_bf16 v[8:11], v[136:139], v[206:209], 0
	v_mfma_f32_16x16x32_bf16 v[8:11], v[140:143], v[220:223], v[8:11]
	s_setprio 0
	s_setprio 1
	v_mfma_f32_16x16x32_bf16 v[52:55], v[144:147], v[160:163], 0
	v_mfma_f32_16x16x32_bf16 v[52:55], v[148:151], v[164:167], v[52:55]
	v_mfma_f32_16x16x32_bf16 v[36:39], v[144:147], v[188:191], 0
	v_mfma_f32_16x16x32_bf16 v[36:39], v[148:151], v[192:195], v[36:39]
	v_mfma_f32_16x16x32_bf16 v[20:23], v[144:147], v[196:199], 0
	v_mfma_f32_16x16x32_bf16 v[20:23], v[148:151], v[202:205], v[20:23]
	v_mfma_f32_16x16x32_bf16 v[4:7], v[144:147], v[206:209], 0
	v_mfma_f32_16x16x32_bf16 v[4:7], v[148:151], v[220:223], v[4:7]
	v_mfma_f32_16x16x32_bf16 v[48:51], v[152:155], v[160:163], 0
	v_mfma_f32_16x16x32_bf16 v[48:51], v[156:159], v[164:167], v[48:51]
	v_mfma_f32_16x16x32_bf16 v[32:35], v[152:155], v[188:191], 0
	v_mfma_f32_16x16x32_bf16 v[32:35], v[156:159], v[192:195], v[32:35]
	v_mfma_f32_16x16x32_bf16 v[16:19], v[152:155], v[196:199], 0
	v_mfma_f32_16x16x32_bf16 v[16:19], v[156:159], v[202:205], v[16:19]
	v_mfma_f32_16x16x32_bf16 v[0:3], v[152:155], v[206:209], 0
	v_mfma_f32_16x16x32_bf16 v[0:3], v[156:159], v[220:223], v[0:3]
	s_barrier
; #define PG8_STAGE(bufoff, gbase, voff) do { _Pragma("unroll") for (int _i = 0; _i < 2; ++_i) \
;         __builtin_amdgcn_global_load_lds((const unsigned*)((const char*)(gbase) + (voff)[_i]), (PG8_LAS unsigned*)(lds + (bufoff) + ldsw + _i * 8192), 16, 0, 0); } while (0)
; #define PG8_LDA(dst, b, h) do { _Pragma("unroll") for (int m = 0; m < 4; ++m) _Pragma("unroll") for (int k = 0; k < 2; ++k) dst[m][k] = *(const PG8_LAS bf16x8*)(lds + PG8_SA(b, h) + aoff + m * 2048 + k * 1024); } while (0)
; #define PG8_LDB(dst, b, h) do { _Pragma("unroll") for (int n = 0; n < 2; ++n) _Pragma("unroll") for (int k = 0; k < 2; ++k) dst[n][k] = *(const PG8_LAS bf16x8*)(lds + PG8_SB(b, h) + boff + n * 2048 + k * 1024); } while (0)
; #define PG8_MMA(ai, bj, At, Bt) do { __builtin_amdgcn_s_setprio(1); _Pragma("unroll") for (int m = 0; m < 4; ++m) _Pragma("unroll") for (int n = 0; n < 2; ++n) _Pragma("unroll") for (int k = 0; k < 2; ++k) \
;         acc[ai][bj][m][n] = __builtin_amdgcn_mfma_f32_16x16x32_bf16(Bt[n][k], At[m][k], acc[ai][bj][m][n], 0, 0, 0); __builtin_amdgcn_s_setprio(0); } while (0)
; #define PG8_WAIT_V(n) asm volatile("s_waitcnt vmcnt(" #n ")" ::: "memory")
; #define PG8_WAIT_L(n) asm volatile("s_waitcnt lgkmcnt(" #n ")" ::: "memory")
; #define PG8_BAR __builtin_amdgcn_s_barrier()
; #define PG8_SCHED __builtin_amdgcn_sched_barrier(0)
; template <class Epi, class Sched, bool ALIGN_EPI = false, bool SP2 = false, bool DUAL = false>
; __device__ __forceinline__ void gemm_phase(PG8_LAS unsigned char* lds, const Gemm g, const Sched& S, const Epi& E) {
;     ...
;             PG8_LDB(B0, 1, 0); PG8_LDB(B1, 1, 1); PG8_SCHED; PG8_LDA(At, 1, 0); PG8_STAGE(PG8_SA(0, 1), a2 + hstep, voffA);
;             PG8_WAIT_V(8); PG8_WAIT_L(0); PG8_BAR; PG8_MMA(0, 0, At, B0); PG8_MMA(0, 1, At, B1); PG8_BAR; PG8_SCHED;
;             PG8_LDA(At, 1, 1); PG8_STAGE(PG8_SB(1, 0), b3, voffB); PG8_STAGE(PG8_SB(1, 1), b3 + hstep, voffB); PG8_STAGE(PG8_SA(1, 0), a3, voffA);
;             PG8_WAIT_V(8); PG8_WAIT_L(0); PG8_BAR; PG8_MMA(1, 0, At, B0); PG8_MMA(1, 1, At, B1); PG8_BAR; PG8_SCHED;
	s_setprio 0
	s_add_i32 s66, 0, 0x18000
	s_add_i32 s67, 0, 0x1c000
	ds_read_b128 v[128:131], v215 offset:32768
	ds_read_b128 v[132:135], v215 offset:33792
	ds_read_b128 v[136:139], v215 offset:34816
	ds_read_b128 v[140:143], v215 offset:35840
	ds_read_b128 v[144:147], v216 offset:32768
	ds_read_b128 v[148:151], v216 offset:33792
	ds_read_b128 v[152:155], v216 offset:34816
	ds_read_b128 v[156:159], v216 offset:35840
	s_add_u32 s26, s26, 0x80000
	s_addc_u32 s27, s27, 0
	s_mov_b32 m0, s43
	ds_read_b128 v[160:163], v217 offset:32768
	ds_read_b128 v[164:167], v217 offset:33792
	ds_read_b128 v[188:191], v217 offset:34816
	ds_read_b128 v[192:195], v217 offset:35840
	ds_read_b128 v[196:199], v217 offset:36864
	ds_read_b128 v[202:205], v217 offset:37888
	ds_read_b128 v[206:209], v217 offset:38912
	ds_read_b128 v[220:223], v217 offset:39936
	global_load_lds_dwordx4 v168, s[26:27]
	s_mov_b32 m0, s44
	s_nop 0
	global_load_lds_dwordx4 v172, s[26:27]
	s_waitcnt vmcnt(8)
	s_waitcnt lgkmcnt(0)
	s_setprio 1
	s_barrier
	v_mfma_f32_16x16x32_bf16 v[124:127], v[128:131], v[160:163], v[124:127]
	v_mfma_f32_16x16x32_bf16 v[124:127], v[132:135], v[164:167], v[124:127]
	v_mfma_f32_16x16x32_bf16 v[108:111], v[128:131], v[188:191], v[108:111]
	v_mfma_f32_16x16x32_bf16 v[108:111], v[132:135], v[192:195], v[108:111]
	v_mfma_f32_16x16x32_bf16 v[92:95], v[128:131], v[196:199], v[92:95]
	v_mfma_f32_16x16x32_bf16 v[92:95], v[132:135], v[202:205], v[92:95]
	v_mfma_f32_16x16x32_bf16 v[76:79], v[128:131], v[206:209], v[76:79]
	v_mfma_f32_16x16x32_bf16 v[76:79], v[132:135], v[220:223], v[76:79]
	v_mfma_f32_16x16x32_bf16 v[120:123], v[136:139], v[160:163], v[120:123]
	v_mfma_f32_16x16x32_bf16 v[120:123], v[140:143], v[164:167], v[120:123]
	v_mfma_f32_16x16x32_bf16 v[104:107], v[136:139], v[188:191], v[104:107]
	v_mfma_f32_16x16x32_bf16 v[104:107], v[140:143], v[192:195], v[104:107]
	v_mfma_f32_16x16x32_bf16 v[88:91], v[136:139], v[196:199], v[88:91]
	v_mfma_f32_16x16x32_bf16 v[88:91], v[140:143], v[202:205], v[88:91]
	v_mfma_f32_16x16x32_bf16 v[72:75], v[136:139], v[206:209], v[72:75]
	v_mfma_f32_16x16x32_bf16 v[72:75], v[140:143], v[220:223], v[72:75]
	s_setprio 0
	s_setprio 1
	v_mfma_f32_16x16x32_bf16 v[116:119], v[144:147], v[160:163], v[116:119]
	v_mfma_f32_16x16x32_bf16 v[116:119], v[148:151], v[164:167], v[116:119]
	v_mfma_f32_16x16x32_bf16 v[100:103], v[144:147], v[188:191], v[100:103]
	v_mfma_f32_16x16x32_bf16 v[100:103], v[148:151], v[192:195], v[100:103]
	v_mfma_f32_16x16x32_bf16 v[84:87], v[144:147], v[196:199], v[84:87]
	v_mfma_f32_16x16x32_bf16 v[84:87], v[148:151], v[202:205], v[84:87]
	v_mfma_f32_16x16x32_bf16 v[68:71], v[144:147], v[206:209], v[68:71]
	v_mfma_f32_16x16x32_bf16 v[68:71], v[148:151], v[220:223], v[68:71]
	v_mfma_f32_16x16x32_bf16 v[112:115], v[152:155], v[160:163], v[112:115]
	v_mfma_f32_16x16x32_bf16 v[112:115], v[156:159], v[164:167], v[112:115]
	v_mfma_f32_16x16x32_bf16 v[96:99], v[152:155], v[188:191], v[96:99]
	v_mfma_f32_16x16x32_bf16 v[96:99], v[156:159], v[192:195], v[96:99]
	v_mfma_f32_16x16x32_bf16 v[80:83], v[152:155], v[196:199], v[80:83]
	v_mfma_f32_16x16x32_bf16 v[80:83], v[156:159], v[202:205], v[80:83]
	v_mfma_f32_16x16x32_bf16 v[64:67], v[152:155], v[206:209], v[64:67]
	v_mfma_f32_16x16x32_bf16 v[64:67], v[156:159], v[220:223], v[64:67]
	s_barrier
	s_setprio 0
	s_add_i32 s26, s66, s34
	s_mov_b32 m0, s26
	ds_read_b128 v[160:163], v217 offset:49152
	ds_read_b128 v[164:167], v217 offset:50176
	ds_read_b128 v[188:191], v217 offset:51200
	ds_read_b128 v[192:195], v217 offset:52224
	ds_read_b128 v[196:199], v217 offset:53248
	ds_read_b128 v[202:205], v217 offset:54272
	ds_read_b128 v[206:209], v217 offset:55296
	ds_read_b128 v[220:223], v217 offset:56320
	global_load_lds_dwordx4 v170, s[98:99]
	s_add_i32 m0, s26, 0x2000
	s_add_u32 s14, s14, 0x80080
	s_addc_u32 s15, s15, 0
	s_add_i32 s26, s67, s34
	global_load_lds_dwordx4 v174, s[98:99]
	s_mov_b32 m0, s26
	s_nop 0
	global_load_lds_dwordx4 v170, s[14:15]
	s_add_i32 m0, s26, 0x2000
	s_nop 0
	global_load_lds_dwordx4 v174, s[14:15]
	s_mov_b32 m0, s47
	s_nop 0
	global_load_lds_dwordx4 v168, s[100:101]
	s_mov_b32 m0, s48
	s_nop 0
	global_load_lds_dwordx4 v172, s[100:101]
	s_waitcnt vmcnt(8)
	s_waitcnt lgkmcnt(0)
	s_setprio 1
	s_barrier
	v_mfma_f32_16x16x32_bf16 v[60:63], v[128:131], v[160:163], v[60:63]
	v_mfma_f32_16x16x32_bf16 v[60:63], v[132:135], v[164:167], v[60:63]
	v_mfma_f32_16x16x32_bf16 v[44:47], v[128:131], v[188:191], v[44:47]
	v_mfma_f32_16x16x32_bf16 v[44:47], v[132:135], v[192:195], v[44:47]
	v_mfma_f32_16x16x32_bf16 v[28:31], v[128:131], v[196:199], v[28:31]
	v_mfma_f32_16x16x32_bf16 v[28:31], v[132:135], v[202:205], v[28:31]
	v_mfma_f32_16x16x32_bf16 v[12:15], v[128:131], v[206:209], v[12:15]
	v_mfma_f32_16x16x32_bf16 v[12:15], v[132:135], v[220:223], v[12:15]
	v_mfma_f32_16x16x32_bf16 v[56:59], v[136:139], v[160:163], v[56:59]
	v_mfma_f32_16x16x32_bf16 v[56:59], v[140:143], v[164:167], v[56:59]
	v_mfma_f32_16x16x32_bf16 v[40:43], v[136:139], v[188:191], v[40:43]
	v_mfma_f32_16x16x32_bf16 v[40:43], v[140:143], v[192:195], v[40:43]
	v_mfma_f32_16x16x32_bf16 v[24:27], v[136:139], v[196:199], v[24:27]
	v_mfma_f32_16x16x32_bf16 v[24:27], v[140:143], v[202:205], v[24:27]
	v_mfma_f32_16x16x32_bf16 v[8:11], v[136:139], v[206:209], v[8:11]
	v_mfma_f32_16x16x32_bf16 v[8:11], v[140:143], v[220:223], v[8:11]
	s_setprio 0
	s_setprio 1
	v_mfma_f32_16x16x32_bf16 v[52:55], v[144:147], v[160:163], v[52:55]
	v_mfma_f32_16x16x32_bf16 v[52:55], v[148:151], v[164:167], v[52:55]
	v_mfma_f32_16x16x32_bf16 v[36:39], v[144:147], v[188:191], v[36:39]
	v_mfma_f32_16x16x32_bf16 v[36:39], v[148:151], v[192:195], v[36:39]
	v_mfma_f32_16x16x32_bf16 v[20:23], v[144:147], v[196:199], v[20:23]
	v_mfma_f32_16x16x32_bf16 v[20:23], v[148:151], v[202:205], v[20:23]
	v_mfma_f32_16x16x32_bf16 v[4:7], v[144:147], v[206:209], v[4:7]
	v_mfma_f32_16x16x32_bf16 v[4:7], v[148:151], v[220:223], v[4:7]
	v_mfma_f32_16x16x32_bf16 v[48:51], v[152:155], v[160:163], v[48:51]
	v_mfma_f32_16x16x32_bf16 v[48:51], v[156:159], v[164:167], v[48:51]
	v_mfma_f32_16x16x32_bf16 v[32:35], v[152:155], v[188:191], v[32:35]
	v_mfma_f32_16x16x32_bf16 v[32:35], v[156:159], v[192:195], v[32:35]
	v_mfma_f32_16x16x32_bf16 v[16:19], v[152:155], v[196:199], v[16:19]
	v_mfma_f32_16x16x32_bf16 v[16:19], v[156:159], v[202:205], v[16:19]
	v_mfma_f32_16x16x32_bf16 v[0:3], v[152:155], v[206:209], v[0:3]
	v_mfma_f32_16x16x32_bf16 v[0:3], v[156:159], v[220:223], v[0:3]
	s_barrier
	s_setprio 0
	s_add_i32 s65, s65, 2
	s_add_u32 s40, s40, 0x100
	s_addc_u32 s41, s41, 0
	s_add_u32 s63, s63, 0x100
	s_addc_u32 s64, s64, 0
; #define PG8_STAGE(bufoff, gbase, voff) do { _Pragma("unroll") for (int _i = 0; _i < 2; ++_i) \
;         __builtin_amdgcn_global_load_lds((const unsigned*)((const char*)(gbase) + (voff)[_i]), (PG8_LAS unsigned*)(lds + (bufoff) + ldsw + _i * 8192), 16, 0, 0); } while (0)
; #define PG8_LDA(dst, b, h) do { _Pragma("unroll") for (int m = 0; m < 4; ++m) _Pragma("unroll") for (int k = 0; k < 2; ++k) dst[m][k] = *(const PG8_LAS bf16x8*)(lds + PG8_SA(b, h) + aoff + m * 2048 + k * 1024); } while (0)
; #define PG8_LDB(dst, b, h) do { _Pragma("unroll") for (int n = 0; n < 2; ++n) _Pragma("unroll") for (int k = 0; k < 2; ++k) dst[n][k] = *(const PG8_LAS bf16x8*)(lds + PG8_SB(b, h) + boff + n * 2048 + k * 1024); } while (0)
; #define PG8_MMA(ai, bj, At, Bt) do { __builtin_amdgcn_s_setprio(1); _Pragma("unroll") for (int m = 0; m < 4; ++m) _Pragma("unroll") for (int n = 0; n < 2; ++n) _Pragma("unroll") for (int k = 0; k < 2; ++k) \
;         acc[ai][bj][m][n] = __builtin_amdgcn_mfma_f32_16x16x32_bf16(Bt[n][k], At[m][k], acc[ai][bj][m][n], 0, 0, 0); __builtin_amdgcn_s_setprio(0); } while (0)
; #define PG8_WAIT_V(n) asm volatile("s_waitcnt vmcnt(" #n ")" ::: "memory")
; #define PG8_WAIT_L(n) asm volatile("s_waitcnt lgkmcnt(" #n ")" ::: "memory")
; template <class Epi, class Sched, bool ALIGN_EPI = false, bool SP2 = false, bool DUAL = false>
; __device__ __forceinline__ void gemm_phase(PG8_LAS unsigned char* lds, const Gemm g, const Sched& S, const Epi& E) {
;     ...
;             const bool last = (t == nt - 2);
;             const char* a1 = cA + (size_t)(t + 1) * kstep;
;             const char* a2 = last ? nA : cA + (size_t)(t + 2) * kstep; const char* b2 = last ? nB : cB + (size_t)(t + 2) * kstep;
;             const char* a3 = a2 + kstep; const char* b3 = b2 + kstep;
;             if (last && has_next) S.a_ready(nxt);
;             if constexpr (SP2) {
;             PG8_LDB(B0, 0, 0); PG8_LDB(B1, 0, 1); PG8_SCHED; PG8_LDA(At, 0, 0); PG8_STAGE(PG8_SA(1, 1), a1 + hstep, voffA);
;             PG8_WAIT_V(8); PG8_WAIT_L(0); PG8_BAR; PG8_MMA(0, 0, At, B0); PG8_MMA(0, 1, At, B1); PG8_BAR; PG8_SCHED;
;             PG8_LDA(At, 0, 1); PG8_STAGE(PG8_SB(0, 0), b2, voffB); PG8_STAGE(PG8_SB(0, 1), b2 + hstep, voffB); PG8_STAGE(PG8_SA(0, 0), a2, voffA);
;             PG8_WAIT_V(8); PG8_WAIT_L(0); PG8_BAR; PG8_MMA(1, 0, At, B0); PG8_MMA(1, 1, At, B1); PG8_BAR; PG8_SCHED;
.LBB0_992:
	ds_read_b128 v[128:131], v215
	ds_read_b128 v[132:135], v215 offset:1024
	ds_read_b128 v[136:139], v215 offset:2048
	ds_read_b128 v[140:143], v215 offset:3072
	ds_read_b128 v[144:147], v216
	ds_read_b128 v[148:151], v216 offset:1024
	ds_read_b128 v[152:155], v216 offset:2048
	ds_read_b128 v[156:159], v216 offset:3072
	s_add_u32 s14, s40, 0xfff80080
	s_addc_u32 s15, s41, -1
	s_cmp_eq_u32 s65, 28
	s_cselect_b32 s27, s25, s15
	s_cselect_b32 s26, s28, s14
	s_cselect_b32 s15, s23, s64
	s_cselect_b32 s14, s29, s63
	s_add_i32 m0, s39, 0xc000
	ds_read_b128 v[160:163], v217
	ds_read_b128 v[164:167], v217 offset:1024
	ds_read_b128 v[188:191], v217 offset:2048
	ds_read_b128 v[192:195], v217 offset:3072
	ds_read_b128 v[196:199], v217 offset:4096
	ds_read_b128 v[202:205], v217 offset:5120
	ds_read_b128 v[206:209], v217 offset:6144
	ds_read_b128 v[220:223], v217 offset:7168
	global_load_lds_dwordx4 v180, s[40:41]
	s_add_i32 m0, s39, 0xe000
	s_nop 0
	global_load_lds_dwordx4 v182, s[40:41]
	s_waitcnt vmcnt(8)
	s_waitcnt lgkmcnt(0)
	s_setprio 1
	s_barrier
	v_mfma_f32_16x16x32_bf16 v[124:127], v[128:131], v[160:163], v[124:127]
	v_mfma_f32_16x16x32_bf16 v[124:127], v[132:135], v[164:167], v[124:127]
	v_mfma_f32_16x16x32_bf16 v[108:111], v[128:131], v[188:191], v[108:111]
	v_mfma_f32_16x16x32_bf16 v[108:111], v[132:135], v[192:195], v[108:111]
	v_mfma_f32_16x16x32_bf16 v[92:95], v[128:131], v[196:199], v[92:95]
	v_mfma_f32_16x16x32_bf16 v[92:95], v[132:135], v[202:205], v[92:95]
	v_mfma_f32_16x16x32_bf16 v[76:79], v[128:131], v[206:209], v[76:79]
	v_mfma_f32_16x16x32_bf16 v[76:79], v[132:135], v[220:223], v[76:79]
	v_mfma_f32_16x16x32_bf16 v[120:123], v[136:139], v[160:163], v[120:123]
	v_mfma_f32_16x16x32_bf16 v[120:123], v[140:143], v[164:167], v[120:123]
	v_mfma_f32_16x16x32_bf16 v[104:107], v[136:139], v[188:191], v[104:107]
	v_mfma_f32_16x16x32_bf16 v[104:107], v[140:143], v[192:195], v[104:107]
	v_mfma_f32_16x16x32_bf16 v[88:91], v[136:139], v[196:199], v[88:91]
	v_mfma_f32_16x16x32_bf16 v[88:91], v[140:143], v[202:205], v[88:91]
	v_mfma_f32_16x16x32_bf16 v[72:75], v[136:139], v[206:209], v[72:75]
	v_mfma_f32_16x16x32_bf16 v[72:75], v[140:143], v[220:223], v[72:75]
	s_setprio 0
	s_setprio 1
	v_mfma_f32_16x16x32_bf16 v[116:119], v[144:147], v[160:163], v[116:119]
	v_mfma_f32_16x16x32_bf16 v[116:119], v[148:151], v[164:167], v[116:119]
	v_mfma_f32_16x16x32_bf16 v[100:103], v[144:147], v[188:191], v[100:103]
	v_mfma_f32_16x16x32_bf16 v[100:103], v[148:151], v[192:195], v[100:103]
	v_mfma_f32_16x16x32_bf16 v[84:87], v[144:147], v[196:199], v[84:87]
	v_mfma_f32_16x16x32_bf16 v[84:87], v[148:151], v[202:205], v[84:87]
	v_mfma_f32_16x16x32_bf16 v[68:71], v[144:147], v[206:209], v[68:71]
	v_mfma_f32_16x16x32_bf16 v[68:71], v[148:151], v[220:223], v[68:71]
	v_mfma_f32_16x16x32_bf16 v[112:115], v[152:155], v[160:163], v[112:115]
	v_mfma_f32_16x16x32_bf16 v[112:115], v[156:159], v[164:167], v[112:115]
	v_mfma_f32_16x16x32_bf16 v[96:99], v[152:155], v[188:191], v[96:99]
	v_mfma_f32_16x16x32_bf16 v[96:99], v[156:159], v[192:195], v[96:99]
	v_mfma_f32_16x16x32_bf16 v[80:83], v[152:155], v[196:199], v[80:83]
	v_mfma_f32_16x16x32_bf16 v[80:83], v[156:159], v[202:205], v[80:83]
	v_mfma_f32_16x16x32_bf16 v[64:67], v[152:155], v[206:209], v[64:67]
	v_mfma_f32_16x16x32_bf16 v[64:67], v[156:159], v[220:223], v[64:67]
	s_barrier
	s_setprio 0
	s_add_u32 s98, s14, 0x80
	s_addc_u32 s99, s15, 0
	s_add_u32 s100, s26, 0x80
	s_addc_u32 s101, s27, 0
	s_add_i32 s66, s50, s34
	s_mov_b32 m0, s66
	ds_read_b128 v[160:163], v217 offset:16384
	ds_read_b128 v[164:167], v217 offset:17408
	ds_read_b128 v[188:191], v217 offset:18432
	ds_read_b128 v[192:195], v217 offset:19456
	ds_read_b128 v[196:199], v217 offset:20480
	ds_read_b128 v[202:205], v217 offset:21504
	ds_read_b128 v[206:209], v217 offset:22528
	ds_read_b128 v[220:223], v217 offset:23552
	global_load_lds_dwordx4 v170, s[14:15]
	s_add_i32 m0, s66, 0x2000
	s_add_u32 s66, s14, 0x80000
	s_addc_u32 s67, s15, 0
	s_add_i32 s68, s51, s34
	global_load_lds_dwordx4 v174, s[14:15]
	s_mov_b32 m0, s68
	s_nop 0
	global_load_lds_dwordx4 v170, s[66:67]
	s_add_i32 m0, s68, 0x2000
	s_nop 0
	global_load_lds_dwordx4 v174, s[66:67]
	s_mov_b32 m0, s39
	s_nop 0
	global_load_lds_dwordx4 v168, s[26:27]
	s_mov_b32 m0, s42
	s_nop 0
	global_load_lds_dwordx4 v172, s[26:27]
	s_waitcnt vmcnt(8)
	s_waitcnt lgkmcnt(0)
	s_setprio 1
	s_barrier
	v_mfma_f32_16x16x32_bf16 v[60:63], v[128:131], v[160:163], v[60:63]
	v_mfma_f32_16x16x32_bf16 v[60:63], v[132:135], v[164:167], v[60:63]
	v_mfma_f32_16x16x32_bf16 v[44:47], v[128:131], v[188:191], v[44:47]
	v_mfma_f32_16x16x32_bf16 v[44:47], v[132:135], v[192:195], v[44:47]
	v_mfma_f32_16x16x32_bf16 v[28:31], v[128:131], v[196:199], v[28:31]
	v_mfma_f32_16x16x32_bf16 v[28:31], v[132:135], v[202:205], v[28:31]
	v_mfma_f32_16x16x32_bf16 v[12:15], v[128:131], v[206:209], v[12:15]
	v_mfma_f32_16x16x32_bf16 v[12:15], v[132:135], v[220:223], v[12:15]
	v_mfma_f32_16x16x32_bf16 v[56:59], v[136:139], v[160:163], v[56:59]
	v_mfma_f32_16x16x32_bf16 v[56:59], v[140:143], v[164:167], v[56:59]
	v_mfma_f32_16x16x32_bf16 v[40:43], v[136:139], v[188:191], v[40:43]
	v_mfma_f32_16x16x32_bf16 v[40:43], v[140:143], v[192:195], v[40:43]
	v_mfma_f32_16x16x32_bf16 v[24:27], v[136:139], v[196:199], v[24:27]
	v_mfma_f32_16x16x32_bf16 v[24:27], v[140:143], v[202:205], v[24:27]
	v_mfma_f32_16x16x32_bf16 v[8:11], v[136:139], v[206:209], v[8:11]
	v_mfma_f32_16x16x32_bf16 v[8:11], v[140:143], v[220:223], v[8:11]
	s_setprio 0
	s_setprio 1
	v_mfma_f32_16x16x32_bf16 v[52:55], v[144:147], v[160:163], v[52:55]
	v_mfma_f32_16x16x32_bf16 v[52:55], v[148:151], v[164:167], v[52:55]
	v_mfma_f32_16x16x32_bf16 v[36:39], v[144:147], v[188:191], v[36:39]
	v_mfma_f32_16x16x32_bf16 v[36:39], v[148:151], v[192:195], v[36:39]
	v_mfma_f32_16x16x32_bf16 v[20:23], v[144:147], v[196:199], v[20:23]
	v_mfma_f32_16x16x32_bf16 v[20:23], v[148:151], v[202:205], v[20:23]
	v_mfma_f32_16x16x32_bf16 v[4:7], v[144:147], v[206:209], v[4:7]
	v_mfma_f32_16x16x32_bf16 v[4:7], v[148:151], v[220:223], v[4:7]
	v_mfma_f32_16x16x32_bf16 v[48:51], v[152:155], v[160:163], v[48:51]
	v_mfma_f32_16x16x32_bf16 v[48:51], v[156:159], v[164:167], v[48:51]
	v_mfma_f32_16x16x32_bf16 v[32:35], v[152:155], v[188:191], v[32:35]
	v_mfma_f32_16x16x32_bf16 v[32:35], v[156:159], v[192:195], v[32:35]
	v_mfma_f32_16x16x32_bf16 v[16:19], v[152:155], v[196:199], v[16:19]
	v_mfma_f32_16x16x32_bf16 v[16:19], v[156:159], v[202:205], v[16:19]
	v_mfma_f32_16x16x32_bf16 v[0:3], v[152:155], v[206:209], v[0:3]
	v_mfma_f32_16x16x32_bf16 v[0:3], v[156:159], v[220:223], v[0:3]
	s_barrier
; #define PG8_STAGE(bufoff, gbase, voff) do { _Pragma("unroll") for (int _i = 0; _i < 2; ++_i) \
;         __builtin_amdgcn_global_load_lds((const unsigned*)((const char*)(gbase) + (voff)[_i]), (PG8_LAS unsigned*)(lds + (bufoff) + ldsw + _i * 8192), 16, 0, 0); } while (0)
; #define PG8_LDA(dst, b, h) do { _Pragma("unroll") for (int m = 0; m < 4; ++m) _Pragma("unroll") for (int k = 0; k < 2; ++k) dst[m][k] = *(const PG8_LAS bf16x8*)(lds + PG8_SA(b, h) + aoff + m * 2048 + k * 1024); } while (0)
; #define PG8_LDB(dst, b, h) do { _Pragma("unroll") for (int n = 0; n < 2; ++n) _Pragma("unroll") for (int k = 0; k < 2; ++k) dst[n][k] = *(const PG8_LAS bf16x8*)(lds + PG8_SB(b, h) + boff + n * 2048 + k * 1024); } while (0)
; #define PG8_MMA(ai, bj, At, Bt) do { __builtin_amdgcn_s_setprio(1); _Pragma("unroll") for (int m = 0; m < 4; ++m) _Pragma("unroll") for (int n = 0; n < 2; ++n) _Pragma("unroll") for (int k = 0; k < 2; ++k) \
;         acc[ai][bj][m][n] = __builtin_amdgcn_mfma_f32_16x16x32_bf16(Bt[n][k], At[m][k], acc[ai][bj][m][n], 0, 0, 0); __builtin_amdgcn_s_setprio(0); } while (0)
; #define PG8_WAIT_V(n) asm volatile("s_waitcnt vmcnt(" #n ")" ::: "memory")
; #define PG8_WAIT_L(n) asm volatile("s_waitcnt lgkmcnt(" #n ")" ::: "memory")
; #define PG8_BAR __builtin_amdgcn_s_barrier()
; #define PG8_SCHED __builtin_amdgcn_sched_barrier(0)
; template <class Epi, class Sched, bool ALIGN_EPI = false, bool SP2 = false, bool DUAL = false>
; __device__ __forceinline__ void gemm_phase(PG8_LAS unsigned char* lds, const Gemm g, const Sched& S, const Epi& E) {
;     ...
;             PG8_LDB(B0, 1, 0); PG8_LDB(B1, 1, 1); PG8_SCHED; PG8_LDA(At, 1, 0); PG8_STAGE(PG8_SA(0, 1), a2 + hstep, voffA);
;             PG8_WAIT_V(8); PG8_WAIT_L(0); PG8_BAR; PG8_MMA(0, 0, At, B0); PG8_MMA(0, 1, At, B1); PG8_BAR; PG8_SCHED;
;             PG8_LDA(At, 1, 1); PG8_STAGE(PG8_SB(1, 0), b3, voffB); PG8_STAGE(PG8_SB(1, 1), b3 + hstep, voffB); PG8_STAGE(PG8_SA(1, 0), a3, voffA);
	s_setprio 0
	s_add_i32 s66, 0, 0x18000
	s_add_i32 s67, 0, 0x1c000
	ds_read_b128 v[128:131], v215 offset:32768
	ds_read_b128 v[132:135], v215 offset:33792
	ds_read_b128 v[136:139], v215 offset:34816
	ds_read_b128 v[140:143], v215 offset:35840
	ds_read_b128 v[144:147], v216 offset:32768
	ds_read_b128 v[148:151], v216 offset:33792
	ds_read_b128 v[152:155], v216 offset:34816
	ds_read_b128 v[156:159], v216 offset:35840
	s_add_u32 s26, s26, 0x80000
	s_addc_u32 s27, s27, 0
	s_mov_b32 m0, s43
	ds_read_b128 v[160:163], v217 offset:32768
	ds_read_b128 v[164:167], v217 offset:33792
	ds_read_b128 v[188:191], v217 offset:34816
	ds_read_b128 v[192:195], v217 offset:35840
	ds_read_b128 v[196:199], v217 offset:36864
	ds_read_b128 v[202:205], v217 offset:37888
	ds_read_b128 v[206:209], v217 offset:38912
	ds_read_b128 v[220:223], v217 offset:39936
	global_load_lds_dwordx4 v168, s[26:27]
	s_mov_b32 m0, s44
	s_nop 0
	global_load_lds_dwordx4 v172, s[26:27]
	s_waitcnt vmcnt(8)
	s_waitcnt lgkmcnt(0)
	s_setprio 1
	s_barrier
	v_mfma_f32_16x16x32_bf16 v[124:127], v[128:131], v[160:163], v[124:127]
	v_mfma_f32_16x16x32_bf16 v[124:127], v[132:135], v[164:167], v[124:127]
	v_mfma_f32_16x16x32_bf16 v[108:111], v[128:131], v[188:191], v[108:111]
	v_mfma_f32_16x16x32_bf16 v[108:111], v[132:135], v[192:195], v[108:111]
	v_mfma_f32_16x16x32_bf16 v[92:95], v[128:131], v[196:199], v[92:95]
	v_mfma_f32_16x16x32_bf16 v[92:95], v[132:135], v[202:205], v[92:95]
	v_mfma_f32_16x16x32_bf16 v[76:79], v[128:131], v[206:209], v[76:79]
	v_mfma_f32_16x16x32_bf16 v[76:79], v[132:135], v[220:223], v[76:79]
	v_mfma_f32_16x16x32_bf16 v[120:123], v[136:139], v[160:163], v[120:123]
	v_mfma_f32_16x16x32_bf16 v[120:123], v[140:143], v[164:167], v[120:123]
	v_mfma_f32_16x16x32_bf16 v[104:107], v[136:139], v[188:191], v[104:107]
	v_mfma_f32_16x16x32_bf16 v[104:107], v[140:143], v[192:195], v[104:107]
	v_mfma_f32_16x16x32_bf16 v[88:91], v[136:139], v[196:199], v[88:91]
	v_mfma_f32_16x16x32_bf16 v[88:91], v[140:143], v[202:205], v[88:91]
	v_mfma_f32_16x16x32_bf16 v[72:75], v[136:139], v[206:209], v[72:75]
	v_mfma_f32_16x16x32_bf16 v[72:75], v[140:143], v[220:223], v[72:75]
	s_setprio 0
	s_setprio 1
	v_mfma_f32_16x16x32_bf16 v[116:119], v[144:147], v[160:163], v[116:119]
	v_mfma_f32_16x16x32_bf16 v[116:119], v[148:151], v[164:167], v[116:119]
	v_mfma_f32_16x16x32_bf16 v[100:103], v[144:147], v[188:191], v[100:103]
	v_mfma_f32_16x16x32_bf16 v[100:103], v[148:151], v[192:195], v[100:103]
	v_mfma_f32_16x16x32_bf16 v[84:87], v[144:147], v[196:199], v[84:87]
	v_mfma_f32_16x16x32_bf16 v[84:87], v[148:151], v[202:205], v[84:87]
	v_mfma_f32_16x16x32_bf16 v[68:71], v[144:147], v[206:209], v[68:71]
	v_mfma_f32_16x16x32_bf16 v[68:71], v[148:151], v[220:223], v[68:71]
	v_mfma_f32_16x16x32_bf16 v[112:115], v[152:155], v[160:163], v[112:115]
	v_mfma_f32_16x16x32_bf16 v[112:115], v[156:159], v[164:167], v[112:115]
	v_mfma_f32_16x16x32_bf16 v[96:99], v[152:155], v[188:191], v[96:99]
	v_mfma_f32_16x16x32_bf16 v[96:99], v[156:159], v[192:195], v[96:99]
	v_mfma_f32_16x16x32_bf16 v[80:83], v[152:155], v[196:199], v[80:83]
	v_mfma_f32_16x16x32_bf16 v[80:83], v[156:159], v[202:205], v[80:83]
	v_mfma_f32_16x16x32_bf16 v[64:67], v[152:155], v[206:209], v[64:67]
	v_mfma_f32_16x16x32_bf16 v[64:67], v[156:159], v[220:223], v[64:67]
	s_barrier
	s_setprio 0
	s_add_i32 s26, s66, s34
	s_mov_b32 m0, s26
	ds_read_b128 v[160:163], v217 offset:49152
	ds_read_b128 v[164:167], v217 offset:50176
	ds_read_b128 v[188:191], v217 offset:51200
	ds_read_b128 v[192:195], v217 offset:52224
	ds_read_b128 v[196:199], v217 offset:53248
	ds_read_b128 v[202:205], v217 offset:54272
	ds_read_b128 v[206:209], v217 offset:55296
	ds_read_b128 v[220:223], v217 offset:56320
	global_load_lds_dwordx4 v170, s[98:99]
	s_add_i32 m0, s26, 0x2000
	s_add_u32 s14, s14, 0x80080
	s_addc_u32 s15, s15, 0
	s_add_i32 s26, s67, s34
	global_load_lds_dwordx4 v174, s[98:99]
	s_mov_b32 m0, s26
	s_nop 0
	global_load_lds_dwordx4 v170, s[14:15]
	s_add_i32 m0, s26, 0x2000
	s_nop 0
	global_load_lds_dwordx4 v174, s[14:15]
	s_mov_b32 m0, s47
	s_nop 0
	global_load_lds_dwordx4 v168, s[100:101]
	s_mov_b32 m0, s48
	s_nop 0
	global_load_lds_dwordx4 v172, s[100:101]
	s_waitcnt vmcnt(8)
	s_waitcnt lgkmcnt(0)
	s_setprio 1
	s_barrier
; #define PG8_WAIT_V(n) asm volatile("s_waitcnt vmcnt(" #n ")" ::: "memory")
; #define PG8_WAIT_L(n) asm volatile("s_waitcnt lgkmcnt(" #n ")" ::: "memory")
; template <class Epi, class Sched, bool ALIGN_EPI = false, bool SP2 = false, bool DUAL = false>
; __device__ __forceinline__ void gemm_phase(PG8_LAS unsigned char* lds, const Gemm g, const Sched& S, const Epi& E) {
;     ...
;             PG8_WAIT_V(8); PG8_WAIT_L(0); PG8_BAR; PG8_MMA(1, 0, At, B0); PG8_MMA(1, 1, At, B1); PG8_BAR; PG8_SCHED;
;             } else {
;             PG8_LDB(B0, 0, 0); PG8_SCHED; PG8_LDA(At, 0, 0); PG8_STAGE(PG8_SA(1, 1), a1 + hstep, voffA);
;             PG8_WAIT_L(8); PG8_BAR; PG8_WAIT_L(0); PG8_MMA(0, 0, At, B0); PG8_BAR; PG8_SCHED;
;             PG8_LDB(B1, 0, 1); PG8_STAGE(PG8_SB(0, 0), b2, voffB);
;             PG8_BAR; PG8_WAIT_L(0); PG8_MMA(0, 1, At, B1); PG8_BAR;
;             PG8_LDA(At, 0, 1); PG8_STAGE(PG8_SA(0, 0), a2, voffA);
;             PG8_BAR; PG8_WAIT_L(0); PG8_MMA(1, 0, At, B0); PG8_BAR; PG8_SCHED;
;             PG8_STAGE(PG8_SB(0, 1), b2 + hstep, voffB);
;             PG8_WAIT_V(6); PG8_BAR; PG8_MMA(1, 1, At, B1); PG8_BAR;
;             PG8_LDB(B0, 1, 0); PG8_SCHED; PG8_LDA(At, 1, 0); PG8_STAGE(PG8_SA(0, 1), a2 + hstep, voffA);
;             PG8_WAIT_L(8); PG8_BAR; PG8_WAIT_L(0); PG8_MMA(0, 0, At, B0); PG8_BAR; PG8_SCHED;
;             PG8_LDB(B1, 1, 1); PG8_STAGE(PG8_SB(1, 0), b3, voffB);
;             PG8_BAR; PG8_WAIT_L(0); PG8_MMA(0, 1, At, B1); PG8_BAR;
;             PG8_LDA(At, 1, 1); PG8_STAGE(PG8_SA(1, 0), a3, voffA);
;             PG8_BAR; PG8_WAIT_L(0); PG8_MMA(1, 0, At, B0); PG8_BAR; PG8_SCHED;
;             PG8_STAGE(PG8_SB(1, 1), b3 + hstep, voffB);
;             PG8_WAIT_V(6); PG8_BAR; PG8_MMA(1, 1, At, B1); PG8_BAR;
;             }
;         }
;         if constexpr (ALIGN_EPI) { if (wr == 0) PG8_BAR; }
;     __device__ __forceinline__ void operator()(const f32x4 (&acc)[2][2][4][2], const Unit& u, int wr, int wc, int fr, int fq) const {
;         const int rowb = u.pm * BM + wr * 64 + fr, col = u.pn * HALF + wc * 32 + fq * 8;
;         f32x4 p[2][4][2];
; #pragma unroll
;         for (int ai = 0; ai < 2; ++ai)
; #pragma unroll
;             for (int m = 0; m < 4; ++m) { const float* sp = ss2 + (size_t)(rowb + ai * HALF + m * 16) * 32 + fq * 8; p[ai][m][0] = *(const f32x4*)sp; p[ai][m][1] = *(const f32x4*)(sp + 4); }
	v_mfma_f32_16x16x32_bf16 v[60:63], v[128:131], v[160:163], v[60:63]
	v_mfma_f32_16x16x32_bf16 v[60:63], v[132:135], v[164:167], v[60:63]
	v_mfma_f32_16x16x32_bf16 v[44:47], v[128:131], v[188:191], v[44:47]
	v_mfma_f32_16x16x32_bf16 v[44:47], v[132:135], v[192:195], v[44:47]
	v_mfma_f32_16x16x32_bf16 v[28:31], v[128:131], v[196:199], v[28:31]
	v_mfma_f32_16x16x32_bf16 v[28:31], v[132:135], v[202:205], v[28:31]
	v_mfma_f32_16x16x32_bf16 v[12:15], v[128:131], v[206:209], v[12:15]
	v_mfma_f32_16x16x32_bf16 v[12:15], v[132:135], v[220:223], v[12:15]
	v_mfma_f32_16x16x32_bf16 v[56:59], v[136:139], v[160:163], v[56:59]
	v_mfma_f32_16x16x32_bf16 v[56:59], v[140:143], v[164:167], v[56:59]
	v_mfma_f32_16x16x32_bf16 v[40:43], v[136:139], v[188:191], v[40:43]
	v_mfma_f32_16x16x32_bf16 v[40:43], v[140:143], v[192:195], v[40:43]
	v_mfma_f32_16x16x32_bf16 v[24:27], v[136:139], v[196:199], v[24:27]
	v_mfma_f32_16x16x32_bf16 v[24:27], v[140:143], v[202:205], v[24:27]
	v_mfma_f32_16x16x32_bf16 v[8:11], v[136:139], v[206:209], v[8:11]
	v_mfma_f32_16x16x32_bf16 v[8:11], v[140:143], v[220:223], v[8:11]
	s_setprio 0
	s_setprio 1
	v_mfma_f32_16x16x32_bf16 v[52:55], v[144:147], v[160:163], v[52:55]
	v_mfma_f32_16x16x32_bf16 v[52:55], v[148:151], v[164:167], v[52:55]
	v_mfma_f32_16x16x32_bf16 v[36:39], v[144:147], v[188:191], v[36:39]
	v_mfma_f32_16x16x32_bf16 v[36:39], v[148:151], v[192:195], v[36:39]
	v_mfma_f32_16x16x32_bf16 v[20:23], v[144:147], v[196:199], v[20:23]
	v_mfma_f32_16x16x32_bf16 v[20:23], v[148:151], v[202:205], v[20:23]
	v_mfma_f32_16x16x32_bf16 v[4:7], v[144:147], v[206:209], v[4:7]
	v_mfma_f32_16x16x32_bf16 v[4:7], v[148:151], v[220:223], v[4:7]
	v_mfma_f32_16x16x32_bf16 v[48:51], v[152:155], v[160:163], v[48:51]
	v_mfma_f32_16x16x32_bf16 v[48:51], v[156:159], v[164:167], v[48:51]
	v_mfma_f32_16x16x32_bf16 v[32:35], v[152:155], v[188:191], v[32:35]
	v_mfma_f32_16x16x32_bf16 v[32:35], v[156:159], v[192:195], v[32:35]
	v_mfma_f32_16x16x32_bf16 v[16:19], v[152:155], v[196:199], v[16:19]
	v_mfma_f32_16x16x32_bf16 v[16:19], v[156:159], v[202:205], v[16:19]
	v_mfma_f32_16x16x32_bf16 v[0:3], v[152:155], v[206:209], v[0:3]
	v_mfma_f32_16x16x32_bf16 v[0:3], v[156:159], v[220:223], v[0:3]
	s_barrier
	s_setprio 0
	s_add_i32 s65, s65, 2
	s_add_u32 s40, s40, 0x100
	s_addc_u32 s41, s41, 0
	s_add_u32 s63, s63, 0x100
	s_addc_u32 s64, s64, 0
	s_cmp_gt_u32 s65, 29
	s_cbranch_scc0 .LBB0_992
	v_lshl_add_u32 v144, s38, 8, v212
	v_ashrrev_i32_e32 v145, 31, v144
	v_or_b32_e32 v206, 16, v144
	v_lshlrev_b64 v[128:129], 7, v[144:145]
	v_ashrrev_i32_e32 v207, 31, v206
	v_lshl_add_u64 v[132:133], v[178:179], 0, v[128:129]
	v_lshlrev_b64 v[136:137], 7, v[206:207]
	global_load_dwordx4 v[128:131], v[132:133], off
	s_nop 0
	global_load_dwordx4 v[132:135], v[132:133], off offset:16
	v_lshl_add_u64 v[140:141], v[178:179], 0, v[136:137]
	global_load_dwordx4 v[136:139], v[140:141], off
	s_nop 0
	global_load_dwordx4 v[140:143], v[140:141], off offset:16
	v_readlane_b32 s64, v254, 20
	v_readlane_b32 s70, v254, 26
	v_readlane_b32 s71, v254, 27
	v_readlane_b32 s72, v254, 28
	v_readlane_b32 s73, v254, 29
	v_readlane_b32 s74, v254, 30
	v_readlane_b32 s75, v254, 31
	v_readlane_b32 s76, v254, 32
	v_readlane_b32 s77, v254, 33
	s_and_b64 vcc, exec, s[16:17]
	s_mov_b64 s[70:71], s[74:75]
	s_mov_b64 s[72:73], s[76:77]
	v_readlane_b32 s65, v254, 21
	v_readlane_b32 s66, v254, 22
	v_readlane_b32 s67, v254, 23
	v_readlane_b32 s68, v254, 24
	v_readlane_b32 s69, v254, 25
	v_readlane_b32 s78, v254, 34
	v_readlane_b32 s79, v254, 35
	s_cbranch_vccz .LBB0_995
	s_barrier

; #define PG8_STAGE(bufoff, gbase, voff) do { _Pragma("unroll") for (int _i = 0; _i < 2; ++_i) \
;         __builtin_amdgcn_global_load_lds((const unsigned*)((const char*)(gbase) + (voff)[_i]), (PG8_LAS unsigned*)(lds + (bufoff) + ldsw + _i * 8192), 16, 0, 0); } while (0)
; #define PG8_LDA(dst, b, h) do { _Pragma("unroll") for (int m = 0; m < 4; ++m) _Pragma("unroll") for (int k = 0; k < 2; ++k) dst[m][k] = *(const PG8_LAS bf16x8*)(lds + PG8_SA(b, h) + aoff + m * 2048 + k * 1024); } while (0)
; #define PG8_LDB(dst, b, h) do { _Pragma("unroll") for (int n = 0; n < 2; ++n) _Pragma("unroll") for (int k = 0; k < 2; ++k) dst[n][k] = *(const PG8_LAS bf16x8*)(lds + PG8_SB(b, h) + boff + n * 2048 + k * 1024); } while (0)
; #define PG8_MMA(ai, bj, At, Bt) do { __builtin_amdgcn_s_setprio(1); _Pragma("unroll") for (int m = 0; m < 4; ++m) _Pragma("unroll") for (int n = 0; n < 2; ++n) _Pragma("unroll") for (int k = 0; k < 2; ++k) \
;         acc[ai][bj][m][n] = __builtin_amdgcn_mfma_f32_16x16x32_bf16(Bt[n][k], At[m][k], acc[ai][bj][m][n], 0, 0, 0); __builtin_amdgcn_s_setprio(0); } while (0)
; #define PG8_WAIT_V(n) asm volatile("s_waitcnt vmcnt(" #n ")" ::: "memory")
; #define PG8_BAR __builtin_amdgcn_s_barrier()
; template <class Epi, class Sched, bool ALIGN_EPI = false, bool SP2 = false, bool DUAL = false>
; __device__ __forceinline__ void gemm_phase(PG8_LAS unsigned char* lds, const Gemm g, const Sched& S, const Epi& E) {
;     ...
;         for (int t = 0; t < nt; t += 2) {
;             const bool last = (t == nt - 2);
;             const char* a1 = cA + (size_t)(t + 1) * kstep;
;             const char* a2 = last ? nA : cA + (size_t)(t + 2) * kstep; const char* b2 = last ? nB : cB + (size_t)(t + 2) * kstep;
;             const char* a3 = a2 + kstep; const char* b3 = b2 + kstep;
;             if (last && has_next) S.a_ready(nxt);
;             if constexpr (SP2) {
;             PG8_LDB(B0, 0, 0); PG8_LDB(B1, 0, 1); PG8_SCHED; PG8_LDA(At, 0, 0); PG8_STAGE(PG8_SA(1, 1), a1 + hstep, voffA);
;             PG8_WAIT_V(8); PG8_WAIT_L(0); PG8_BAR; PG8_MMA(0, 0, At, B0); PG8_MMA(0, 1, At, B1); PG8_BAR; PG8_SCHED;
;             PG8_LDA(At, 0, 1); PG8_STAGE(PG8_SB(0, 0), b2, voffB); PG8_STAGE(PG8_SB(0, 1), b2 + hstep, voffB); PG8_STAGE(PG8_SA(0, 0), a2, voffA);
;             PG8_WAIT_V(8); PG8_WAIT_L(0); PG8_BAR; PG8_MMA(1, 0, At, B0); PG8_MMA(1, 1, At, B1); PG8_BAR; PG8_SCHED;
.LBB0_1192:
	s_add_u32 s24, s24, 0x160080
	s_addc_u32 s25, s25, 0
	s_add_u32 s46, s14, 0x100
	s_addc_u32 s47, s15, 0
	s_mov_b32 s48, -2
	s_add_u32 s14, s24, 0xffea0080
	s_addc_u32 s15, s25, -1
	s_cmpk_eq_i32 s48, 0x54
	s_cselect_b32 s27, s5, s15
	s_cselect_b32 s26, s4, s14
	s_cselect_b32 s15, s23, s47
	s_cselect_b32 s14, s22, s46
	s_waitcnt vmcnt(8)
	s_waitcnt lgkmcnt(0)
	s_setprio 1
	s_barrier
	v_mfma_f32_16x16x32_bf16 v[124:127], v[128:131], v[160:163], 0
	v_mfma_f32_16x16x32_bf16 v[124:127], v[132:135], v[182:185], v[124:127]
	v_mfma_f32_16x16x32_bf16 v[112:115], v[128:131], v[186:189], 0
	v_mfma_f32_16x16x32_bf16 v[112:115], v[132:135], v[190:193], v[112:115]
	v_mfma_f32_16x16x32_bf16 v[96:99], v[128:131], v[204:207], 0
	v_mfma_f32_16x16x32_bf16 v[96:99], v[132:135], v[208:211], v[96:99]
	v_mfma_f32_16x16x32_bf16 v[80:83], v[128:131], v[212:215], 0
	v_mfma_f32_16x16x32_bf16 v[80:83], v[132:135], v[216:219], v[80:83]
	v_mfma_f32_16x16x32_bf16 v[120:123], v[136:139], v[160:163], 0
	v_mfma_f32_16x16x32_bf16 v[120:123], v[140:143], v[182:185], v[120:123]
	v_mfma_f32_16x16x32_bf16 v[104:107], v[136:139], v[186:189], 0
	v_mfma_f32_16x16x32_bf16 v[104:107], v[140:143], v[190:193], v[104:107]
	v_mfma_f32_16x16x32_bf16 v[88:91], v[136:139], v[204:207], 0
	v_mfma_f32_16x16x32_bf16 v[88:91], v[140:143], v[208:211], v[88:91]
	v_mfma_f32_16x16x32_bf16 v[72:75], v[136:139], v[212:215], 0
	v_mfma_f32_16x16x32_bf16 v[72:75], v[140:143], v[216:219], v[72:75]
	s_setprio 0
	s_setprio 1
	v_mfma_f32_16x16x32_bf16 v[116:119], v[144:147], v[160:163], 0
	v_mfma_f32_16x16x32_bf16 v[116:119], v[148:151], v[182:185], v[116:119]
	v_mfma_f32_16x16x32_bf16 v[100:103], v[144:147], v[186:189], 0
	v_mfma_f32_16x16x32_bf16 v[100:103], v[148:151], v[190:193], v[100:103]
	v_mfma_f32_16x16x32_bf16 v[84:87], v[144:147], v[204:207], 0
	v_mfma_f32_16x16x32_bf16 v[84:87], v[148:151], v[208:211], v[84:87]
	v_mfma_f32_16x16x32_bf16 v[68:71], v[144:147], v[212:215], 0
	v_mfma_f32_16x16x32_bf16 v[68:71], v[148:151], v[216:219], v[68:71]
	v_mfma_f32_16x16x32_bf16 v[108:111], v[152:155], v[160:163], 0
	v_mfma_f32_16x16x32_bf16 v[108:111], v[156:159], v[182:185], v[108:111]
	v_mfma_f32_16x16x32_bf16 v[92:95], v[152:155], v[186:189], 0
	v_mfma_f32_16x16x32_bf16 v[92:95], v[156:159], v[190:193], v[92:95]
	v_mfma_f32_16x16x32_bf16 v[76:79], v[152:155], v[204:207], 0
	v_mfma_f32_16x16x32_bf16 v[76:79], v[156:159], v[208:211], v[76:79]
	v_mfma_f32_16x16x32_bf16 v[64:67], v[152:155], v[212:215], 0
	v_mfma_f32_16x16x32_bf16 v[64:67], v[156:159], v[216:219], v[64:67]
	s_barrier
	s_setprio 0
	s_add_u32 s98, s14, 0x80
	s_addc_u32 s99, s15, 0
	s_add_u32 s100, s26, 0x80
	s_addc_u32 s101, s27, 0
	s_add_i32 m0, s31, 0xc000
	s_nop 0
	global_load_lds_dwordx4 v172, s[24:25]
	s_add_i32 m0, s31, 0xe000
	s_nop 0
	global_load_lds_dwordx4 v174, s[24:25]
	s_add_i32 s49, s40, s30
	s_mov_b32 m0, s49
	ds_read_b128 v[160:163], v203 offset:16384
	ds_read_b128 v[182:185], v203 offset:17408
	ds_read_b128 v[186:189], v203 offset:18432
	ds_read_b128 v[190:193], v203 offset:19456
	ds_read_b128 v[204:207], v203 offset:20480
	ds_read_b128 v[208:211], v203 offset:21504
	ds_read_b128 v[212:215], v203 offset:22528
	ds_read_b128 v[216:219], v203 offset:23552
	global_load_lds_dwordx4 v166, s[14:15]
	s_add_i32 m0, s49, 0x2000
	s_add_u32 s50, s14, 0x160000
	s_addc_u32 s51, s15, 0
	s_add_i32 s49, s41, s30
	global_load_lds_dwordx4 v170, s[14:15]
	s_mov_b32 m0, s49
	s_nop 0
	global_load_lds_dwordx4 v166, s[50:51]
	s_add_i32 m0, s49, 0x2000
	s_nop 0
	global_load_lds_dwordx4 v170, s[50:51]
	s_mov_b32 m0, s31
	s_nop 0
	global_load_lds_dwordx4 v164, s[26:27]
	s_mov_b32 m0, s33
	s_nop 0
	global_load_lds_dwordx4 v168, s[26:27]
	s_waitcnt vmcnt(8)
	s_waitcnt lgkmcnt(0)
	s_setprio 1
	s_barrier
	v_mfma_f32_16x16x32_bf16 v[60:63], v[128:131], v[160:163], 0
	v_mfma_f32_16x16x32_bf16 v[60:63], v[132:135], v[182:185], v[60:63]
	v_mfma_f32_16x16x32_bf16 v[48:51], v[128:131], v[186:189], 0
	v_mfma_f32_16x16x32_bf16 v[48:51], v[132:135], v[190:193], v[48:51]
	v_mfma_f32_16x16x32_bf16 v[32:35], v[128:131], v[204:207], 0
	v_mfma_f32_16x16x32_bf16 v[32:35], v[132:135], v[208:211], v[32:35]
	v_mfma_f32_16x16x32_bf16 v[16:19], v[128:131], v[212:215], 0
	v_mfma_f32_16x16x32_bf16 v[16:19], v[132:135], v[216:219], v[16:19]
	v_mfma_f32_16x16x32_bf16 v[56:59], v[136:139], v[160:163], 0
	v_mfma_f32_16x16x32_bf16 v[56:59], v[140:143], v[182:185], v[56:59]
	v_mfma_f32_16x16x32_bf16 v[40:43], v[136:139], v[186:189], 0
	v_mfma_f32_16x16x32_bf16 v[40:43], v[140:143], v[190:193], v[40:43]
	v_mfma_f32_16x16x32_bf16 v[24:27], v[136:139], v[204:207], 0
	v_mfma_f32_16x16x32_bf16 v[24:27], v[140:143], v[208:211], v[24:27]
	v_mfma_f32_16x16x32_bf16 v[8:11], v[136:139], v[212:215], 0
	v_mfma_f32_16x16x32_bf16 v[8:11], v[140:143], v[216:219], v[8:11]
	s_setprio 0
	s_setprio 1
	v_mfma_f32_16x16x32_bf16 v[52:55], v[144:147], v[160:163], 0
	v_mfma_f32_16x16x32_bf16 v[52:55], v[148:151], v[182:185], v[52:55]
	v_mfma_f32_16x16x32_bf16 v[36:39], v[144:147], v[186:189], 0
	v_mfma_f32_16x16x32_bf16 v[36:39], v[148:151], v[190:193], v[36:39]
	v_mfma_f32_16x16x32_bf16 v[20:23], v[144:147], v[204:207], 0
	v_mfma_f32_16x16x32_bf16 v[20:23], v[148:151], v[208:211], v[20:23]
	v_mfma_f32_16x16x32_bf16 v[4:7], v[144:147], v[212:215], 0
	v_mfma_f32_16x16x32_bf16 v[4:7], v[148:151], v[216:219], v[4:7]
	v_mfma_f32_16x16x32_bf16 v[44:47], v[152:155], v[160:163], 0
	v_mfma_f32_16x16x32_bf16 v[44:47], v[156:159], v[182:185], v[44:47]
	v_mfma_f32_16x16x32_bf16 v[28:31], v[152:155], v[186:189], 0
	v_mfma_f32_16x16x32_bf16 v[28:31], v[156:159], v[190:193], v[28:31]
	v_mfma_f32_16x16x32_bf16 v[12:15], v[152:155], v[204:207], 0
	v_mfma_f32_16x16x32_bf16 v[12:15], v[156:159], v[208:211], v[12:15]
	v_mfma_f32_16x16x32_bf16 v[0:3], v[152:155], v[212:215], 0
	v_mfma_f32_16x16x32_bf16 v[0:3], v[156:159], v[216:219], v[0:3]
	s_barrier
; #define PG8_STAGE(bufoff, gbase, voff) do { _Pragma("unroll") for (int _i = 0; _i < 2; ++_i) \
;         __builtin_amdgcn_global_load_lds((const unsigned*)((const char*)(gbase) + (voff)[_i]), (PG8_LAS unsigned*)(lds + (bufoff) + ldsw + _i * 8192), 16, 0, 0); } while (0)
; #define PG8_LDA(dst, b, h) do { _Pragma("unroll") for (int m = 0; m < 4; ++m) _Pragma("unroll") for (int k = 0; k < 2; ++k) dst[m][k] = *(const PG8_LAS bf16x8*)(lds + PG8_SA(b, h) + aoff + m * 2048 + k * 1024); } while (0)
; #define PG8_LDB(dst, b, h) do { _Pragma("unroll") for (int n = 0; n < 2; ++n) _Pragma("unroll") for (int k = 0; k < 2; ++k) dst[n][k] = *(const PG8_LAS bf16x8*)(lds + PG8_SB(b, h) + boff + n * 2048 + k * 1024); } while (0)
; #define PG8_MMA(ai, bj, At, Bt) do { __builtin_amdgcn_s_setprio(1); _Pragma("unroll") for (int m = 0; m < 4; ++m) _Pragma("unroll") for (int n = 0; n < 2; ++n) _Pragma("unroll") for (int k = 0; k < 2; ++k) \
;         acc[ai][bj][m][n] = __builtin_amdgcn_mfma_f32_16x16x32_bf16(Bt[n][k], At[m][k], acc[ai][bj][m][n], 0, 0, 0); __builtin_amdgcn_s_setprio(0); } while (0)
; #define PG8_WAIT_V(n) asm volatile("s_waitcnt vmcnt(" #n ")" ::: "memory")
; #define PG8_WAIT_L(n) asm volatile("s_waitcnt lgkmcnt(" #n ")" ::: "memory")
; #define PG8_BAR __builtin_amdgcn_s_barrier()
; #define PG8_SCHED __builtin_amdgcn_sched_barrier(0)
; template <class Epi, class Sched, bool ALIGN_EPI = false, bool SP2 = false, bool DUAL = false>
; __device__ __forceinline__ void gemm_phase(PG8_LAS unsigned char* lds, const Gemm g, const Sched& S, const Epi& E) {
;     ...
;             PG8_LDB(B0, 1, 0); PG8_LDB(B1, 1, 1); PG8_SCHED; PG8_LDA(At, 1, 0); PG8_STAGE(PG8_SA(0, 1), a2 + hstep, voffA);
;             PG8_WAIT_V(8); PG8_WAIT_L(0); PG8_BAR; PG8_MMA(0, 0, At, B0); PG8_MMA(0, 1, At, B1); PG8_BAR; PG8_SCHED;
;             PG8_LDA(At, 1, 1); PG8_STAGE(PG8_SB(1, 0), b3, voffB); PG8_STAGE(PG8_SB(1, 1), b3 + hstep, voffB); PG8_STAGE(PG8_SA(1, 0), a3, voffA);
;             PG8_WAIT_V(8); PG8_WAIT_L(0); PG8_BAR; PG8_MMA(1, 0, At, B0); PG8_MMA(1, 1, At, B1); PG8_BAR; PG8_SCHED;
	s_setprio 0
	s_add_i32 s49, 0, 0x18000
	s_add_i32 s50, 0, 0x1c000
	ds_read_b128 v[128:131], v201 offset:32768
	ds_read_b128 v[132:135], v201 offset:33792
	ds_read_b128 v[136:139], v201 offset:34816
	ds_read_b128 v[140:143], v201 offset:35840
	ds_read_b128 v[144:147], v202 offset:32768
	ds_read_b128 v[148:151], v202 offset:33792
	ds_read_b128 v[152:155], v202 offset:34816
	ds_read_b128 v[156:159], v202 offset:35840
	s_add_u32 s26, s26, 0x160000
	s_addc_u32 s27, s27, 0
	s_mov_b32 m0, s34
	ds_read_b128 v[160:163], v203 offset:32768
	ds_read_b128 v[182:185], v203 offset:33792
	ds_read_b128 v[186:189], v203 offset:34816
	ds_read_b128 v[190:193], v203 offset:35840
	ds_read_b128 v[204:207], v203 offset:36864
	ds_read_b128 v[208:211], v203 offset:37888
	ds_read_b128 v[212:215], v203 offset:38912
	ds_read_b128 v[216:219], v203 offset:39936
	global_load_lds_dwordx4 v164, s[26:27]
	s_mov_b32 m0, s35
	s_nop 0
	global_load_lds_dwordx4 v168, s[26:27]
	s_waitcnt vmcnt(8)
	s_waitcnt lgkmcnt(0)
	s_setprio 1
	s_barrier
	v_mfma_f32_16x16x32_bf16 v[124:127], v[128:131], v[160:163], v[124:127]
	v_mfma_f32_16x16x32_bf16 v[124:127], v[132:135], v[182:185], v[124:127]
	v_mfma_f32_16x16x32_bf16 v[112:115], v[128:131], v[186:189], v[112:115]
	v_mfma_f32_16x16x32_bf16 v[112:115], v[132:135], v[190:193], v[112:115]
	v_mfma_f32_16x16x32_bf16 v[96:99], v[128:131], v[204:207], v[96:99]
	v_mfma_f32_16x16x32_bf16 v[96:99], v[132:135], v[208:211], v[96:99]
	v_mfma_f32_16x16x32_bf16 v[80:83], v[128:131], v[212:215], v[80:83]
	v_mfma_f32_16x16x32_bf16 v[80:83], v[132:135], v[216:219], v[80:83]
	v_mfma_f32_16x16x32_bf16 v[120:123], v[136:139], v[160:163], v[120:123]
	v_mfma_f32_16x16x32_bf16 v[120:123], v[140:143], v[182:185], v[120:123]
	v_mfma_f32_16x16x32_bf16 v[104:107], v[136:139], v[186:189], v[104:107]
	v_mfma_f32_16x16x32_bf16 v[104:107], v[140:143], v[190:193], v[104:107]
	v_mfma_f32_16x16x32_bf16 v[88:91], v[136:139], v[204:207], v[88:91]
	v_mfma_f32_16x16x32_bf16 v[88:91], v[140:143], v[208:211], v[88:91]
	v_mfma_f32_16x16x32_bf16 v[72:75], v[136:139], v[212:215], v[72:75]
	v_mfma_f32_16x16x32_bf16 v[72:75], v[140:143], v[216:219], v[72:75]
	s_setprio 0
	s_setprio 1
	v_mfma_f32_16x16x32_bf16 v[116:119], v[144:147], v[160:163], v[116:119]
	v_mfma_f32_16x16x32_bf16 v[116:119], v[148:151], v[182:185], v[116:119]
	v_mfma_f32_16x16x32_bf16 v[100:103], v[144:147], v[186:189], v[100:103]
	v_mfma_f32_16x16x32_bf16 v[100:103], v[148:151], v[190:193], v[100:103]
	v_mfma_f32_16x16x32_bf16 v[84:87], v[144:147], v[204:207], v[84:87]
	v_mfma_f32_16x16x32_bf16 v[84:87], v[148:151], v[208:211], v[84:87]
	v_mfma_f32_16x16x32_bf16 v[68:71], v[144:147], v[212:215], v[68:71]
	v_mfma_f32_16x16x32_bf16 v[68:71], v[148:151], v[216:219], v[68:71]
	v_mfma_f32_16x16x32_bf16 v[108:111], v[152:155], v[160:163], v[108:111]
	v_mfma_f32_16x16x32_bf16 v[108:111], v[156:159], v[182:185], v[108:111]
	v_mfma_f32_16x16x32_bf16 v[92:95], v[152:155], v[186:189], v[92:95]
	v_mfma_f32_16x16x32_bf16 v[92:95], v[156:159], v[190:193], v[92:95]
	v_mfma_f32_16x16x32_bf16 v[76:79], v[152:155], v[204:207], v[76:79]
	v_mfma_f32_16x16x32_bf16 v[76:79], v[156:159], v[208:211], v[76:79]
	v_mfma_f32_16x16x32_bf16 v[64:67], v[152:155], v[212:215], v[64:67]
	v_mfma_f32_16x16x32_bf16 v[64:67], v[156:159], v[216:219], v[64:67]
	s_barrier
	s_setprio 0
	s_add_i32 s26, s49, s30
	s_mov_b32 m0, s26
	ds_read_b128 v[160:163], v203 offset:49152
	ds_read_b128 v[182:185], v203 offset:50176
	ds_read_b128 v[186:189], v203 offset:51200
	ds_read_b128 v[190:193], v203 offset:52224
	ds_read_b128 v[204:207], v203 offset:53248
	ds_read_b128 v[208:211], v203 offset:54272
	ds_read_b128 v[212:215], v203 offset:55296
	ds_read_b128 v[216:219], v203 offset:56320
	global_load_lds_dwordx4 v166, s[98:99]
	s_add_i32 m0, s26, 0x2000
	s_add_u32 s14, s14, 0x160080
	s_addc_u32 s15, s15, 0
	s_add_i32 s26, s50, s30
	global_load_lds_dwordx4 v170, s[98:99]
	s_mov_b32 m0, s26
	s_nop 0
	global_load_lds_dwordx4 v166, s[14:15]
	s_add_i32 m0, s26, 0x2000
	s_nop 0
	global_load_lds_dwordx4 v170, s[14:15]
	s_mov_b32 m0, s37
	s_nop 0
	global_load_lds_dwordx4 v164, s[100:101]
	s_mov_b32 m0, s38
	s_nop 0
	global_load_lds_dwordx4 v168, s[100:101]
	s_waitcnt vmcnt(8)
	s_waitcnt lgkmcnt(0)
	s_setprio 1
	s_barrier
	v_mfma_f32_16x16x32_bf16 v[60:63], v[128:131], v[160:163], v[60:63]
	v_mfma_f32_16x16x32_bf16 v[60:63], v[132:135], v[182:185], v[60:63]
	v_mfma_f32_16x16x32_bf16 v[48:51], v[128:131], v[186:189], v[48:51]
	v_mfma_f32_16x16x32_bf16 v[48:51], v[132:135], v[190:193], v[48:51]
	v_mfma_f32_16x16x32_bf16 v[32:35], v[128:131], v[204:207], v[32:35]
	v_mfma_f32_16x16x32_bf16 v[32:35], v[132:135], v[208:211], v[32:35]
	v_mfma_f32_16x16x32_bf16 v[16:19], v[128:131], v[212:215], v[16:19]
	v_mfma_f32_16x16x32_bf16 v[16:19], v[132:135], v[216:219], v[16:19]
	v_mfma_f32_16x16x32_bf16 v[56:59], v[136:139], v[160:163], v[56:59]
	v_mfma_f32_16x16x32_bf16 v[56:59], v[140:143], v[182:185], v[56:59]
	v_mfma_f32_16x16x32_bf16 v[40:43], v[136:139], v[186:189], v[40:43]
	v_mfma_f32_16x16x32_bf16 v[40:43], v[140:143], v[190:193], v[40:43]
	v_mfma_f32_16x16x32_bf16 v[24:27], v[136:139], v[204:207], v[24:27]
	v_mfma_f32_16x16x32_bf16 v[24:27], v[140:143], v[208:211], v[24:27]
	v_mfma_f32_16x16x32_bf16 v[8:11], v[136:139], v[212:215], v[8:11]
	v_mfma_f32_16x16x32_bf16 v[8:11], v[140:143], v[216:219], v[8:11]
	s_setprio 0
	s_setprio 1
	v_mfma_f32_16x16x32_bf16 v[52:55], v[144:147], v[160:163], v[52:55]
	v_mfma_f32_16x16x32_bf16 v[52:55], v[148:151], v[182:185], v[52:55]
	v_mfma_f32_16x16x32_bf16 v[36:39], v[144:147], v[186:189], v[36:39]
	v_mfma_f32_16x16x32_bf16 v[36:39], v[148:151], v[190:193], v[36:39]
	v_mfma_f32_16x16x32_bf16 v[20:23], v[144:147], v[204:207], v[20:23]
	v_mfma_f32_16x16x32_bf16 v[20:23], v[148:151], v[208:211], v[20:23]
	v_mfma_f32_16x16x32_bf16 v[4:7], v[144:147], v[212:215], v[4:7]
	v_mfma_f32_16x16x32_bf16 v[4:7], v[148:151], v[216:219], v[4:7]
	v_mfma_f32_16x16x32_bf16 v[44:47], v[152:155], v[160:163], v[44:47]
	v_mfma_f32_16x16x32_bf16 v[44:47], v[156:159], v[182:185], v[44:47]
	v_mfma_f32_16x16x32_bf16 v[28:31], v[152:155], v[186:189], v[28:31]
	v_mfma_f32_16x16x32_bf16 v[28:31], v[156:159], v[190:193], v[28:31]
	v_mfma_f32_16x16x32_bf16 v[12:15], v[152:155], v[204:207], v[12:15]
	v_mfma_f32_16x16x32_bf16 v[12:15], v[156:159], v[208:211], v[12:15]
	v_mfma_f32_16x16x32_bf16 v[0:3], v[152:155], v[212:215], v[0:3]
	v_mfma_f32_16x16x32_bf16 v[0:3], v[156:159], v[216:219], v[0:3]
	s_barrier
	s_setprio 0
	s_add_i32 s48, s48, 2
	s_add_u32 s24, s24, 0x100
	s_addc_u32 s25, s25, 0
	s_add_u32 s46, s46, 0x100
	s_addc_u32 s47, s47, 0
; #define PG8_STAGE(bufoff, gbase, voff) do { _Pragma("unroll") for (int _i = 0; _i < 2; ++_i) \
;         __builtin_amdgcn_global_load_lds((const unsigned*)((const char*)(gbase) + (voff)[_i]), (PG8_LAS unsigned*)(lds + (bufoff) + ldsw + _i * 8192), 16, 0, 0); } while (0)
; #define PG8_LDA(dst, b, h) do { _Pragma("unroll") for (int m = 0; m < 4; ++m) _Pragma("unroll") for (int k = 0; k < 2; ++k) dst[m][k] = *(const PG8_LAS bf16x8*)(lds + PG8_SA(b, h) + aoff + m * 2048 + k * 1024); } while (0)
; #define PG8_LDB(dst, b, h) do { _Pragma("unroll") for (int n = 0; n < 2; ++n) _Pragma("unroll") for (int k = 0; k < 2; ++k) dst[n][k] = *(const PG8_LAS bf16x8*)(lds + PG8_SB(b, h) + boff + n * 2048 + k * 1024); } while (0)
; #define PG8_MMA(ai, bj, At, Bt) do { __builtin_amdgcn_s_setprio(1); _Pragma("unroll") for (int m = 0; m < 4; ++m) _Pragma("unroll") for (int n = 0; n < 2; ++n) _Pragma("unroll") for (int k = 0; k < 2; ++k) \
;         acc[ai][bj][m][n] = __builtin_amdgcn_mfma_f32_16x16x32_bf16(Bt[n][k], At[m][k], acc[ai][bj][m][n], 0, 0, 0); __builtin_amdgcn_s_setprio(0); } while (0)
; #define PG8_WAIT_V(n) asm volatile("s_waitcnt vmcnt(" #n ")" ::: "memory")
; #define PG8_WAIT_L(n) asm volatile("s_waitcnt lgkmcnt(" #n ")" ::: "memory")
; template <class Epi, class Sched, bool ALIGN_EPI = false, bool SP2 = false, bool DUAL = false>
; __device__ __forceinline__ void gemm_phase(PG8_LAS unsigned char* lds, const Gemm g, const Sched& S, const Epi& E) {
;     ...
;             const bool last = (t == nt - 2);
;             const char* a1 = cA + (size_t)(t + 1) * kstep;
;             const char* a2 = last ? nA : cA + (size_t)(t + 2) * kstep; const char* b2 = last ? nB : cB + (size_t)(t + 2) * kstep;
;             const char* a3 = a2 + kstep; const char* b3 = b2 + kstep;
;             if (last && has_next) S.a_ready(nxt);
;             if constexpr (SP2) {
;             PG8_LDB(B0, 0, 0); PG8_LDB(B1, 0, 1); PG8_SCHED; PG8_LDA(At, 0, 0); PG8_STAGE(PG8_SA(1, 1), a1 + hstep, voffA);
;             PG8_WAIT_V(8); PG8_WAIT_L(0); PG8_BAR; PG8_MMA(0, 0, At, B0); PG8_MMA(0, 1, At, B1); PG8_BAR; PG8_SCHED;
;             PG8_LDA(At, 0, 1); PG8_STAGE(PG8_SB(0, 0), b2, voffB); PG8_STAGE(PG8_SB(0, 1), b2 + hstep, voffB); PG8_STAGE(PG8_SA(0, 0), a2, voffA);
;             PG8_WAIT_V(8); PG8_WAIT_L(0); PG8_BAR; PG8_MMA(1, 0, At, B0); PG8_MMA(1, 1, At, B1); PG8_BAR; PG8_SCHED;
.LBB0_1193:
	ds_read_b128 v[128:131], v201
	ds_read_b128 v[132:135], v201 offset:1024
	ds_read_b128 v[136:139], v201 offset:2048
	ds_read_b128 v[140:143], v201 offset:3072
	ds_read_b128 v[144:147], v202
	ds_read_b128 v[148:151], v202 offset:1024
	ds_read_b128 v[152:155], v202 offset:2048
	ds_read_b128 v[156:159], v202 offset:3072
	s_add_u32 s14, s24, 0xffea0080
	s_addc_u32 s15, s25, -1
	s_cmpk_eq_i32 s48, 0x54
	s_cselect_b32 s27, s5, s15
	s_cselect_b32 s26, s4, s14
	s_cselect_b32 s15, s23, s47
	s_cselect_b32 s14, s22, s46
	s_add_i32 m0, s31, 0xc000
	ds_read_b128 v[160:163], v203
	ds_read_b128 v[182:185], v203 offset:1024
	ds_read_b128 v[186:189], v203 offset:2048
	ds_read_b128 v[190:193], v203 offset:3072
	ds_read_b128 v[204:207], v203 offset:4096
	ds_read_b128 v[208:211], v203 offset:5120
	ds_read_b128 v[212:215], v203 offset:6144
	ds_read_b128 v[216:219], v203 offset:7168
	global_load_lds_dwordx4 v172, s[24:25]
	s_add_i32 m0, s31, 0xe000
	s_nop 0
	global_load_lds_dwordx4 v174, s[24:25]
	s_waitcnt vmcnt(8)
	s_waitcnt lgkmcnt(0)
	s_setprio 1
	s_barrier
	v_mfma_f32_16x16x32_bf16 v[124:127], v[128:131], v[160:163], v[124:127]
	v_mfma_f32_16x16x32_bf16 v[124:127], v[132:135], v[182:185], v[124:127]
	v_mfma_f32_16x16x32_bf16 v[112:115], v[128:131], v[186:189], v[112:115]
	v_mfma_f32_16x16x32_bf16 v[112:115], v[132:135], v[190:193], v[112:115]
	v_mfma_f32_16x16x32_bf16 v[96:99], v[128:131], v[204:207], v[96:99]
	v_mfma_f32_16x16x32_bf16 v[96:99], v[132:135], v[208:211], v[96:99]
	v_mfma_f32_16x16x32_bf16 v[80:83], v[128:131], v[212:215], v[80:83]
	v_mfma_f32_16x16x32_bf16 v[80:83], v[132:135], v[216:219], v[80:83]
	v_mfma_f32_16x16x32_bf16 v[120:123], v[136:139], v[160:163], v[120:123]
	v_mfma_f32_16x16x32_bf16 v[120:123], v[140:143], v[182:185], v[120:123]
	v_mfma_f32_16x16x32_bf16 v[104:107], v[136:139], v[186:189], v[104:107]
	v_mfma_f32_16x16x32_bf16 v[104:107], v[140:143], v[190:193], v[104:107]
	v_mfma_f32_16x16x32_bf16 v[88:91], v[136:139], v[204:207], v[88:91]
	v_mfma_f32_16x16x32_bf16 v[88:91], v[140:143], v[208:211], v[88:91]
	v_mfma_f32_16x16x32_bf16 v[72:75], v[136:139], v[212:215], v[72:75]
	v_mfma_f32_16x16x32_bf16 v[72:75], v[140:143], v[216:219], v[72:75]
	s_setprio 0
	s_setprio 1
	v_mfma_f32_16x16x32_bf16 v[116:119], v[144:147], v[160:163], v[116:119]
	v_mfma_f32_16x16x32_bf16 v[116:119], v[148:151], v[182:185], v[116:119]
	v_mfma_f32_16x16x32_bf16 v[100:103], v[144:147], v[186:189], v[100:103]
	v_mfma_f32_16x16x32_bf16 v[100:103], v[148:151], v[190:193], v[100:103]
	v_mfma_f32_16x16x32_bf16 v[84:87], v[144:147], v[204:207], v[84:87]
	v_mfma_f32_16x16x32_bf16 v[84:87], v[148:151], v[208:211], v[84:87]
	v_mfma_f32_16x16x32_bf16 v[68:71], v[144:147], v[212:215], v[68:71]
	v_mfma_f32_16x16x32_bf16 v[68:71], v[148:151], v[216:219], v[68:71]
	v_mfma_f32_16x16x32_bf16 v[108:111], v[152:155], v[160:163], v[108:111]
	v_mfma_f32_16x16x32_bf16 v[108:111], v[156:159], v[182:185], v[108:111]
	v_mfma_f32_16x16x32_bf16 v[92:95], v[152:155], v[186:189], v[92:95]
	v_mfma_f32_16x16x32_bf16 v[92:95], v[156:159], v[190:193], v[92:95]
	v_mfma_f32_16x16x32_bf16 v[76:79], v[152:155], v[204:207], v[76:79]
	v_mfma_f32_16x16x32_bf16 v[76:79], v[156:159], v[208:211], v[76:79]
	v_mfma_f32_16x16x32_bf16 v[64:67], v[152:155], v[212:215], v[64:67]
	v_mfma_f32_16x16x32_bf16 v[64:67], v[156:159], v[216:219], v[64:67]
	s_barrier
	s_setprio 0
	s_add_u32 s98, s14, 0x80
	s_addc_u32 s99, s15, 0
	s_add_u32 s100, s26, 0x80
	s_addc_u32 s101, s27, 0
	s_add_i32 s49, s40, s30
	s_mov_b32 m0, s49
	ds_read_b128 v[160:163], v203 offset:16384
	ds_read_b128 v[182:185], v203 offset:17408
	ds_read_b128 v[186:189], v203 offset:18432
	ds_read_b128 v[190:193], v203 offset:19456
	ds_read_b128 v[204:207], v203 offset:20480
	ds_read_b128 v[208:211], v203 offset:21504
	ds_read_b128 v[212:215], v203 offset:22528
	ds_read_b128 v[216:219], v203 offset:23552
	global_load_lds_dwordx4 v166, s[14:15]
	s_add_i32 m0, s49, 0x2000
	s_add_u32 s50, s14, 0x160000
	s_addc_u32 s51, s15, 0
	s_add_i32 s49, s41, s30
	global_load_lds_dwordx4 v170, s[14:15]
	s_mov_b32 m0, s49
	s_nop 0
	global_load_lds_dwordx4 v166, s[50:51]
	s_add_i32 m0, s49, 0x2000
	s_nop 0
	global_load_lds_dwordx4 v170, s[50:51]
	s_mov_b32 m0, s31
	s_nop 0
	global_load_lds_dwordx4 v164, s[26:27]
	s_mov_b32 m0, s33
	s_nop 0
	global_load_lds_dwordx4 v168, s[26:27]
	s_waitcnt vmcnt(8)
	s_waitcnt lgkmcnt(0)
	s_setprio 1
	s_barrier
	v_mfma_f32_16x16x32_bf16 v[60:63], v[128:131], v[160:163], v[60:63]
	v_mfma_f32_16x16x32_bf16 v[60:63], v[132:135], v[182:185], v[60:63]
	v_mfma_f32_16x16x32_bf16 v[48:51], v[128:131], v[186:189], v[48:51]
	v_mfma_f32_16x16x32_bf16 v[48:51], v[132:135], v[190:193], v[48:51]
	v_mfma_f32_16x16x32_bf16 v[32:35], v[128:131], v[204:207], v[32:35]
	v_mfma_f32_16x16x32_bf16 v[32:35], v[132:135], v[208:211], v[32:35]
	v_mfma_f32_16x16x32_bf16 v[16:19], v[128:131], v[212:215], v[16:19]
	v_mfma_f32_16x16x32_bf16 v[16:19], v[132:135], v[216:219], v[16:19]
	v_mfma_f32_16x16x32_bf16 v[56:59], v[136:139], v[160:163], v[56:59]
	v_mfma_f32_16x16x32_bf16 v[56:59], v[140:143], v[182:185], v[56:59]
	v_mfma_f32_16x16x32_bf16 v[40:43], v[136:139], v[186:189], v[40:43]
	v_mfma_f32_16x16x32_bf16 v[40:43], v[140:143], v[190:193], v[40:43]
	v_mfma_f32_16x16x32_bf16 v[24:27], v[136:139], v[204:207], v[24:27]
	v_mfma_f32_16x16x32_bf16 v[24:27], v[140:143], v[208:211], v[24:27]
	v_mfma_f32_16x16x32_bf16 v[8:11], v[136:139], v[212:215], v[8:11]
	v_mfma_f32_16x16x32_bf16 v[8:11], v[140:143], v[216:219], v[8:11]
	s_setprio 0
	s_setprio 1
	v_mfma_f32_16x16x32_bf16 v[52:55], v[144:147], v[160:163], v[52:55]
	v_mfma_f32_16x16x32_bf16 v[52:55], v[148:151], v[182:185], v[52:55]
	v_mfma_f32_16x16x32_bf16 v[36:39], v[144:147], v[186:189], v[36:39]
	v_mfma_f32_16x16x32_bf16 v[36:39], v[148:151], v[190:193], v[36:39]
	v_mfma_f32_16x16x32_bf16 v[20:23], v[144:147], v[204:207], v[20:23]
	v_mfma_f32_16x16x32_bf16 v[20:23], v[148:151], v[208:211], v[20:23]
	v_mfma_f32_16x16x32_bf16 v[4:7], v[144:147], v[212:215], v[4:7]
	v_mfma_f32_16x16x32_bf16 v[4:7], v[148:151], v[216:219], v[4:7]
	v_mfma_f32_16x16x32_bf16 v[44:47], v[152:155], v[160:163], v[44:47]
	v_mfma_f32_16x16x32_bf16 v[44:47], v[156:159], v[182:185], v[44:47]
	v_mfma_f32_16x16x32_bf16 v[28:31], v[152:155], v[186:189], v[28:31]
	v_mfma_f32_16x16x32_bf16 v[28:31], v[156:159], v[190:193], v[28:31]
	v_mfma_f32_16x16x32_bf16 v[12:15], v[152:155], v[204:207], v[12:15]
	v_mfma_f32_16x16x32_bf16 v[12:15], v[156:159], v[208:211], v[12:15]
	v_mfma_f32_16x16x32_bf16 v[0:3], v[152:155], v[212:215], v[0:3]
	v_mfma_f32_16x16x32_bf16 v[0:3], v[156:159], v[216:219], v[0:3]
	s_barrier
; #define PG8_STAGE(bufoff, gbase, voff) do { _Pragma("unroll") for (int _i = 0; _i < 2; ++_i) \
;         __builtin_amdgcn_global_load_lds((const unsigned*)((const char*)(gbase) + (voff)[_i]), (PG8_LAS unsigned*)(lds + (bufoff) + ldsw + _i * 8192), 16, 0, 0); } while (0)
; template <class Epi, class Sched, bool ALIGN_EPI = false, bool SP2 = false, bool DUAL = false>
; __device__ __forceinline__ void gemm_phase(PG8_LAS unsigned char* lds, const Gemm g, const Sched& S, const Epi& E) {
;     ...
;             PG8_LDB(B0, 1, 0); PG8_LDB(B1, 1, 1); PG8_SCHED; PG8_LDA(At, 1, 0); PG8_STAGE(PG8_SA(0, 1), a2 + hstep, voffA);
;             PG8_WAIT_V(8); PG8_WAIT_L(0); PG8_BAR; PG8_MMA(0, 0, At, B0); PG8_MMA(0, 1, At, B1); PG8_BAR; PG8_SCHED;
;             PG8_LDA(At, 1, 1); PG8_STAGE(PG8_SB(1, 0), b3, voffB); PG8_STAGE(PG8_SB(1, 1), b3 + hstep, voffB); PG8_STAGE(PG8_SA(1, 0), a3, voffA);
;             PG8_WAIT_V(8); PG8_WAIT_L(0); PG8_BAR; PG8_MMA(1, 0, At, B0); PG8_MMA(1, 1, At, B1); PG8_BAR; PG8_SCHED;
;             } else {
;             PG8_LDB(B0, 0, 0); PG8_SCHED; PG8_LDA(At, 0, 0); PG8_STAGE(PG8_SA(1, 1), a1 + hstep, voffA);
;             PG8_WAIT_L(8); PG8_BAR; PG8_WAIT_L(0); PG8_MMA(0, 0, At, B0); PG8_BAR; PG8_SCHED;
;             PG8_LDB(B1, 0, 1); PG8_STAGE(PG8_SB(0, 0), b2, voffB);
;             PG8_BAR; PG8_WAIT_L(0); PG8_MMA(0, 1, At, B1); PG8_BAR;
;             PG8_LDA(At, 0, 1); PG8_STAGE(PG8_SA(0, 0), a2, voffA);
;             PG8_BAR; PG8_WAIT_L(0); PG8_MMA(1, 0, At, B0); PG8_BAR; PG8_SCHED;
;             PG8_STAGE(PG8_SB(0, 1), b2 + hstep, voffB);
;             PG8_WAIT_V(6); PG8_BAR; PG8_MMA(1, 1, At, B1); PG8_BAR;
;             PG8_LDB(B0, 1, 0); PG8_SCHED; PG8_LDA(At, 1, 0); PG8_STAGE(PG8_SA(0, 1), a2 + hstep, voffA);
;             PG8_WAIT_L(8); PG8_BAR; PG8_WAIT_L(0); PG8_MMA(0, 0, At, B0); PG8_BAR; PG8_SCHED;
;             PG8_LDB(B1, 1, 1); PG8_STAGE(PG8_SB(1, 0), b3, voffB);
;             PG8_BAR; PG8_WAIT_L(0); PG8_MMA(0, 1, At, B1); PG8_BAR;
;             PG8_LDA(At, 1, 1); PG8_STAGE(PG8_SA(1, 0), a3, voffA);
;             PG8_BAR; PG8_WAIT_L(0); PG8_MMA(1, 0, At, B0); PG8_BAR; PG8_SCHED;
;             PG8_STAGE(PG8_SB(1, 1), b3 + hstep, voffB);
;             PG8_WAIT_V(6); PG8_BAR; PG8_MMA(1, 1, At, B1); PG8_BAR;
;             }
;         }
;         if constexpr (ALIGN_EPI) { if (wr == 0) PG8_BAR; }
	s_setprio 0
	s_add_i32 s49, 0, 0x18000
	s_add_i32 s50, 0, 0x1c000
	ds_read_b128 v[128:131], v201 offset:32768
	ds_read_b128 v[132:135], v201 offset:33792
	ds_read_b128 v[136:139], v201 offset:34816
	ds_read_b128 v[140:143], v201 offset:35840
	ds_read_b128 v[144:147], v202 offset:32768
	ds_read_b128 v[148:151], v202 offset:33792
	ds_read_b128 v[152:155], v202 offset:34816
	ds_read_b128 v[156:159], v202 offset:35840
	s_add_u32 s26, s26, 0x160000
	s_addc_u32 s27, s27, 0
	s_mov_b32 m0, s34
	ds_read_b128 v[160:163], v203 offset:32768
	ds_read_b128 v[182:185], v203 offset:33792
	ds_read_b128 v[186:189], v203 offset:34816
	ds_read_b128 v[190:193], v203 offset:35840
	ds_read_b128 v[204:207], v203 offset:36864
	ds_read_b128 v[208:211], v203 offset:37888
	ds_read_b128 v[212:215], v203 offset:38912
	ds_read_b128 v[216:219], v203 offset:39936
	global_load_lds_dwordx4 v164, s[26:27]
	s_mov_b32 m0, s35
	s_nop 0
	global_load_lds_dwordx4 v168, s[26:27]
	s_waitcnt vmcnt(8)
	s_waitcnt lgkmcnt(0)
	s_setprio 1
	s_barrier
	v_mfma_f32_16x16x32_bf16 v[124:127], v[128:131], v[160:163], v[124:127]
	v_mfma_f32_16x16x32_bf16 v[124:127], v[132:135], v[182:185], v[124:127]
	v_mfma_f32_16x16x32_bf16 v[112:115], v[128:131], v[186:189], v[112:115]
	v_mfma_f32_16x16x32_bf16 v[112:115], v[132:135], v[190:193], v[112:115]
	v_mfma_f32_16x16x32_bf16 v[96:99], v[128:131], v[204:207], v[96:99]
	v_mfma_f32_16x16x32_bf16 v[96:99], v[132:135], v[208:211], v[96:99]
	v_mfma_f32_16x16x32_bf16 v[80:83], v[128:131], v[212:215], v[80:83]
	v_mfma_f32_16x16x32_bf16 v[80:83], v[132:135], v[216:219], v[80:83]
	v_mfma_f32_16x16x32_bf16 v[120:123], v[136:139], v[160:163], v[120:123]
	v_mfma_f32_16x16x32_bf16 v[120:123], v[140:143], v[182:185], v[120:123]
	v_mfma_f32_16x16x32_bf16 v[104:107], v[136:139], v[186:189], v[104:107]
	v_mfma_f32_16x16x32_bf16 v[104:107], v[140:143], v[190:193], v[104:107]
	v_mfma_f32_16x16x32_bf16 v[88:91], v[136:139], v[204:207], v[88:91]
	v_mfma_f32_16x16x32_bf16 v[88:91], v[140:143], v[208:211], v[88:91]
	v_mfma_f32_16x16x32_bf16 v[72:75], v[136:139], v[212:215], v[72:75]
	v_mfma_f32_16x16x32_bf16 v[72:75], v[140:143], v[216:219], v[72:75]
	s_setprio 0
	s_setprio 1
	v_mfma_f32_16x16x32_bf16 v[116:119], v[144:147], v[160:163], v[116:119]
	v_mfma_f32_16x16x32_bf16 v[116:119], v[148:151], v[182:185], v[116:119]
	v_mfma_f32_16x16x32_bf16 v[100:103], v[144:147], v[186:189], v[100:103]
	v_mfma_f32_16x16x32_bf16 v[100:103], v[148:151], v[190:193], v[100:103]
	v_mfma_f32_16x16x32_bf16 v[84:87], v[144:147], v[204:207], v[84:87]
	v_mfma_f32_16x16x32_bf16 v[84:87], v[148:151], v[208:211], v[84:87]
	v_mfma_f32_16x16x32_bf16 v[68:71], v[144:147], v[212:215], v[68:71]
	v_mfma_f32_16x16x32_bf16 v[68:71], v[148:151], v[216:219], v[68:71]
	v_mfma_f32_16x16x32_bf16 v[108:111], v[152:155], v[160:163], v[108:111]
	v_mfma_f32_16x16x32_bf16 v[108:111], v[156:159], v[182:185], v[108:111]
	v_mfma_f32_16x16x32_bf16 v[92:95], v[152:155], v[186:189], v[92:95]
	v_mfma_f32_16x16x32_bf16 v[92:95], v[156:159], v[190:193], v[92:95]
	v_mfma_f32_16x16x32_bf16 v[76:79], v[152:155], v[204:207], v[76:79]
	v_mfma_f32_16x16x32_bf16 v[76:79], v[156:159], v[208:211], v[76:79]
	v_mfma_f32_16x16x32_bf16 v[64:67], v[152:155], v[212:215], v[64:67]
	v_mfma_f32_16x16x32_bf16 v[64:67], v[156:159], v[216:219], v[64:67]
	s_barrier
	s_setprio 0
	s_add_i32 s26, s49, s30
	s_mov_b32 m0, s26
	ds_read_b128 v[160:163], v203 offset:49152
	ds_read_b128 v[182:185], v203 offset:50176
	ds_read_b128 v[186:189], v203 offset:51200
	ds_read_b128 v[190:193], v203 offset:52224
	ds_read_b128 v[204:207], v203 offset:53248
	ds_read_b128 v[208:211], v203 offset:54272
	ds_read_b128 v[212:215], v203 offset:55296
	ds_read_b128 v[216:219], v203 offset:56320
	global_load_lds_dwordx4 v166, s[98:99]
	s_add_i32 m0, s26, 0x2000
	s_add_u32 s14, s14, 0x160080
	s_addc_u32 s15, s15, 0
	s_add_i32 s26, s50, s30
	global_load_lds_dwordx4 v170, s[98:99]
	s_mov_b32 m0, s26
	s_nop 0
	global_load_lds_dwordx4 v166, s[14:15]
	s_add_i32 m0, s26, 0x2000
	s_nop 0
	global_load_lds_dwordx4 v170, s[14:15]
	s_mov_b32 m0, s37
	s_nop 0
	global_load_lds_dwordx4 v164, s[100:101]
	s_mov_b32 m0, s38
	s_nop 0
	global_load_lds_dwordx4 v168, s[100:101]
	s_waitcnt vmcnt(8)
	s_waitcnt lgkmcnt(0)
	s_setprio 1
	s_barrier
	v_mfma_f32_16x16x32_bf16 v[60:63], v[128:131], v[160:163], v[60:63]
	v_mfma_f32_16x16x32_bf16 v[60:63], v[132:135], v[182:185], v[60:63]
	v_mfma_f32_16x16x32_bf16 v[48:51], v[128:131], v[186:189], v[48:51]
	v_mfma_f32_16x16x32_bf16 v[48:51], v[132:135], v[190:193], v[48:51]
	v_mfma_f32_16x16x32_bf16 v[32:35], v[128:131], v[204:207], v[32:35]
	v_mfma_f32_16x16x32_bf16 v[32:35], v[132:135], v[208:211], v[32:35]
	v_mfma_f32_16x16x32_bf16 v[16:19], v[128:131], v[212:215], v[16:19]
	v_mfma_f32_16x16x32_bf16 v[16:19], v[132:135], v[216:219], v[16:19]
	v_mfma_f32_16x16x32_bf16 v[56:59], v[136:139], v[160:163], v[56:59]
	v_mfma_f32_16x16x32_bf16 v[56:59], v[140:143], v[182:185], v[56:59]
	v_mfma_f32_16x16x32_bf16 v[40:43], v[136:139], v[186:189], v[40:43]
	v_mfma_f32_16x16x32_bf16 v[40:43], v[140:143], v[190:193], v[40:43]
	v_mfma_f32_16x16x32_bf16 v[24:27], v[136:139], v[204:207], v[24:27]
	v_mfma_f32_16x16x32_bf16 v[24:27], v[140:143], v[208:211], v[24:27]
	v_mfma_f32_16x16x32_bf16 v[8:11], v[136:139], v[212:215], v[8:11]
	v_mfma_f32_16x16x32_bf16 v[8:11], v[140:143], v[216:219], v[8:11]
	s_setprio 0
	s_setprio 1
	v_mfma_f32_16x16x32_bf16 v[52:55], v[144:147], v[160:163], v[52:55]
	v_mfma_f32_16x16x32_bf16 v[52:55], v[148:151], v[182:185], v[52:55]
	v_mfma_f32_16x16x32_bf16 v[36:39], v[144:147], v[186:189], v[36:39]
	v_mfma_f32_16x16x32_bf16 v[36:39], v[148:151], v[190:193], v[36:39]
	v_mfma_f32_16x16x32_bf16 v[20:23], v[144:147], v[204:207], v[20:23]
	v_mfma_f32_16x16x32_bf16 v[20:23], v[148:151], v[208:211], v[20:23]
	v_mfma_f32_16x16x32_bf16 v[4:7], v[144:147], v[212:215], v[4:7]
	v_mfma_f32_16x16x32_bf16 v[4:7], v[148:151], v[216:219], v[4:7]
	v_mfma_f32_16x16x32_bf16 v[44:47], v[152:155], v[160:163], v[44:47]
	v_mfma_f32_16x16x32_bf16 v[44:47], v[156:159], v[182:185], v[44:47]
	v_mfma_f32_16x16x32_bf16 v[28:31], v[152:155], v[186:189], v[28:31]
	v_mfma_f32_16x16x32_bf16 v[28:31], v[156:159], v[190:193], v[28:31]
	v_mfma_f32_16x16x32_bf16 v[12:15], v[152:155], v[204:207], v[12:15]
	v_mfma_f32_16x16x32_bf16 v[12:15], v[156:159], v[208:211], v[12:15]
	v_mfma_f32_16x16x32_bf16 v[0:3], v[152:155], v[212:215], v[0:3]
	v_mfma_f32_16x16x32_bf16 v[0:3], v[156:159], v[216:219], v[0:3]
	s_barrier
	s_setprio 0
	s_add_i32 s48, s48, 2
	s_add_u32 s24, s24, 0x100
	s_addc_u32 s25, s25, 0
	s_add_u32 s46, s46, 0x100
	s_addc_u32 s47, s47, 0
	s_cmpk_gt_u32 s48, 0x55
	s_cbranch_scc0 .LBB0_1193
	s_and_b64 vcc, exec, s[20:21]
	s_cbranch_vccz .LBB0_1196
	s_barrier
